# scan: step-0 operand LDS reads issued before the per-trip address set-up; y-partial LDS slots swizzled (bank-conflict-free ds_write_b64)
# speedup vs baseline: 1.0930x; 1.0005x over previous
; __device__ __forceinline__ void scan_rows(f32x2 (&X)[8], const ScanOps& o, const f32x4 (&b)[2], const f32x4 (&kd)[2], const f32x4 (&r)[2], const bool use_v, float& yA, float& yB) {
;     f32x2 aA = X[0] * o.kk[0].xy, aB = X[4] * o.kk[0].xy;
;     aA += X[1] * o.kk[0].zw; aB += X[5] * o.kk[0].zw;
;     aA += X[2] * o.kk[1].xy; aB += X[6] * o.kk[1].xy;
;     aA += X[3] * o.kk[1].zw; aB += X[7] * o.kk[1].zw;
;     const float saA = sum8(aA.x + aA.y), saB = sum8(aB.x + aB.y);
;     const f32x2 nA = (f32x2){-saA, -saA}, nB = (f32x2){-saB, -saB}, vA = (f32x2){o.v.x, o.v.x}, vB = (f32x2){o.v.y, o.v.y};
;     f32x2 tA, tB, accA, accB;
;     tA = X[0] * o.w[0].xy; tA += nA * b[0].xy; if (use_v) tA += vA * kd[0].xy; X[0] = tA; accA = tA * r[0].xy;
;     tB = X[4] * o.w[0].xy; tB += nB * b[0].xy; if (use_v) tB += vB * kd[0].xy; X[4] = tB; accB = tB * r[0].xy;
;     tA = X[1] * o.w[0].zw; tA += nA * b[0].zw; if (use_v) tA += vA * kd[0].zw; X[1] = tA; accA += tA * r[0].zw;
;     tB = X[5] * o.w[0].zw; tB += nB * b[0].zw; if (use_v) tB += vB * kd[0].zw; X[5] = tB; accB += tB * r[0].zw;
;     tA = X[2] * o.w[1].xy; tA += nA * b[1].xy; if (use_v) tA += vA * kd[1].xy; X[2] = tA; accA += tA * r[1].xy;
;     tB = X[6] * o.w[1].xy; tB += nB * b[1].xy; if (use_v) tB += vB * kd[1].xy; X[6] = tB; accB += tB * r[1].xy;
; __device__ void phase_scan(int c, const bf16_t* PROJ, const float* k_k, const bf16_t* Wd, const bf16_t* Bd, const float* k_a, bf16_t* Y, bf16_t* Q, float* FS, float* sm) {
;     ...
;             if (act) {
;                 const float* ob = opb + (ci & 1) * 6144 + q * 8;
;                 const float* obv = opb + (ci & 1) * 6144 + 5120 + wq * 16 + 2 * vp;
;                 ScanOps A, B;
;                 scan_ld(ob, obv, 0, A);
; #pragma unroll
;                 for (int i = 0; i < 16; i += 2) {
;                     float yA = 0.f, yB = 0.f;
;                     scan_ld(ob, obv, i + 1, B);
;                     if (roleP) A.v = (f32x2){0.f, 0.f};
;                     scan_step1(X, A, ob + i * 64, yA, yB);
;                     *(f32x2*)(obw + i * 16 + 2 * vp) = (f32x2){yA, yB};
;                     if (i + 2 < 16) scan_ld(ob, obv, i + 2, A);
;                     if (roleP) B.v = (f32x2){0.f, 0.f};
;                     scan_step1(X, B, ob + (i + 1) * 64, yA, yB);
;                     *(f32x2*)(obw + (i + 1) * 16 + 2 * vp) = (f32x2){yA, yB};
.LBB0_75:
	s_or_b64 exec, exec, s[56:57]
	s_and_saveexec_b64 s[12:13], s[54:55]
	s_cbranch_execz .LBB0_71
	s_bitcmp1_b32 s28, 0
	s_cselect_b32 s41, 0x6000, 0
	s_add_i32 s41, s41, 0
	v_lshl_add_u32 v84, v68, 2, s41
	v_lshlrev_b32_e32 v85, 2, v66
	v_lshlrev_b32_e32 v86, 2, v67
	v_add3_u32 v85, s41, v85, v86
	ds_read_b128 v[86:89], v84 offset:0
	ds_read_b128 v[90:93], v84 offset:16
	ds_read_b128 v[94:97], v84 offset:4096
	ds_read_b128 v[98:101], v84 offset:4112
	ds_read_b128 v[102:105], v84 offset:8192
	ds_read_b128 v[106:109], v84 offset:8208
	ds_read_b128 v[118:121], v84 offset:16384
	ds_read_b128 v[122:125], v84 offset:16400
	v_lshrrev_b32_e32 v228, 6, v180
	v_mul_u32_u24_e32 v228, 0x2400, v228
	v_add_u32_e32 v228, 0xe000, v228
	v_bfe_u32 v236, v180, 2, 4
	v_mul_u32_u24_e32 v236, 0x240, v236
	v_add_u32_e32 v236, v236, v228
	v_and_b32_e32 v237, 3, v180
	v_lshl_add_u32 v229, v237, 4, v236
	v_add_u32_e32 v230, 1, v237
	v_and_b32_e32 v230, 3, v230
	v_lshl_add_u32 v231, v230, 4, v236
	v_add_u32_e32 v230, 2, v237
	v_and_b32_e32 v230, 3, v230
	v_lshl_add_u32 v234, v230, 4, v236
	v_add_u32_e32 v230, 3, v237
	v_and_b32_e32 v230, 3, v230
	v_lshl_add_u32 v235, v230, 4, v236
	v_and_b32_e32 v230, 7, v180
	v_lshl_add_u32 v228, v230, 6, v228
	v_bfe_u32 v230, v180, 3, 3
	v_bfe_u32 v237, v180, 1, 2
	v_lshl_add_u32 v230, v237, 1, v230
	v_and_b32_e32 v230, 7, v230
	v_lshl_add_u32 v228, v230, 3, v228
	s_cmp_lg_u64 s[8:9], 0
	s_cbranch_scc1 .Lscan_p_body
	ds_read_b128 v[110:113], v84 offset:12288
	ds_read_b128 v[114:117], v84 offset:12304
	ds_read_b64 v[126:127], v85 offset:20480
	s_waitcnt lgkmcnt(0)
	ds_read_b128 v[128:131], v84 offset:256
	ds_read_b128 v[132:135], v84 offset:272
	ds_read_b128 v[136:139], v84 offset:4352
	ds_read_b128 v[140:143], v84 offset:4368
	ds_read_b128 v[144:147], v84 offset:8448
	ds_read_b128 v[148:151], v84 offset:8464
	ds_read_b128 v[152:155], v84 offset:12544
	ds_read_b128 v[156:159], v84 offset:12560
	ds_read_b128 v[160:163], v84 offset:16640
	ds_read_b128 v[164:167], v84 offset:16656
	ds_read_b64 v[168:169], v85 offset:20736
	v_pk_mul_f32 v[212:213], v[22:23], v[94:95]
	v_pk_mul_f32 v[216:217], v[14:15], v[94:95]
	v_pk_mul_f32 v[196:197], v[22:23], v[86:87]
	v_pk_mul_f32 v[204:205], v[14:15], v[86:87]
	v_pk_fma_f32 v[212:213], v[24:25], v[96:97], v[212:213]
	v_pk_fma_f32 v[216:217], v[16:17], v[96:97], v[216:217]
	v_pk_mul_f32 v[198:199], v[24:25], v[88:89]
	v_pk_mul_f32 v[206:207], v[16:17], v[88:89]
	v_pk_fma_f32 v[212:213], v[18:19], v[98:99], v[212:213]
	v_pk_fma_f32 v[216:217], v[10:11], v[98:99], v[216:217]
	v_pk_mul_f32 v[200:201], v[18:19], v[90:91]
	v_pk_mul_f32 v[208:209], v[10:11], v[90:91]
	v_pk_fma_f32 v[212:213], v[20:21], v[100:101], v[212:213]
	v_pk_fma_f32 v[216:217], v[12:13], v[100:101], v[216:217]
	v_pk_mul_f32 v[202:203], v[20:21], v[92:93]
	v_pk_mul_f32 v[210:211], v[12:13], v[92:93]
	v_add_f32_e32 v220, v212, v213
	v_add_f32_e32 v221, v216, v217
	v_pk_fma_f32 v[196:197], v[126:127], v[110:111], v[196:197] op_sel_hi:[0,1,1]
	v_pk_fma_f32 v[204:205], v[126:127], v[110:111], v[204:205] op_sel:[1,0,0] op_sel_hi:[1,1,1]
	v_add_f32_dpp v220, v220, v220 quad_perm:[1,0,3,2] row_mask:0xf bank_mask:0xf bound_ctrl:1
	v_add_f32_dpp v221, v221, v221 quad_perm:[1,0,3,2] row_mask:0xf bank_mask:0xf bound_ctrl:1
	v_pk_fma_f32 v[198:199], v[126:127], v[112:113], v[198:199] op_sel_hi:[0,1,1]
	v_pk_fma_f32 v[206:207], v[126:127], v[112:113], v[206:207] op_sel:[1,0,0] op_sel_hi:[1,1,1]
	v_add_f32_dpp v220, v220, v220 quad_perm:[2,3,0,1] row_mask:0xf bank_mask:0xf bound_ctrl:1
	v_add_f32_dpp v221, v221, v221 quad_perm:[2,3,0,1] row_mask:0xf bank_mask:0xf bound_ctrl:1
	v_pk_fma_f32 v[200:201], v[126:127], v[114:115], v[200:201] op_sel_hi:[0,1,1]
	v_pk_fma_f32 v[208:209], v[126:127], v[114:115], v[208:209] op_sel:[1,0,0] op_sel_hi:[1,1,1]
	v_add_f32_dpp v220, v220, v220 row_half_mirror row_mask:0xf bank_mask:0xf bound_ctrl:1
	v_add_f32_dpp v221, v221, v221 row_half_mirror row_mask:0xf bank_mask:0xf bound_ctrl:1
	v_pk_fma_f32 v[202:203], v[126:127], v[116:117], v[202:203] op_sel_hi:[0,1,1]
	v_pk_fma_f32 v[210:211], v[126:127], v[116:117], v[210:211] op_sel:[1,0,0] op_sel_hi:[1,1,1]
	v_pk_fma_f32 v[22:23], v[220:221], v[102:103], v[196:197] op_sel_hi:[0,1,1] neg_lo:[1,0,0] neg_hi:[1,0,0]
	v_pk_fma_f32 v[14:15], v[220:221], v[102:103], v[204:205] op_sel:[1,0,0] op_sel_hi:[1,1,1] neg_lo:[1,0,0] neg_hi:[1,0,0]
	v_pk_fma_f32 v[24:25], v[220:221], v[104:105], v[198:199] op_sel_hi:[0,1,1] neg_lo:[1,0,0] neg_hi:[1,0,0]
	v_pk_fma_f32 v[16:17], v[220:221], v[104:105], v[206:207] op_sel:[1,0,0] op_sel_hi:[1,1,1] neg_lo:[1,0,0] neg_hi:[1,0,0]
	v_pk_fma_f32 v[18:19], v[220:221], v[106:107], v[200:201] op_sel_hi:[0,1,1] neg_lo:[1,0,0] neg_hi:[1,0,0]
	v_pk_fma_f32 v[10:11], v[220:221], v[106:107], v[208:209] op_sel:[1,0,0] op_sel_hi:[1,1,1] neg_lo:[1,0,0] neg_hi:[1,0,0]
	v_pk_fma_f32 v[20:21], v[220:221], v[108:109], v[202:203] op_sel_hi:[0,1,1] neg_lo:[1,0,0] neg_hi:[1,0,0]
	v_pk_fma_f32 v[12:13], v[220:221], v[108:109], v[210:211] op_sel:[1,0,0] op_sel_hi:[1,1,1] neg_lo:[1,0,0] neg_hi:[1,0,0]
	v_pk_mul_f32 v[222:223], v[22:23], v[118:119]
	v_pk_mul_f32 v[224:225], v[14:15], v[118:119]
	v_pk_fma_f32 v[222:223], v[24:25], v[120:121], v[222:223]
	v_pk_fma_f32 v[224:225], v[16:17], v[120:121], v[224:225]
	v_pk_fma_f32 v[222:223], v[18:19], v[122:123], v[222:223]
	v_pk_fma_f32 v[224:225], v[10:11], v[122:123], v[224:225]
	v_pk_fma_f32 v[222:223], v[20:21], v[124:125], v[222:223]
	v_pk_fma_f32 v[224:225], v[12:13], v[124:125], v[224:225]
	s_waitcnt lgkmcnt(0)
; __device__ __forceinline__ void scan_rows(f32x2 (&X)[8], const ScanOps& o, const f32x4 (&b)[2], const f32x4 (&kd)[2], const f32x4 (&r)[2], const bool use_v, float& yA, float& yB) {
;     f32x2 aA = X[0] * o.kk[0].xy, aB = X[4] * o.kk[0].xy;
;     aA += X[1] * o.kk[0].zw; aB += X[5] * o.kk[0].zw;
;     aA += X[2] * o.kk[1].xy; aB += X[6] * o.kk[1].xy;
;     aA += X[3] * o.kk[1].zw; aB += X[7] * o.kk[1].zw;
;     const float saA = sum8(aA.x + aA.y), saB = sum8(aB.x + aB.y);
;     const f32x2 nA = (f32x2){-saA, -saA}, nB = (f32x2){-saB, -saB}, vA = (f32x2){o.v.x, o.v.x}, vB = (f32x2){o.v.y, o.v.y};
;     f32x2 tA, tB, accA, accB;
;     tA = X[0] * o.w[0].xy; tA += nA * b[0].xy; if (use_v) tA += vA * kd[0].xy; X[0] = tA; accA = tA * r[0].xy;
;     tB = X[4] * o.w[0].xy; tB += nB * b[0].xy; if (use_v) tB += vB * kd[0].xy; X[4] = tB; accB = tB * r[0].xy;
;     tA = X[1] * o.w[0].zw; tA += nA * b[0].zw; if (use_v) tA += vA * kd[0].zw; X[1] = tA; accA += tA * r[0].zw;
;     tB = X[5] * o.w[0].zw; tB += nB * b[0].zw; if (use_v) tB += vB * kd[0].zw; X[5] = tB; accB += tB * r[0].zw;
;     tA = X[2] * o.w[1].xy; tA += nA * b[1].xy; if (use_v) tA += vA * kd[1].xy; X[2] = tA; accA += tA * r[1].xy;
;     tB = X[6] * o.w[1].xy; tB += nB * b[1].xy; if (use_v) tB += vB * kd[1].xy; X[6] = tB; accB += tB * r[1].xy;
;     tA = X[3] * o.w[1].zw; tA += nA * b[1].zw; if (use_v) tA += vA * kd[1].zw; X[3] = tA; accA += tA * r[1].zw;
;     tB = X[7] * o.w[1].zw; tB += nB * b[1].zw; if (use_v) tB += vB * kd[1].zw; X[7] = tB; accB += tB * r[1].zw;
;     yA = sum8(accA.x + accA.y); yB = sum8(accB.x + accB.y);
; __device__ void phase_scan(int c, const bf16_t* PROJ, const float* k_k, const bf16_t* Wd, const bf16_t* Bd, const float* k_a, bf16_t* Y, bf16_t* Q, float* FS, float* sm) {
;     ...
;                 for (int i = 0; i < 16; i += 2) {
;                     float yA = 0.f, yB = 0.f;
;                     scan_ld(ob, obv, i + 1, B);
;                     if (roleP) A.v = (f32x2){0.f, 0.f};
;                     scan_step1(X, A, ob + i * 64, yA, yB);
;                     *(f32x2*)(obw + i * 16 + 2 * vp) = (f32x2){yA, yB};
;                     if (i + 2 < 16) scan_ld(ob, obv, i + 2, A);
;                     if (roleP) B.v = (f32x2){0.f, 0.f};
;                     scan_step1(X, B, ob + (i + 1) * 64, yA, yB);
;                     *(f32x2*)(obw + (i + 1) * 16 + 2 * vp) = (f32x2){yA, yB};
	ds_read_b128 v[86:89], v84 offset:512
	ds_read_b128 v[90:93], v84 offset:528
	ds_read_b128 v[94:97], v84 offset:4608
	ds_read_b128 v[98:101], v84 offset:4624
	ds_read_b128 v[102:105], v84 offset:8704
	ds_read_b128 v[106:109], v84 offset:8720
	ds_read_b128 v[110:113], v84 offset:12800
	ds_read_b128 v[114:117], v84 offset:12816
	ds_read_b128 v[118:121], v84 offset:16896
	ds_read_b128 v[122:125], v84 offset:16912
	ds_read_b64 v[126:127], v85 offset:20992
	v_pk_mul_f32 v[212:213], v[22:23], v[136:137]
	v_pk_mul_f32 v[216:217], v[14:15], v[136:137]
	v_pk_mul_f32 v[196:197], v[22:23], v[128:129]
	v_pk_mul_f32 v[204:205], v[14:15], v[128:129]
	v_pk_fma_f32 v[212:213], v[24:25], v[138:139], v[212:213]
	v_pk_fma_f32 v[216:217], v[16:17], v[138:139], v[216:217]
	v_pk_mul_f32 v[198:199], v[24:25], v[130:131]
	v_pk_mul_f32 v[206:207], v[16:17], v[130:131]
	v_pk_fma_f32 v[212:213], v[18:19], v[140:141], v[212:213]
	v_pk_fma_f32 v[216:217], v[10:11], v[140:141], v[216:217]
	v_pk_mul_f32 v[200:201], v[18:19], v[132:133]
	v_pk_mul_f32 v[208:209], v[10:11], v[132:133]
	v_pk_fma_f32 v[212:213], v[20:21], v[142:143], v[212:213]
	v_pk_fma_f32 v[216:217], v[12:13], v[142:143], v[216:217]
	v_pk_mul_f32 v[202:203], v[20:21], v[134:135]
	v_pk_mul_f32 v[210:211], v[12:13], v[134:135]
	v_add_f32_e32 v226, v222, v223
	v_add_f32_e32 v227, v224, v225
	v_add_f32_e32 v220, v212, v213
	v_add_f32_e32 v221, v216, v217
	v_pk_fma_f32 v[196:197], v[168:169], v[152:153], v[196:197] op_sel_hi:[0,1,1]
	v_pk_fma_f32 v[204:205], v[168:169], v[152:153], v[204:205] op_sel:[1,0,0] op_sel_hi:[1,1,1]
	ds_write_b64 v228, v[226:227]
	v_add_f32_dpp v220, v220, v220 quad_perm:[1,0,3,2] row_mask:0xf bank_mask:0xf bound_ctrl:1
	v_add_f32_dpp v221, v221, v221 quad_perm:[1,0,3,2] row_mask:0xf bank_mask:0xf bound_ctrl:1
	v_pk_fma_f32 v[198:199], v[168:169], v[154:155], v[198:199] op_sel_hi:[0,1,1]
	v_pk_fma_f32 v[206:207], v[168:169], v[154:155], v[206:207] op_sel:[1,0,0] op_sel_hi:[1,1,1]
	v_add_f32_dpp v220, v220, v220 quad_perm:[2,3,0,1] row_mask:0xf bank_mask:0xf bound_ctrl:1
	v_add_f32_dpp v221, v221, v221 quad_perm:[2,3,0,1] row_mask:0xf bank_mask:0xf bound_ctrl:1
	v_pk_fma_f32 v[200:201], v[168:169], v[156:157], v[200:201] op_sel_hi:[0,1,1]
	v_pk_fma_f32 v[208:209], v[168:169], v[156:157], v[208:209] op_sel:[1,0,0] op_sel_hi:[1,1,1]
	v_add_f32_dpp v220, v220, v220 row_half_mirror row_mask:0xf bank_mask:0xf bound_ctrl:1
	v_add_f32_dpp v221, v221, v221 row_half_mirror row_mask:0xf bank_mask:0xf bound_ctrl:1
	v_pk_fma_f32 v[202:203], v[168:169], v[158:159], v[202:203] op_sel_hi:[0,1,1]
	v_pk_fma_f32 v[210:211], v[168:169], v[158:159], v[210:211] op_sel:[1,0,0] op_sel_hi:[1,1,1]
	v_pk_fma_f32 v[22:23], v[220:221], v[144:145], v[196:197] op_sel_hi:[0,1,1] neg_lo:[1,0,0] neg_hi:[1,0,0]
	v_pk_fma_f32 v[14:15], v[220:221], v[144:145], v[204:205] op_sel:[1,0,0] op_sel_hi:[1,1,1] neg_lo:[1,0,0] neg_hi:[1,0,0]
	v_pk_fma_f32 v[24:25], v[220:221], v[146:147], v[198:199] op_sel_hi:[0,1,1] neg_lo:[1,0,0] neg_hi:[1,0,0]
	v_pk_fma_f32 v[16:17], v[220:221], v[146:147], v[206:207] op_sel:[1,0,0] op_sel_hi:[1,1,1] neg_lo:[1,0,0] neg_hi:[1,0,0]
	v_pk_fma_f32 v[18:19], v[220:221], v[148:149], v[200:201] op_sel_hi:[0,1,1] neg_lo:[1,0,0] neg_hi:[1,0,0]
	v_pk_fma_f32 v[10:11], v[220:221], v[148:149], v[208:209] op_sel:[1,0,0] op_sel_hi:[1,1,1] neg_lo:[1,0,0] neg_hi:[1,0,0]
	v_pk_fma_f32 v[20:21], v[220:221], v[150:151], v[202:203] op_sel_hi:[0,1,1] neg_lo:[1,0,0] neg_hi:[1,0,0]
	v_pk_fma_f32 v[12:13], v[220:221], v[150:151], v[210:211] op_sel:[1,0,0] op_sel_hi:[1,1,1] neg_lo:[1,0,0] neg_hi:[1,0,0]
	v_pk_mul_f32 v[222:223], v[22:23], v[160:161]
	v_pk_mul_f32 v[224:225], v[14:15], v[160:161]
	v_pk_fma_f32 v[222:223], v[24:25], v[162:163], v[222:223]
	v_pk_fma_f32 v[224:225], v[16:17], v[162:163], v[224:225]
	v_pk_fma_f32 v[222:223], v[18:19], v[164:165], v[222:223]
	v_pk_fma_f32 v[224:225], v[10:11], v[164:165], v[224:225]
	v_pk_fma_f32 v[222:223], v[20:21], v[166:167], v[222:223]
	v_pk_fma_f32 v[224:225], v[12:13], v[166:167], v[224:225]
	s_waitcnt lgkmcnt(0)
	ds_read_b128 v[128:131], v84 offset:768
	ds_read_b128 v[132:135], v84 offset:784
	ds_read_b128 v[136:139], v84 offset:4864
	ds_read_b128 v[140:143], v84 offset:4880
	ds_read_b128 v[144:147], v84 offset:8960
	ds_read_b128 v[148:151], v84 offset:8976
	ds_read_b128 v[152:155], v84 offset:13056
	ds_read_b128 v[156:159], v84 offset:13072
	ds_read_b128 v[160:163], v84 offset:17152
	ds_read_b128 v[164:167], v84 offset:17168
	ds_read_b64 v[168:169], v85 offset:21248
	v_pk_mul_f32 v[212:213], v[22:23], v[94:95]
	v_pk_mul_f32 v[216:217], v[14:15], v[94:95]
	v_pk_mul_f32 v[196:197], v[22:23], v[86:87]
	v_pk_mul_f32 v[204:205], v[14:15], v[86:87]
	v_pk_fma_f32 v[212:213], v[24:25], v[96:97], v[212:213]
	v_pk_fma_f32 v[216:217], v[16:17], v[96:97], v[216:217]
	v_pk_mul_f32 v[198:199], v[24:25], v[88:89]
	v_pk_mul_f32 v[206:207], v[16:17], v[88:89]
	v_pk_fma_f32 v[212:213], v[18:19], v[98:99], v[212:213]
	v_pk_fma_f32 v[216:217], v[10:11], v[98:99], v[216:217]
	v_pk_mul_f32 v[200:201], v[18:19], v[90:91]
	v_pk_mul_f32 v[208:209], v[10:11], v[90:91]
	v_pk_fma_f32 v[212:213], v[20:21], v[100:101], v[212:213]
	v_pk_fma_f32 v[216:217], v[12:13], v[100:101], v[216:217]
	v_pk_mul_f32 v[202:203], v[20:21], v[92:93]
	v_pk_mul_f32 v[210:211], v[12:13], v[92:93]
	v_add_f32_e32 v226, v222, v223
	v_add_f32_e32 v227, v224, v225
	v_add_f32_e32 v220, v212, v213
	v_add_f32_e32 v221, v216, v217
	v_pk_fma_f32 v[196:197], v[126:127], v[110:111], v[196:197] op_sel_hi:[0,1,1]
	v_pk_fma_f32 v[204:205], v[126:127], v[110:111], v[204:205] op_sel:[1,0,0] op_sel_hi:[1,1,1]
; __device__ __forceinline__ void scan_rows(f32x2 (&X)[8], const ScanOps& o, const f32x4 (&b)[2], const f32x4 (&kd)[2], const f32x4 (&r)[2], const bool use_v, float& yA, float& yB) {
;     f32x2 aA = X[0] * o.kk[0].xy, aB = X[4] * o.kk[0].xy;
;     aA += X[1] * o.kk[0].zw; aB += X[5] * o.kk[0].zw;
;     aA += X[2] * o.kk[1].xy; aB += X[6] * o.kk[1].xy;
;     aA += X[3] * o.kk[1].zw; aB += X[7] * o.kk[1].zw;
;     const float saA = sum8(aA.x + aA.y), saB = sum8(aB.x + aB.y);
;     const f32x2 nA = (f32x2){-saA, -saA}, nB = (f32x2){-saB, -saB}, vA = (f32x2){o.v.x, o.v.x}, vB = (f32x2){o.v.y, o.v.y};
;     f32x2 tA, tB, accA, accB;
;     tA = X[0] * o.w[0].xy; tA += nA * b[0].xy; if (use_v) tA += vA * kd[0].xy; X[0] = tA; accA = tA * r[0].xy;
;     tB = X[4] * o.w[0].xy; tB += nB * b[0].xy; if (use_v) tB += vB * kd[0].xy; X[4] = tB; accB = tB * r[0].xy;
;     tA = X[1] * o.w[0].zw; tA += nA * b[0].zw; if (use_v) tA += vA * kd[0].zw; X[1] = tA; accA += tA * r[0].zw;
;     tB = X[5] * o.w[0].zw; tB += nB * b[0].zw; if (use_v) tB += vB * kd[0].zw; X[5] = tB; accB += tB * r[0].zw;
;     tA = X[2] * o.w[1].xy; tA += nA * b[1].xy; if (use_v) tA += vA * kd[1].xy; X[2] = tA; accA += tA * r[1].xy;
;     tB = X[6] * o.w[1].xy; tB += nB * b[1].xy; if (use_v) tB += vB * kd[1].xy; X[6] = tB; accB += tB * r[1].xy;
;     tA = X[3] * o.w[1].zw; tA += nA * b[1].zw; if (use_v) tA += vA * kd[1].zw; X[3] = tA; accA += tA * r[1].zw;
;     tB = X[7] * o.w[1].zw; tB += nB * b[1].zw; if (use_v) tB += vB * kd[1].zw; X[7] = tB; accB += tB * r[1].zw;
;     yA = sum8(accA.x + accA.y); yB = sum8(accB.x + accB.y);
; __device__ void phase_scan(int c, const bf16_t* PROJ, const float* k_k, const bf16_t* Wd, const bf16_t* Bd, const float* k_a, bf16_t* Y, bf16_t* Q, float* FS, float* sm) {
;     ...
;                 for (int i = 0; i < 16; i += 2) {
;                     float yA = 0.f, yB = 0.f;
;                     scan_ld(ob, obv, i + 1, B);
;                     if (roleP) A.v = (f32x2){0.f, 0.f};
;                     scan_step1(X, A, ob + i * 64, yA, yB);
;                     *(f32x2*)(obw + i * 16 + 2 * vp) = (f32x2){yA, yB};
;                     if (i + 2 < 16) scan_ld(ob, obv, i + 2, A);
;                     if (roleP) B.v = (f32x2){0.f, 0.f};
;                     scan_step1(X, B, ob + (i + 1) * 64, yA, yB);
;                     *(f32x2*)(obw + (i + 1) * 16 + 2 * vp) = (f32x2){yA, yB};
	ds_write_b64 v228, v[226:227] offset:576
	v_add_f32_dpp v220, v220, v220 quad_perm:[1,0,3,2] row_mask:0xf bank_mask:0xf bound_ctrl:1
	v_add_f32_dpp v221, v221, v221 quad_perm:[1,0,3,2] row_mask:0xf bank_mask:0xf bound_ctrl:1
	v_pk_fma_f32 v[198:199], v[126:127], v[112:113], v[198:199] op_sel_hi:[0,1,1]
	v_pk_fma_f32 v[206:207], v[126:127], v[112:113], v[206:207] op_sel:[1,0,0] op_sel_hi:[1,1,1]
	v_add_f32_dpp v220, v220, v220 quad_perm:[2,3,0,1] row_mask:0xf bank_mask:0xf bound_ctrl:1
	v_add_f32_dpp v221, v221, v221 quad_perm:[2,3,0,1] row_mask:0xf bank_mask:0xf bound_ctrl:1
	v_pk_fma_f32 v[200:201], v[126:127], v[114:115], v[200:201] op_sel_hi:[0,1,1]
	v_pk_fma_f32 v[208:209], v[126:127], v[114:115], v[208:209] op_sel:[1,0,0] op_sel_hi:[1,1,1]
	v_add_f32_dpp v220, v220, v220 row_half_mirror row_mask:0xf bank_mask:0xf bound_ctrl:1
	v_add_f32_dpp v221, v221, v221 row_half_mirror row_mask:0xf bank_mask:0xf bound_ctrl:1
	v_pk_fma_f32 v[202:203], v[126:127], v[116:117], v[202:203] op_sel_hi:[0,1,1]
	v_pk_fma_f32 v[210:211], v[126:127], v[116:117], v[210:211] op_sel:[1,0,0] op_sel_hi:[1,1,1]
	v_pk_fma_f32 v[22:23], v[220:221], v[102:103], v[196:197] op_sel_hi:[0,1,1] neg_lo:[1,0,0] neg_hi:[1,0,0]
	v_pk_fma_f32 v[14:15], v[220:221], v[102:103], v[204:205] op_sel:[1,0,0] op_sel_hi:[1,1,1] neg_lo:[1,0,0] neg_hi:[1,0,0]
	v_pk_fma_f32 v[24:25], v[220:221], v[104:105], v[198:199] op_sel_hi:[0,1,1] neg_lo:[1,0,0] neg_hi:[1,0,0]
	v_pk_fma_f32 v[16:17], v[220:221], v[104:105], v[206:207] op_sel:[1,0,0] op_sel_hi:[1,1,1] neg_lo:[1,0,0] neg_hi:[1,0,0]
	v_pk_fma_f32 v[18:19], v[220:221], v[106:107], v[200:201] op_sel_hi:[0,1,1] neg_lo:[1,0,0] neg_hi:[1,0,0]
	v_pk_fma_f32 v[10:11], v[220:221], v[106:107], v[208:209] op_sel:[1,0,0] op_sel_hi:[1,1,1] neg_lo:[1,0,0] neg_hi:[1,0,0]
	v_pk_fma_f32 v[20:21], v[220:221], v[108:109], v[202:203] op_sel_hi:[0,1,1] neg_lo:[1,0,0] neg_hi:[1,0,0]
	v_pk_fma_f32 v[12:13], v[220:221], v[108:109], v[210:211] op_sel:[1,0,0] op_sel_hi:[1,1,1] neg_lo:[1,0,0] neg_hi:[1,0,0]
	v_pk_mul_f32 v[222:223], v[22:23], v[118:119]
	v_pk_mul_f32 v[224:225], v[14:15], v[118:119]
	v_pk_fma_f32 v[222:223], v[24:25], v[120:121], v[222:223]
	v_pk_fma_f32 v[224:225], v[16:17], v[120:121], v[224:225]
	v_pk_fma_f32 v[222:223], v[18:19], v[122:123], v[222:223]
	v_pk_fma_f32 v[224:225], v[10:11], v[122:123], v[224:225]
	v_pk_fma_f32 v[222:223], v[20:21], v[124:125], v[222:223]
	v_pk_fma_f32 v[224:225], v[12:13], v[124:125], v[224:225]
	s_waitcnt lgkmcnt(0)
	ds_read_b128 v[86:89], v84 offset:1024
	ds_read_b128 v[90:93], v84 offset:1040
	ds_read_b128 v[94:97], v84 offset:5120
	ds_read_b128 v[98:101], v84 offset:5136
	ds_read_b128 v[102:105], v84 offset:9216
	ds_read_b128 v[106:109], v84 offset:9232
	ds_read_b128 v[110:113], v84 offset:13312
	ds_read_b128 v[114:117], v84 offset:13328
	ds_read_b128 v[118:121], v84 offset:17408
	ds_read_b128 v[122:125], v84 offset:17424
	ds_read_b64 v[126:127], v85 offset:21504
	v_pk_mul_f32 v[212:213], v[22:23], v[136:137]
	v_pk_mul_f32 v[216:217], v[14:15], v[136:137]
	v_pk_mul_f32 v[196:197], v[22:23], v[128:129]
	v_pk_mul_f32 v[204:205], v[14:15], v[128:129]
	v_pk_fma_f32 v[212:213], v[24:25], v[138:139], v[212:213]
	v_pk_fma_f32 v[216:217], v[16:17], v[138:139], v[216:217]
	v_pk_mul_f32 v[198:199], v[24:25], v[130:131]
	v_pk_mul_f32 v[206:207], v[16:17], v[130:131]
	v_pk_fma_f32 v[212:213], v[18:19], v[140:141], v[212:213]
	v_pk_fma_f32 v[216:217], v[10:11], v[140:141], v[216:217]
	v_pk_mul_f32 v[200:201], v[18:19], v[132:133]
	v_pk_mul_f32 v[208:209], v[10:11], v[132:133]
	v_pk_fma_f32 v[212:213], v[20:21], v[142:143], v[212:213]
	v_pk_fma_f32 v[216:217], v[12:13], v[142:143], v[216:217]
	v_pk_mul_f32 v[202:203], v[20:21], v[134:135]
	v_pk_mul_f32 v[210:211], v[12:13], v[134:135]
	v_add_f32_e32 v226, v222, v223
	v_add_f32_e32 v227, v224, v225
	v_add_f32_e32 v220, v212, v213
	v_add_f32_e32 v221, v216, v217
	v_pk_fma_f32 v[196:197], v[168:169], v[152:153], v[196:197] op_sel_hi:[0,1,1]
	v_pk_fma_f32 v[204:205], v[168:169], v[152:153], v[204:205] op_sel:[1,0,0] op_sel_hi:[1,1,1]
	ds_write_b64 v228, v[226:227] offset:1152
	v_add_f32_dpp v220, v220, v220 quad_perm:[1,0,3,2] row_mask:0xf bank_mask:0xf bound_ctrl:1
	v_add_f32_dpp v221, v221, v221 quad_perm:[1,0,3,2] row_mask:0xf bank_mask:0xf bound_ctrl:1
	v_pk_fma_f32 v[198:199], v[168:169], v[154:155], v[198:199] op_sel_hi:[0,1,1]
	v_pk_fma_f32 v[206:207], v[168:169], v[154:155], v[206:207] op_sel:[1,0,0] op_sel_hi:[1,1,1]
	v_add_f32_dpp v220, v220, v220 quad_perm:[2,3,0,1] row_mask:0xf bank_mask:0xf bound_ctrl:1
	v_add_f32_dpp v221, v221, v221 quad_perm:[2,3,0,1] row_mask:0xf bank_mask:0xf bound_ctrl:1
	v_pk_fma_f32 v[200:201], v[168:169], v[156:157], v[200:201] op_sel_hi:[0,1,1]
	v_pk_fma_f32 v[208:209], v[168:169], v[156:157], v[208:209] op_sel:[1,0,0] op_sel_hi:[1,1,1]
	v_add_f32_dpp v220, v220, v220 row_half_mirror row_mask:0xf bank_mask:0xf bound_ctrl:1
	v_add_f32_dpp v221, v221, v221 row_half_mirror row_mask:0xf bank_mask:0xf bound_ctrl:1
	v_pk_fma_f32 v[202:203], v[168:169], v[158:159], v[202:203] op_sel_hi:[0,1,1]
	v_pk_fma_f32 v[210:211], v[168:169], v[158:159], v[210:211] op_sel:[1,0,0] op_sel_hi:[1,1,1]
	v_pk_fma_f32 v[22:23], v[220:221], v[144:145], v[196:197] op_sel_hi:[0,1,1] neg_lo:[1,0,0] neg_hi:[1,0,0]
	v_pk_fma_f32 v[14:15], v[220:221], v[144:145], v[204:205] op_sel:[1,0,0] op_sel_hi:[1,1,1] neg_lo:[1,0,0] neg_hi:[1,0,0]
	v_pk_fma_f32 v[24:25], v[220:221], v[146:147], v[198:199] op_sel_hi:[0,1,1] neg_lo:[1,0,0] neg_hi:[1,0,0]
	v_pk_fma_f32 v[16:17], v[220:221], v[146:147], v[206:207] op_sel:[1,0,0] op_sel_hi:[1,1,1] neg_lo:[1,0,0] neg_hi:[1,0,0]
	v_pk_fma_f32 v[18:19], v[220:221], v[148:149], v[200:201] op_sel_hi:[0,1,1] neg_lo:[1,0,0] neg_hi:[1,0,0]
	v_pk_fma_f32 v[10:11], v[220:221], v[148:149], v[208:209] op_sel:[1,0,0] op_sel_hi:[1,1,1] neg_lo:[1,0,0] neg_hi:[1,0,0]
	v_pk_fma_f32 v[20:21], v[220:221], v[150:151], v[202:203] op_sel_hi:[0,1,1] neg_lo:[1,0,0] neg_hi:[1,0,0]
	v_pk_fma_f32 v[12:13], v[220:221], v[150:151], v[210:211] op_sel:[1,0,0] op_sel_hi:[1,1,1] neg_lo:[1,0,0] neg_hi:[1,0,0]
	v_pk_mul_f32 v[222:223], v[22:23], v[160:161]
	v_pk_mul_f32 v[224:225], v[14:15], v[160:161]
	v_pk_fma_f32 v[222:223], v[24:25], v[162:163], v[222:223]
	v_pk_fma_f32 v[224:225], v[16:17], v[162:163], v[224:225]
	v_pk_fma_f32 v[222:223], v[18:19], v[164:165], v[222:223]
	v_pk_fma_f32 v[224:225], v[10:11], v[164:165], v[224:225]
	v_pk_fma_f32 v[222:223], v[20:21], v[166:167], v[222:223]
	v_pk_fma_f32 v[224:225], v[12:13], v[166:167], v[224:225]
	s_waitcnt lgkmcnt(0)
; __device__ __forceinline__ void scan_rows(f32x2 (&X)[8], const ScanOps& o, const f32x4 (&b)[2], const f32x4 (&kd)[2], const f32x4 (&r)[2], const bool use_v, float& yA, float& yB) {
;     f32x2 aA = X[0] * o.kk[0].xy, aB = X[4] * o.kk[0].xy;
;     aA += X[1] * o.kk[0].zw; aB += X[5] * o.kk[0].zw;
;     aA += X[2] * o.kk[1].xy; aB += X[6] * o.kk[1].xy;
;     aA += X[3] * o.kk[1].zw; aB += X[7] * o.kk[1].zw;
;     const float saA = sum8(aA.x + aA.y), saB = sum8(aB.x + aB.y);
;     const f32x2 nA = (f32x2){-saA, -saA}, nB = (f32x2){-saB, -saB}, vA = (f32x2){o.v.x, o.v.x}, vB = (f32x2){o.v.y, o.v.y};
;     f32x2 tA, tB, accA, accB;
;     tA = X[0] * o.w[0].xy; tA += nA * b[0].xy; if (use_v) tA += vA * kd[0].xy; X[0] = tA; accA = tA * r[0].xy;
;     tB = X[4] * o.w[0].xy; tB += nB * b[0].xy; if (use_v) tB += vB * kd[0].xy; X[4] = tB; accB = tB * r[0].xy;
;     tA = X[1] * o.w[0].zw; tA += nA * b[0].zw; if (use_v) tA += vA * kd[0].zw; X[1] = tA; accA += tA * r[0].zw;
;     tB = X[5] * o.w[0].zw; tB += nB * b[0].zw; if (use_v) tB += vB * kd[0].zw; X[5] = tB; accB += tB * r[0].zw;
;     tA = X[2] * o.w[1].xy; tA += nA * b[1].xy; if (use_v) tA += vA * kd[1].xy; X[2] = tA; accA += tA * r[1].xy;
;     tB = X[6] * o.w[1].xy; tB += nB * b[1].xy; if (use_v) tB += vB * kd[1].xy; X[6] = tB; accB += tB * r[1].xy;
;     tA = X[3] * o.w[1].zw; tA += nA * b[1].zw; if (use_v) tA += vA * kd[1].zw; X[3] = tA; accA += tA * r[1].zw;
;     tB = X[7] * o.w[1].zw; tB += nB * b[1].zw; if (use_v) tB += vB * kd[1].zw; X[7] = tB; accB += tB * r[1].zw;
;     yA = sum8(accA.x + accA.y); yB = sum8(accB.x + accB.y);
; __device__ void phase_scan(int c, const bf16_t* PROJ, const float* k_k, const bf16_t* Wd, const bf16_t* Bd, const float* k_a, bf16_t* Y, bf16_t* Q, float* FS, float* sm) {
;     ...
;                 for (int i = 0; i < 16; i += 2) {
;                     float yA = 0.f, yB = 0.f;
;                     scan_ld(ob, obv, i + 1, B);
;                     if (roleP) A.v = (f32x2){0.f, 0.f};
;                     scan_step1(X, A, ob + i * 64, yA, yB);
;                     *(f32x2*)(obw + i * 16 + 2 * vp) = (f32x2){yA, yB};
;                     if (i + 2 < 16) scan_ld(ob, obv, i + 2, A);
;                     if (roleP) B.v = (f32x2){0.f, 0.f};
;                     scan_step1(X, B, ob + (i + 1) * 64, yA, yB);
;                     *(f32x2*)(obw + (i + 1) * 16 + 2 * vp) = (f32x2){yA, yB};
	ds_read_b128 v[128:131], v84 offset:1280
	ds_read_b128 v[132:135], v84 offset:1296
	ds_read_b128 v[136:139], v84 offset:5376
	ds_read_b128 v[140:143], v84 offset:5392
	ds_read_b128 v[144:147], v84 offset:9472
	ds_read_b128 v[148:151], v84 offset:9488
	ds_read_b128 v[152:155], v84 offset:13568
	ds_read_b128 v[156:159], v84 offset:13584
	ds_read_b128 v[160:163], v84 offset:17664
	ds_read_b128 v[164:167], v84 offset:17680
	ds_read_b64 v[168:169], v85 offset:21760
	v_pk_mul_f32 v[212:213], v[22:23], v[94:95]
	v_pk_mul_f32 v[216:217], v[14:15], v[94:95]
	v_pk_mul_f32 v[196:197], v[22:23], v[86:87]
	v_pk_mul_f32 v[204:205], v[14:15], v[86:87]
	v_pk_fma_f32 v[212:213], v[24:25], v[96:97], v[212:213]
	v_pk_fma_f32 v[216:217], v[16:17], v[96:97], v[216:217]
	v_pk_mul_f32 v[198:199], v[24:25], v[88:89]
	v_pk_mul_f32 v[206:207], v[16:17], v[88:89]
	v_pk_fma_f32 v[212:213], v[18:19], v[98:99], v[212:213]
	v_pk_fma_f32 v[216:217], v[10:11], v[98:99], v[216:217]
	v_pk_mul_f32 v[200:201], v[18:19], v[90:91]
	v_pk_mul_f32 v[208:209], v[10:11], v[90:91]
	v_pk_fma_f32 v[212:213], v[20:21], v[100:101], v[212:213]
	v_pk_fma_f32 v[216:217], v[12:13], v[100:101], v[216:217]
	v_pk_mul_f32 v[202:203], v[20:21], v[92:93]
	v_pk_mul_f32 v[210:211], v[12:13], v[92:93]
	v_add_f32_e32 v226, v222, v223
	v_add_f32_e32 v227, v224, v225
	v_add_f32_e32 v220, v212, v213
	v_add_f32_e32 v221, v216, v217
	v_pk_fma_f32 v[196:197], v[126:127], v[110:111], v[196:197] op_sel_hi:[0,1,1]
	v_pk_fma_f32 v[204:205], v[126:127], v[110:111], v[204:205] op_sel:[1,0,0] op_sel_hi:[1,1,1]
	ds_write_b64 v228, v[226:227] offset:1728
	v_add_f32_dpp v220, v220, v220 quad_perm:[1,0,3,2] row_mask:0xf bank_mask:0xf bound_ctrl:1
	v_add_f32_dpp v221, v221, v221 quad_perm:[1,0,3,2] row_mask:0xf bank_mask:0xf bound_ctrl:1
	v_pk_fma_f32 v[198:199], v[126:127], v[112:113], v[198:199] op_sel_hi:[0,1,1]
	v_pk_fma_f32 v[206:207], v[126:127], v[112:113], v[206:207] op_sel:[1,0,0] op_sel_hi:[1,1,1]
	v_add_f32_dpp v220, v220, v220 quad_perm:[2,3,0,1] row_mask:0xf bank_mask:0xf bound_ctrl:1
	v_add_f32_dpp v221, v221, v221 quad_perm:[2,3,0,1] row_mask:0xf bank_mask:0xf bound_ctrl:1
	v_pk_fma_f32 v[200:201], v[126:127], v[114:115], v[200:201] op_sel_hi:[0,1,1]
	v_pk_fma_f32 v[208:209], v[126:127], v[114:115], v[208:209] op_sel:[1,0,0] op_sel_hi:[1,1,1]
	v_add_f32_dpp v220, v220, v220 row_half_mirror row_mask:0xf bank_mask:0xf bound_ctrl:1
	v_add_f32_dpp v221, v221, v221 row_half_mirror row_mask:0xf bank_mask:0xf bound_ctrl:1
	v_pk_fma_f32 v[202:203], v[126:127], v[116:117], v[202:203] op_sel_hi:[0,1,1]
	v_pk_fma_f32 v[210:211], v[126:127], v[116:117], v[210:211] op_sel:[1,0,0] op_sel_hi:[1,1,1]
	v_pk_fma_f32 v[22:23], v[220:221], v[102:103], v[196:197] op_sel_hi:[0,1,1] neg_lo:[1,0,0] neg_hi:[1,0,0]
	v_pk_fma_f32 v[14:15], v[220:221], v[102:103], v[204:205] op_sel:[1,0,0] op_sel_hi:[1,1,1] neg_lo:[1,0,0] neg_hi:[1,0,0]
	v_pk_fma_f32 v[24:25], v[220:221], v[104:105], v[198:199] op_sel_hi:[0,1,1] neg_lo:[1,0,0] neg_hi:[1,0,0]
	v_pk_fma_f32 v[16:17], v[220:221], v[104:105], v[206:207] op_sel:[1,0,0] op_sel_hi:[1,1,1] neg_lo:[1,0,0] neg_hi:[1,0,0]
	v_pk_fma_f32 v[18:19], v[220:221], v[106:107], v[200:201] op_sel_hi:[0,1,1] neg_lo:[1,0,0] neg_hi:[1,0,0]
	v_pk_fma_f32 v[10:11], v[220:221], v[106:107], v[208:209] op_sel:[1,0,0] op_sel_hi:[1,1,1] neg_lo:[1,0,0] neg_hi:[1,0,0]
	v_pk_fma_f32 v[20:21], v[220:221], v[108:109], v[202:203] op_sel_hi:[0,1,1] neg_lo:[1,0,0] neg_hi:[1,0,0]
	v_pk_fma_f32 v[12:13], v[220:221], v[108:109], v[210:211] op_sel:[1,0,0] op_sel_hi:[1,1,1] neg_lo:[1,0,0] neg_hi:[1,0,0]
	v_pk_mul_f32 v[222:223], v[22:23], v[118:119]
	v_pk_mul_f32 v[224:225], v[14:15], v[118:119]
	v_pk_fma_f32 v[222:223], v[24:25], v[120:121], v[222:223]
	v_pk_fma_f32 v[224:225], v[16:17], v[120:121], v[224:225]
	v_pk_fma_f32 v[222:223], v[18:19], v[122:123], v[222:223]
	v_pk_fma_f32 v[224:225], v[10:11], v[122:123], v[224:225]
	v_pk_fma_f32 v[222:223], v[20:21], v[124:125], v[222:223]
	v_pk_fma_f32 v[224:225], v[12:13], v[124:125], v[224:225]
	s_waitcnt lgkmcnt(0)
	ds_read_b128 v[86:89], v84 offset:1536
	ds_read_b128 v[90:93], v84 offset:1552
	ds_read_b128 v[94:97], v84 offset:5632
	ds_read_b128 v[98:101], v84 offset:5648
	ds_read_b128 v[102:105], v84 offset:9728
	ds_read_b128 v[106:109], v84 offset:9744
	ds_read_b128 v[110:113], v84 offset:13824
	ds_read_b128 v[114:117], v84 offset:13840
	ds_read_b128 v[118:121], v84 offset:17920
	ds_read_b128 v[122:125], v84 offset:17936
	ds_read_b64 v[126:127], v85 offset:22016
	v_pk_mul_f32 v[212:213], v[22:23], v[136:137]
	v_pk_mul_f32 v[216:217], v[14:15], v[136:137]
	v_pk_mul_f32 v[196:197], v[22:23], v[128:129]
	v_pk_mul_f32 v[204:205], v[14:15], v[128:129]
	v_pk_fma_f32 v[212:213], v[24:25], v[138:139], v[212:213]
	v_pk_fma_f32 v[216:217], v[16:17], v[138:139], v[216:217]
	v_pk_mul_f32 v[198:199], v[24:25], v[130:131]
	v_pk_mul_f32 v[206:207], v[16:17], v[130:131]
	v_pk_fma_f32 v[212:213], v[18:19], v[140:141], v[212:213]
	v_pk_fma_f32 v[216:217], v[10:11], v[140:141], v[216:217]
	v_pk_mul_f32 v[200:201], v[18:19], v[132:133]
	v_pk_mul_f32 v[208:209], v[10:11], v[132:133]
	v_pk_fma_f32 v[212:213], v[20:21], v[142:143], v[212:213]
	v_pk_fma_f32 v[216:217], v[12:13], v[142:143], v[216:217]
	v_pk_mul_f32 v[202:203], v[20:21], v[134:135]
	v_pk_mul_f32 v[210:211], v[12:13], v[134:135]
	v_add_f32_e32 v226, v222, v223
	v_add_f32_e32 v227, v224, v225
	v_add_f32_e32 v220, v212, v213
	v_add_f32_e32 v221, v216, v217
	v_pk_fma_f32 v[196:197], v[168:169], v[152:153], v[196:197] op_sel_hi:[0,1,1]
	v_pk_fma_f32 v[204:205], v[168:169], v[152:153], v[204:205] op_sel:[1,0,0] op_sel_hi:[1,1,1]
; __device__ __forceinline__ void scan_rows(f32x2 (&X)[8], const ScanOps& o, const f32x4 (&b)[2], const f32x4 (&kd)[2], const f32x4 (&r)[2], const bool use_v, float& yA, float& yB) {
;     f32x2 aA = X[0] * o.kk[0].xy, aB = X[4] * o.kk[0].xy;
;     aA += X[1] * o.kk[0].zw; aB += X[5] * o.kk[0].zw;
;     aA += X[2] * o.kk[1].xy; aB += X[6] * o.kk[1].xy;
;     aA += X[3] * o.kk[1].zw; aB += X[7] * o.kk[1].zw;
;     const float saA = sum8(aA.x + aA.y), saB = sum8(aB.x + aB.y);
;     const f32x2 nA = (f32x2){-saA, -saA}, nB = (f32x2){-saB, -saB}, vA = (f32x2){o.v.x, o.v.x}, vB = (f32x2){o.v.y, o.v.y};
;     f32x2 tA, tB, accA, accB;
;     tA = X[0] * o.w[0].xy; tA += nA * b[0].xy; if (use_v) tA += vA * kd[0].xy; X[0] = tA; accA = tA * r[0].xy;
;     tB = X[4] * o.w[0].xy; tB += nB * b[0].xy; if (use_v) tB += vB * kd[0].xy; X[4] = tB; accB = tB * r[0].xy;
;     tA = X[1] * o.w[0].zw; tA += nA * b[0].zw; if (use_v) tA += vA * kd[0].zw; X[1] = tA; accA += tA * r[0].zw;
;     tB = X[5] * o.w[0].zw; tB += nB * b[0].zw; if (use_v) tB += vB * kd[0].zw; X[5] = tB; accB += tB * r[0].zw;
;     tA = X[2] * o.w[1].xy; tA += nA * b[1].xy; if (use_v) tA += vA * kd[1].xy; X[2] = tA; accA += tA * r[1].xy;
;     tB = X[6] * o.w[1].xy; tB += nB * b[1].xy; if (use_v) tB += vB * kd[1].xy; X[6] = tB; accB += tB * r[1].xy;
;     tA = X[3] * o.w[1].zw; tA += nA * b[1].zw; if (use_v) tA += vA * kd[1].zw; X[3] = tA; accA += tA * r[1].zw;
;     tB = X[7] * o.w[1].zw; tB += nB * b[1].zw; if (use_v) tB += vB * kd[1].zw; X[7] = tB; accB += tB * r[1].zw;
;     yA = sum8(accA.x + accA.y); yB = sum8(accB.x + accB.y);
; __device__ void phase_scan(int c, const bf16_t* PROJ, const float* k_k, const bf16_t* Wd, const bf16_t* Bd, const float* k_a, bf16_t* Y, bf16_t* Q, float* FS, float* sm) {
;     ...
;                 for (int i = 0; i < 16; i += 2) {
;                     float yA = 0.f, yB = 0.f;
;                     scan_ld(ob, obv, i + 1, B);
;                     if (roleP) A.v = (f32x2){0.f, 0.f};
;                     scan_step1(X, A, ob + i * 64, yA, yB);
;                     *(f32x2*)(obw + i * 16 + 2 * vp) = (f32x2){yA, yB};
;                     if (i + 2 < 16) scan_ld(ob, obv, i + 2, A);
;                     if (roleP) B.v = (f32x2){0.f, 0.f};
;                     scan_step1(X, B, ob + (i + 1) * 64, yA, yB);
;                     *(f32x2*)(obw + (i + 1) * 16 + 2 * vp) = (f32x2){yA, yB};
	ds_write_b64 v228, v[226:227] offset:2304
	v_add_f32_dpp v220, v220, v220 quad_perm:[1,0,3,2] row_mask:0xf bank_mask:0xf bound_ctrl:1
	v_add_f32_dpp v221, v221, v221 quad_perm:[1,0,3,2] row_mask:0xf bank_mask:0xf bound_ctrl:1
	v_pk_fma_f32 v[198:199], v[168:169], v[154:155], v[198:199] op_sel_hi:[0,1,1]
	v_pk_fma_f32 v[206:207], v[168:169], v[154:155], v[206:207] op_sel:[1,0,0] op_sel_hi:[1,1,1]
	v_add_f32_dpp v220, v220, v220 quad_perm:[2,3,0,1] row_mask:0xf bank_mask:0xf bound_ctrl:1
	v_add_f32_dpp v221, v221, v221 quad_perm:[2,3,0,1] row_mask:0xf bank_mask:0xf bound_ctrl:1
	v_pk_fma_f32 v[200:201], v[168:169], v[156:157], v[200:201] op_sel_hi:[0,1,1]
	v_pk_fma_f32 v[208:209], v[168:169], v[156:157], v[208:209] op_sel:[1,0,0] op_sel_hi:[1,1,1]
	v_add_f32_dpp v220, v220, v220 row_half_mirror row_mask:0xf bank_mask:0xf bound_ctrl:1
	v_add_f32_dpp v221, v221, v221 row_half_mirror row_mask:0xf bank_mask:0xf bound_ctrl:1
	v_pk_fma_f32 v[202:203], v[168:169], v[158:159], v[202:203] op_sel_hi:[0,1,1]
	v_pk_fma_f32 v[210:211], v[168:169], v[158:159], v[210:211] op_sel:[1,0,0] op_sel_hi:[1,1,1]
	v_pk_fma_f32 v[22:23], v[220:221], v[144:145], v[196:197] op_sel_hi:[0,1,1] neg_lo:[1,0,0] neg_hi:[1,0,0]
	v_pk_fma_f32 v[14:15], v[220:221], v[144:145], v[204:205] op_sel:[1,0,0] op_sel_hi:[1,1,1] neg_lo:[1,0,0] neg_hi:[1,0,0]
	v_pk_fma_f32 v[24:25], v[220:221], v[146:147], v[198:199] op_sel_hi:[0,1,1] neg_lo:[1,0,0] neg_hi:[1,0,0]
	v_pk_fma_f32 v[16:17], v[220:221], v[146:147], v[206:207] op_sel:[1,0,0] op_sel_hi:[1,1,1] neg_lo:[1,0,0] neg_hi:[1,0,0]
	v_pk_fma_f32 v[18:19], v[220:221], v[148:149], v[200:201] op_sel_hi:[0,1,1] neg_lo:[1,0,0] neg_hi:[1,0,0]
	v_pk_fma_f32 v[10:11], v[220:221], v[148:149], v[208:209] op_sel:[1,0,0] op_sel_hi:[1,1,1] neg_lo:[1,0,0] neg_hi:[1,0,0]
	v_pk_fma_f32 v[20:21], v[220:221], v[150:151], v[202:203] op_sel_hi:[0,1,1] neg_lo:[1,0,0] neg_hi:[1,0,0]
	v_pk_fma_f32 v[12:13], v[220:221], v[150:151], v[210:211] op_sel:[1,0,0] op_sel_hi:[1,1,1] neg_lo:[1,0,0] neg_hi:[1,0,0]
	v_pk_mul_f32 v[222:223], v[22:23], v[160:161]
	v_pk_mul_f32 v[224:225], v[14:15], v[160:161]
	v_pk_fma_f32 v[222:223], v[24:25], v[162:163], v[222:223]
	v_pk_fma_f32 v[224:225], v[16:17], v[162:163], v[224:225]
	v_pk_fma_f32 v[222:223], v[18:19], v[164:165], v[222:223]
	v_pk_fma_f32 v[224:225], v[10:11], v[164:165], v[224:225]
	v_pk_fma_f32 v[222:223], v[20:21], v[166:167], v[222:223]
	v_pk_fma_f32 v[224:225], v[12:13], v[166:167], v[224:225]
	s_waitcnt lgkmcnt(0)
	ds_read_b128 v[128:131], v84 offset:1792
	ds_read_b128 v[132:135], v84 offset:1808
	ds_read_b128 v[136:139], v84 offset:5888
	ds_read_b128 v[140:143], v84 offset:5904
	ds_read_b128 v[144:147], v84 offset:9984
	ds_read_b128 v[148:151], v84 offset:10000
	ds_read_b128 v[152:155], v84 offset:14080
	ds_read_b128 v[156:159], v84 offset:14096
	ds_read_b128 v[160:163], v84 offset:18176
	ds_read_b128 v[164:167], v84 offset:18192
	ds_read_b64 v[168:169], v85 offset:22272
	v_pk_mul_f32 v[212:213], v[22:23], v[94:95]
	v_pk_mul_f32 v[216:217], v[14:15], v[94:95]
	v_pk_mul_f32 v[196:197], v[22:23], v[86:87]
	v_pk_mul_f32 v[204:205], v[14:15], v[86:87]
	v_pk_fma_f32 v[212:213], v[24:25], v[96:97], v[212:213]
	v_pk_fma_f32 v[216:217], v[16:17], v[96:97], v[216:217]
	v_pk_mul_f32 v[198:199], v[24:25], v[88:89]
	v_pk_mul_f32 v[206:207], v[16:17], v[88:89]
	v_pk_fma_f32 v[212:213], v[18:19], v[98:99], v[212:213]
	v_pk_fma_f32 v[216:217], v[10:11], v[98:99], v[216:217]
	v_pk_mul_f32 v[200:201], v[18:19], v[90:91]
	v_pk_mul_f32 v[208:209], v[10:11], v[90:91]
	v_pk_fma_f32 v[212:213], v[20:21], v[100:101], v[212:213]
	v_pk_fma_f32 v[216:217], v[12:13], v[100:101], v[216:217]
	v_pk_mul_f32 v[202:203], v[20:21], v[92:93]
	v_pk_mul_f32 v[210:211], v[12:13], v[92:93]
	v_add_f32_e32 v226, v222, v223
	v_add_f32_e32 v227, v224, v225
	v_add_f32_e32 v220, v212, v213
	v_add_f32_e32 v221, v216, v217
	v_pk_fma_f32 v[196:197], v[126:127], v[110:111], v[196:197] op_sel_hi:[0,1,1]
	v_pk_fma_f32 v[204:205], v[126:127], v[110:111], v[204:205] op_sel:[1,0,0] op_sel_hi:[1,1,1]
	ds_write_b64 v228, v[226:227] offset:2880
	v_add_f32_dpp v220, v220, v220 quad_perm:[1,0,3,2] row_mask:0xf bank_mask:0xf bound_ctrl:1
	v_add_f32_dpp v221, v221, v221 quad_perm:[1,0,3,2] row_mask:0xf bank_mask:0xf bound_ctrl:1
	v_pk_fma_f32 v[198:199], v[126:127], v[112:113], v[198:199] op_sel_hi:[0,1,1]
	v_pk_fma_f32 v[206:207], v[126:127], v[112:113], v[206:207] op_sel:[1,0,0] op_sel_hi:[1,1,1]
	v_add_f32_dpp v220, v220, v220 quad_perm:[2,3,0,1] row_mask:0xf bank_mask:0xf bound_ctrl:1
	v_add_f32_dpp v221, v221, v221 quad_perm:[2,3,0,1] row_mask:0xf bank_mask:0xf bound_ctrl:1
	v_pk_fma_f32 v[200:201], v[126:127], v[114:115], v[200:201] op_sel_hi:[0,1,1]
	v_pk_fma_f32 v[208:209], v[126:127], v[114:115], v[208:209] op_sel:[1,0,0] op_sel_hi:[1,1,1]
	v_add_f32_dpp v220, v220, v220 row_half_mirror row_mask:0xf bank_mask:0xf bound_ctrl:1
	v_add_f32_dpp v221, v221, v221 row_half_mirror row_mask:0xf bank_mask:0xf bound_ctrl:1
	v_pk_fma_f32 v[202:203], v[126:127], v[116:117], v[202:203] op_sel_hi:[0,1,1]
	v_pk_fma_f32 v[210:211], v[126:127], v[116:117], v[210:211] op_sel:[1,0,0] op_sel_hi:[1,1,1]
	v_pk_fma_f32 v[22:23], v[220:221], v[102:103], v[196:197] op_sel_hi:[0,1,1] neg_lo:[1,0,0] neg_hi:[1,0,0]
	v_pk_fma_f32 v[14:15], v[220:221], v[102:103], v[204:205] op_sel:[1,0,0] op_sel_hi:[1,1,1] neg_lo:[1,0,0] neg_hi:[1,0,0]
	v_pk_fma_f32 v[24:25], v[220:221], v[104:105], v[198:199] op_sel_hi:[0,1,1] neg_lo:[1,0,0] neg_hi:[1,0,0]
	v_pk_fma_f32 v[16:17], v[220:221], v[104:105], v[206:207] op_sel:[1,0,0] op_sel_hi:[1,1,1] neg_lo:[1,0,0] neg_hi:[1,0,0]
	v_pk_fma_f32 v[18:19], v[220:221], v[106:107], v[200:201] op_sel_hi:[0,1,1] neg_lo:[1,0,0] neg_hi:[1,0,0]
	v_pk_fma_f32 v[10:11], v[220:221], v[106:107], v[208:209] op_sel:[1,0,0] op_sel_hi:[1,1,1] neg_lo:[1,0,0] neg_hi:[1,0,0]
	v_pk_fma_f32 v[20:21], v[220:221], v[108:109], v[202:203] op_sel_hi:[0,1,1] neg_lo:[1,0,0] neg_hi:[1,0,0]
	v_pk_fma_f32 v[12:13], v[220:221], v[108:109], v[210:211] op_sel:[1,0,0] op_sel_hi:[1,1,1] neg_lo:[1,0,0] neg_hi:[1,0,0]
	v_pk_mul_f32 v[222:223], v[22:23], v[118:119]
	v_pk_mul_f32 v[224:225], v[14:15], v[118:119]
	v_pk_fma_f32 v[222:223], v[24:25], v[120:121], v[222:223]
	v_pk_fma_f32 v[224:225], v[16:17], v[120:121], v[224:225]
	v_pk_fma_f32 v[222:223], v[18:19], v[122:123], v[222:223]
	v_pk_fma_f32 v[224:225], v[10:11], v[122:123], v[224:225]
	v_pk_fma_f32 v[222:223], v[20:21], v[124:125], v[222:223]
	v_pk_fma_f32 v[224:225], v[12:13], v[124:125], v[224:225]
	s_waitcnt lgkmcnt(0)
; __device__ __forceinline__ void scan_rows(f32x2 (&X)[8], const ScanOps& o, const f32x4 (&b)[2], const f32x4 (&kd)[2], const f32x4 (&r)[2], const bool use_v, float& yA, float& yB) {
;     f32x2 aA = X[0] * o.kk[0].xy, aB = X[4] * o.kk[0].xy;
;     aA += X[1] * o.kk[0].zw; aB += X[5] * o.kk[0].zw;
;     aA += X[2] * o.kk[1].xy; aB += X[6] * o.kk[1].xy;
;     aA += X[3] * o.kk[1].zw; aB += X[7] * o.kk[1].zw;
;     const float saA = sum8(aA.x + aA.y), saB = sum8(aB.x + aB.y);
;     const f32x2 nA = (f32x2){-saA, -saA}, nB = (f32x2){-saB, -saB}, vA = (f32x2){o.v.x, o.v.x}, vB = (f32x2){o.v.y, o.v.y};
;     f32x2 tA, tB, accA, accB;
;     tA = X[0] * o.w[0].xy; tA += nA * b[0].xy; if (use_v) tA += vA * kd[0].xy; X[0] = tA; accA = tA * r[0].xy;
;     tB = X[4] * o.w[0].xy; tB += nB * b[0].xy; if (use_v) tB += vB * kd[0].xy; X[4] = tB; accB = tB * r[0].xy;
;     tA = X[1] * o.w[0].zw; tA += nA * b[0].zw; if (use_v) tA += vA * kd[0].zw; X[1] = tA; accA += tA * r[0].zw;
;     tB = X[5] * o.w[0].zw; tB += nB * b[0].zw; if (use_v) tB += vB * kd[0].zw; X[5] = tB; accB += tB * r[0].zw;
;     tA = X[2] * o.w[1].xy; tA += nA * b[1].xy; if (use_v) tA += vA * kd[1].xy; X[2] = tA; accA += tA * r[1].xy;
;     tB = X[6] * o.w[1].xy; tB += nB * b[1].xy; if (use_v) tB += vB * kd[1].xy; X[6] = tB; accB += tB * r[1].xy;
;     tA = X[3] * o.w[1].zw; tA += nA * b[1].zw; if (use_v) tA += vA * kd[1].zw; X[3] = tA; accA += tA * r[1].zw;
;     tB = X[7] * o.w[1].zw; tB += nB * b[1].zw; if (use_v) tB += vB * kd[1].zw; X[7] = tB; accB += tB * r[1].zw;
;     yA = sum8(accA.x + accA.y); yB = sum8(accB.x + accB.y);
; __device__ void phase_scan(int c, const bf16_t* PROJ, const float* k_k, const bf16_t* Wd, const bf16_t* Bd, const float* k_a, bf16_t* Y, bf16_t* Q, float* FS, float* sm) {
;     ...
;                 for (int i = 0; i < 16; i += 2) {
;                     float yA = 0.f, yB = 0.f;
;                     scan_ld(ob, obv, i + 1, B);
;                     if (roleP) A.v = (f32x2){0.f, 0.f};
;                     scan_step1(X, A, ob + i * 64, yA, yB);
;                     *(f32x2*)(obw + i * 16 + 2 * vp) = (f32x2){yA, yB};
;                     if (i + 2 < 16) scan_ld(ob, obv, i + 2, A);
;                     if (roleP) B.v = (f32x2){0.f, 0.f};
;                     scan_step1(X, B, ob + (i + 1) * 64, yA, yB);
;                     *(f32x2*)(obw + (i + 1) * 16 + 2 * vp) = (f32x2){yA, yB};
	ds_read_b128 v[86:89], v84 offset:2048
	ds_read_b128 v[90:93], v84 offset:2064
	ds_read_b128 v[94:97], v84 offset:6144
	ds_read_b128 v[98:101], v84 offset:6160
	ds_read_b128 v[102:105], v84 offset:10240
	ds_read_b128 v[106:109], v84 offset:10256
	ds_read_b128 v[110:113], v84 offset:14336
	ds_read_b128 v[114:117], v84 offset:14352
	ds_read_b128 v[118:121], v84 offset:18432
	ds_read_b128 v[122:125], v84 offset:18448
	ds_read_b64 v[126:127], v85 offset:22528
	v_pk_mul_f32 v[212:213], v[22:23], v[136:137]
	v_pk_mul_f32 v[216:217], v[14:15], v[136:137]
	v_pk_mul_f32 v[196:197], v[22:23], v[128:129]
	v_pk_mul_f32 v[204:205], v[14:15], v[128:129]
	v_pk_fma_f32 v[212:213], v[24:25], v[138:139], v[212:213]
	v_pk_fma_f32 v[216:217], v[16:17], v[138:139], v[216:217]
	v_pk_mul_f32 v[198:199], v[24:25], v[130:131]
	v_pk_mul_f32 v[206:207], v[16:17], v[130:131]
	v_pk_fma_f32 v[212:213], v[18:19], v[140:141], v[212:213]
	v_pk_fma_f32 v[216:217], v[10:11], v[140:141], v[216:217]
	v_pk_mul_f32 v[200:201], v[18:19], v[132:133]
	v_pk_mul_f32 v[208:209], v[10:11], v[132:133]
	v_pk_fma_f32 v[212:213], v[20:21], v[142:143], v[212:213]
	v_pk_fma_f32 v[216:217], v[12:13], v[142:143], v[216:217]
	v_pk_mul_f32 v[202:203], v[20:21], v[134:135]
	v_pk_mul_f32 v[210:211], v[12:13], v[134:135]
	v_add_f32_e32 v226, v222, v223
	v_add_f32_e32 v227, v224, v225
	v_add_f32_e32 v220, v212, v213
	v_add_f32_e32 v221, v216, v217
	v_pk_fma_f32 v[196:197], v[168:169], v[152:153], v[196:197] op_sel_hi:[0,1,1]
	v_pk_fma_f32 v[204:205], v[168:169], v[152:153], v[204:205] op_sel:[1,0,0] op_sel_hi:[1,1,1]
	ds_write_b64 v228, v[226:227] offset:3456
	v_add_f32_dpp v220, v220, v220 quad_perm:[1,0,3,2] row_mask:0xf bank_mask:0xf bound_ctrl:1
	v_add_f32_dpp v221, v221, v221 quad_perm:[1,0,3,2] row_mask:0xf bank_mask:0xf bound_ctrl:1
	v_pk_fma_f32 v[198:199], v[168:169], v[154:155], v[198:199] op_sel_hi:[0,1,1]
	v_pk_fma_f32 v[206:207], v[168:169], v[154:155], v[206:207] op_sel:[1,0,0] op_sel_hi:[1,1,1]
	v_add_f32_dpp v220, v220, v220 quad_perm:[2,3,0,1] row_mask:0xf bank_mask:0xf bound_ctrl:1
	v_add_f32_dpp v221, v221, v221 quad_perm:[2,3,0,1] row_mask:0xf bank_mask:0xf bound_ctrl:1
	v_pk_fma_f32 v[200:201], v[168:169], v[156:157], v[200:201] op_sel_hi:[0,1,1]
	v_pk_fma_f32 v[208:209], v[168:169], v[156:157], v[208:209] op_sel:[1,0,0] op_sel_hi:[1,1,1]
	v_add_f32_dpp v220, v220, v220 row_half_mirror row_mask:0xf bank_mask:0xf bound_ctrl:1
	v_add_f32_dpp v221, v221, v221 row_half_mirror row_mask:0xf bank_mask:0xf bound_ctrl:1
	v_pk_fma_f32 v[202:203], v[168:169], v[158:159], v[202:203] op_sel_hi:[0,1,1]
	v_pk_fma_f32 v[210:211], v[168:169], v[158:159], v[210:211] op_sel:[1,0,0] op_sel_hi:[1,1,1]
	v_pk_fma_f32 v[22:23], v[220:221], v[144:145], v[196:197] op_sel_hi:[0,1,1] neg_lo:[1,0,0] neg_hi:[1,0,0]
	v_pk_fma_f32 v[14:15], v[220:221], v[144:145], v[204:205] op_sel:[1,0,0] op_sel_hi:[1,1,1] neg_lo:[1,0,0] neg_hi:[1,0,0]
	v_pk_fma_f32 v[24:25], v[220:221], v[146:147], v[198:199] op_sel_hi:[0,1,1] neg_lo:[1,0,0] neg_hi:[1,0,0]
	v_pk_fma_f32 v[16:17], v[220:221], v[146:147], v[206:207] op_sel:[1,0,0] op_sel_hi:[1,1,1] neg_lo:[1,0,0] neg_hi:[1,0,0]
	v_pk_fma_f32 v[18:19], v[220:221], v[148:149], v[200:201] op_sel_hi:[0,1,1] neg_lo:[1,0,0] neg_hi:[1,0,0]
	v_pk_fma_f32 v[10:11], v[220:221], v[148:149], v[208:209] op_sel:[1,0,0] op_sel_hi:[1,1,1] neg_lo:[1,0,0] neg_hi:[1,0,0]
	v_pk_fma_f32 v[20:21], v[220:221], v[150:151], v[202:203] op_sel_hi:[0,1,1] neg_lo:[1,0,0] neg_hi:[1,0,0]
	v_pk_fma_f32 v[12:13], v[220:221], v[150:151], v[210:211] op_sel:[1,0,0] op_sel_hi:[1,1,1] neg_lo:[1,0,0] neg_hi:[1,0,0]
	v_pk_mul_f32 v[222:223], v[22:23], v[160:161]
	v_pk_mul_f32 v[224:225], v[14:15], v[160:161]
	v_pk_fma_f32 v[222:223], v[24:25], v[162:163], v[222:223]
	v_pk_fma_f32 v[224:225], v[16:17], v[162:163], v[224:225]
	v_pk_fma_f32 v[222:223], v[18:19], v[164:165], v[222:223]
	v_pk_fma_f32 v[224:225], v[10:11], v[164:165], v[224:225]
	v_pk_fma_f32 v[222:223], v[20:21], v[166:167], v[222:223]
	v_pk_fma_f32 v[224:225], v[12:13], v[166:167], v[224:225]
	s_waitcnt lgkmcnt(0)
	ds_read_b128 v[128:131], v84 offset:2304
	ds_read_b128 v[132:135], v84 offset:2320
	ds_read_b128 v[136:139], v84 offset:6400
	ds_read_b128 v[140:143], v84 offset:6416
	ds_read_b128 v[144:147], v84 offset:10496
	ds_read_b128 v[148:151], v84 offset:10512
	ds_read_b128 v[152:155], v84 offset:14592
	ds_read_b128 v[156:159], v84 offset:14608
	ds_read_b128 v[160:163], v84 offset:18688
	ds_read_b128 v[164:167], v84 offset:18704
	ds_read_b64 v[168:169], v85 offset:22784
	v_pk_mul_f32 v[212:213], v[22:23], v[94:95]
	v_pk_mul_f32 v[216:217], v[14:15], v[94:95]
	v_pk_mul_f32 v[196:197], v[22:23], v[86:87]
	v_pk_mul_f32 v[204:205], v[14:15], v[86:87]
	v_pk_fma_f32 v[212:213], v[24:25], v[96:97], v[212:213]
	v_pk_fma_f32 v[216:217], v[16:17], v[96:97], v[216:217]
	v_pk_mul_f32 v[198:199], v[24:25], v[88:89]
	v_pk_mul_f32 v[206:207], v[16:17], v[88:89]
	v_pk_fma_f32 v[212:213], v[18:19], v[98:99], v[212:213]
	v_pk_fma_f32 v[216:217], v[10:11], v[98:99], v[216:217]
	v_pk_mul_f32 v[200:201], v[18:19], v[90:91]
	v_pk_mul_f32 v[208:209], v[10:11], v[90:91]
	v_pk_fma_f32 v[212:213], v[20:21], v[100:101], v[212:213]
	v_pk_fma_f32 v[216:217], v[12:13], v[100:101], v[216:217]
	v_pk_mul_f32 v[202:203], v[20:21], v[92:93]
	v_pk_mul_f32 v[210:211], v[12:13], v[92:93]
	v_add_f32_e32 v226, v222, v223
	v_add_f32_e32 v227, v224, v225
	v_add_f32_e32 v220, v212, v213
	v_add_f32_e32 v221, v216, v217
	v_pk_fma_f32 v[196:197], v[126:127], v[110:111], v[196:197] op_sel_hi:[0,1,1]
	v_pk_fma_f32 v[204:205], v[126:127], v[110:111], v[204:205] op_sel:[1,0,0] op_sel_hi:[1,1,1]
; __device__ __forceinline__ void scan_rows(f32x2 (&X)[8], const ScanOps& o, const f32x4 (&b)[2], const f32x4 (&kd)[2], const f32x4 (&r)[2], const bool use_v, float& yA, float& yB) {
;     f32x2 aA = X[0] * o.kk[0].xy, aB = X[4] * o.kk[0].xy;
;     aA += X[1] * o.kk[0].zw; aB += X[5] * o.kk[0].zw;
;     aA += X[2] * o.kk[1].xy; aB += X[6] * o.kk[1].xy;
;     aA += X[3] * o.kk[1].zw; aB += X[7] * o.kk[1].zw;
;     const float saA = sum8(aA.x + aA.y), saB = sum8(aB.x + aB.y);
;     const f32x2 nA = (f32x2){-saA, -saA}, nB = (f32x2){-saB, -saB}, vA = (f32x2){o.v.x, o.v.x}, vB = (f32x2){o.v.y, o.v.y};
;     f32x2 tA, tB, accA, accB;
;     tA = X[0] * o.w[0].xy; tA += nA * b[0].xy; if (use_v) tA += vA * kd[0].xy; X[0] = tA; accA = tA * r[0].xy;
;     tB = X[4] * o.w[0].xy; tB += nB * b[0].xy; if (use_v) tB += vB * kd[0].xy; X[4] = tB; accB = tB * r[0].xy;
;     tA = X[1] * o.w[0].zw; tA += nA * b[0].zw; if (use_v) tA += vA * kd[0].zw; X[1] = tA; accA += tA * r[0].zw;
;     tB = X[5] * o.w[0].zw; tB += nB * b[0].zw; if (use_v) tB += vB * kd[0].zw; X[5] = tB; accB += tB * r[0].zw;
;     tA = X[2] * o.w[1].xy; tA += nA * b[1].xy; if (use_v) tA += vA * kd[1].xy; X[2] = tA; accA += tA * r[1].xy;
;     tB = X[6] * o.w[1].xy; tB += nB * b[1].xy; if (use_v) tB += vB * kd[1].xy; X[6] = tB; accB += tB * r[1].xy;
;     tA = X[3] * o.w[1].zw; tA += nA * b[1].zw; if (use_v) tA += vA * kd[1].zw; X[3] = tA; accA += tA * r[1].zw;
;     tB = X[7] * o.w[1].zw; tB += nB * b[1].zw; if (use_v) tB += vB * kd[1].zw; X[7] = tB; accB += tB * r[1].zw;
;     yA = sum8(accA.x + accA.y); yB = sum8(accB.x + accB.y);
; __device__ void phase_scan(int c, const bf16_t* PROJ, const float* k_k, const bf16_t* Wd, const bf16_t* Bd, const float* k_a, bf16_t* Y, bf16_t* Q, float* FS, float* sm) {
;     ...
;                 for (int i = 0; i < 16; i += 2) {
;                     float yA = 0.f, yB = 0.f;
;                     scan_ld(ob, obv, i + 1, B);
;                     if (roleP) A.v = (f32x2){0.f, 0.f};
;                     scan_step1(X, A, ob + i * 64, yA, yB);
;                     *(f32x2*)(obw + i * 16 + 2 * vp) = (f32x2){yA, yB};
;                     if (i + 2 < 16) scan_ld(ob, obv, i + 2, A);
;                     if (roleP) B.v = (f32x2){0.f, 0.f};
;                     scan_step1(X, B, ob + (i + 1) * 64, yA, yB);
;                     *(f32x2*)(obw + (i + 1) * 16 + 2 * vp) = (f32x2){yA, yB};
	ds_write_b64 v228, v[226:227] offset:4032
	v_add_f32_dpp v220, v220, v220 quad_perm:[1,0,3,2] row_mask:0xf bank_mask:0xf bound_ctrl:1
	v_add_f32_dpp v221, v221, v221 quad_perm:[1,0,3,2] row_mask:0xf bank_mask:0xf bound_ctrl:1
	v_pk_fma_f32 v[198:199], v[126:127], v[112:113], v[198:199] op_sel_hi:[0,1,1]
	v_pk_fma_f32 v[206:207], v[126:127], v[112:113], v[206:207] op_sel:[1,0,0] op_sel_hi:[1,1,1]
	v_add_f32_dpp v220, v220, v220 quad_perm:[2,3,0,1] row_mask:0xf bank_mask:0xf bound_ctrl:1
	v_add_f32_dpp v221, v221, v221 quad_perm:[2,3,0,1] row_mask:0xf bank_mask:0xf bound_ctrl:1
	v_pk_fma_f32 v[200:201], v[126:127], v[114:115], v[200:201] op_sel_hi:[0,1,1]
	v_pk_fma_f32 v[208:209], v[126:127], v[114:115], v[208:209] op_sel:[1,0,0] op_sel_hi:[1,1,1]
	v_add_f32_dpp v220, v220, v220 row_half_mirror row_mask:0xf bank_mask:0xf bound_ctrl:1
	v_add_f32_dpp v221, v221, v221 row_half_mirror row_mask:0xf bank_mask:0xf bound_ctrl:1
	v_pk_fma_f32 v[202:203], v[126:127], v[116:117], v[202:203] op_sel_hi:[0,1,1]
	v_pk_fma_f32 v[210:211], v[126:127], v[116:117], v[210:211] op_sel:[1,0,0] op_sel_hi:[1,1,1]
	v_pk_fma_f32 v[22:23], v[220:221], v[102:103], v[196:197] op_sel_hi:[0,1,1] neg_lo:[1,0,0] neg_hi:[1,0,0]
	v_pk_fma_f32 v[14:15], v[220:221], v[102:103], v[204:205] op_sel:[1,0,0] op_sel_hi:[1,1,1] neg_lo:[1,0,0] neg_hi:[1,0,0]
	v_pk_fma_f32 v[24:25], v[220:221], v[104:105], v[198:199] op_sel_hi:[0,1,1] neg_lo:[1,0,0] neg_hi:[1,0,0]
	v_pk_fma_f32 v[16:17], v[220:221], v[104:105], v[206:207] op_sel:[1,0,0] op_sel_hi:[1,1,1] neg_lo:[1,0,0] neg_hi:[1,0,0]
	v_pk_fma_f32 v[18:19], v[220:221], v[106:107], v[200:201] op_sel_hi:[0,1,1] neg_lo:[1,0,0] neg_hi:[1,0,0]
	v_pk_fma_f32 v[10:11], v[220:221], v[106:107], v[208:209] op_sel:[1,0,0] op_sel_hi:[1,1,1] neg_lo:[1,0,0] neg_hi:[1,0,0]
	v_pk_fma_f32 v[20:21], v[220:221], v[108:109], v[202:203] op_sel_hi:[0,1,1] neg_lo:[1,0,0] neg_hi:[1,0,0]
	v_pk_fma_f32 v[12:13], v[220:221], v[108:109], v[210:211] op_sel:[1,0,0] op_sel_hi:[1,1,1] neg_lo:[1,0,0] neg_hi:[1,0,0]
	v_pk_mul_f32 v[222:223], v[22:23], v[118:119]
	v_pk_mul_f32 v[224:225], v[14:15], v[118:119]
	v_pk_fma_f32 v[222:223], v[24:25], v[120:121], v[222:223]
	v_pk_fma_f32 v[224:225], v[16:17], v[120:121], v[224:225]
	v_pk_fma_f32 v[222:223], v[18:19], v[122:123], v[222:223]
	v_pk_fma_f32 v[224:225], v[10:11], v[122:123], v[224:225]
	v_pk_fma_f32 v[222:223], v[20:21], v[124:125], v[222:223]
	v_pk_fma_f32 v[224:225], v[12:13], v[124:125], v[224:225]
	s_waitcnt lgkmcnt(0)
	ds_read_b128 v[86:89], v84 offset:2560
	ds_read_b128 v[90:93], v84 offset:2576
	ds_read_b128 v[94:97], v84 offset:6656
	ds_read_b128 v[98:101], v84 offset:6672
	ds_read_b128 v[102:105], v84 offset:10752
	ds_read_b128 v[106:109], v84 offset:10768
	ds_read_b128 v[110:113], v84 offset:14848
	ds_read_b128 v[114:117], v84 offset:14864
	ds_read_b128 v[118:121], v84 offset:18944
	ds_read_b128 v[122:125], v84 offset:18960
	ds_read_b64 v[126:127], v85 offset:23040
	v_pk_mul_f32 v[212:213], v[22:23], v[136:137]
	v_pk_mul_f32 v[216:217], v[14:15], v[136:137]
	v_pk_mul_f32 v[196:197], v[22:23], v[128:129]
	v_pk_mul_f32 v[204:205], v[14:15], v[128:129]
	v_pk_fma_f32 v[212:213], v[24:25], v[138:139], v[212:213]
	v_pk_fma_f32 v[216:217], v[16:17], v[138:139], v[216:217]
	v_pk_mul_f32 v[198:199], v[24:25], v[130:131]
	v_pk_mul_f32 v[206:207], v[16:17], v[130:131]
	v_pk_fma_f32 v[212:213], v[18:19], v[140:141], v[212:213]
	v_pk_fma_f32 v[216:217], v[10:11], v[140:141], v[216:217]
	v_pk_mul_f32 v[200:201], v[18:19], v[132:133]
	v_pk_mul_f32 v[208:209], v[10:11], v[132:133]
	v_pk_fma_f32 v[212:213], v[20:21], v[142:143], v[212:213]
	v_pk_fma_f32 v[216:217], v[12:13], v[142:143], v[216:217]
	v_pk_mul_f32 v[202:203], v[20:21], v[134:135]
	v_pk_mul_f32 v[210:211], v[12:13], v[134:135]
	v_add_f32_e32 v226, v222, v223
	v_add_f32_e32 v227, v224, v225
	v_add_f32_e32 v220, v212, v213
	v_add_f32_e32 v221, v216, v217
	v_pk_fma_f32 v[196:197], v[168:169], v[152:153], v[196:197] op_sel_hi:[0,1,1]
	v_pk_fma_f32 v[204:205], v[168:169], v[152:153], v[204:205] op_sel:[1,0,0] op_sel_hi:[1,1,1]
	ds_write_b64 v228, v[226:227] offset:4608
	v_add_f32_dpp v220, v220, v220 quad_perm:[1,0,3,2] row_mask:0xf bank_mask:0xf bound_ctrl:1
	v_add_f32_dpp v221, v221, v221 quad_perm:[1,0,3,2] row_mask:0xf bank_mask:0xf bound_ctrl:1
	v_pk_fma_f32 v[198:199], v[168:169], v[154:155], v[198:199] op_sel_hi:[0,1,1]
	v_pk_fma_f32 v[206:207], v[168:169], v[154:155], v[206:207] op_sel:[1,0,0] op_sel_hi:[1,1,1]
	v_add_f32_dpp v220, v220, v220 quad_perm:[2,3,0,1] row_mask:0xf bank_mask:0xf bound_ctrl:1
	v_add_f32_dpp v221, v221, v221 quad_perm:[2,3,0,1] row_mask:0xf bank_mask:0xf bound_ctrl:1
	v_pk_fma_f32 v[200:201], v[168:169], v[156:157], v[200:201] op_sel_hi:[0,1,1]
	v_pk_fma_f32 v[208:209], v[168:169], v[156:157], v[208:209] op_sel:[1,0,0] op_sel_hi:[1,1,1]
	v_add_f32_dpp v220, v220, v220 row_half_mirror row_mask:0xf bank_mask:0xf bound_ctrl:1
	v_add_f32_dpp v221, v221, v221 row_half_mirror row_mask:0xf bank_mask:0xf bound_ctrl:1
	v_pk_fma_f32 v[202:203], v[168:169], v[158:159], v[202:203] op_sel_hi:[0,1,1]
	v_pk_fma_f32 v[210:211], v[168:169], v[158:159], v[210:211] op_sel:[1,0,0] op_sel_hi:[1,1,1]
	v_pk_fma_f32 v[22:23], v[220:221], v[144:145], v[196:197] op_sel_hi:[0,1,1] neg_lo:[1,0,0] neg_hi:[1,0,0]
	v_pk_fma_f32 v[14:15], v[220:221], v[144:145], v[204:205] op_sel:[1,0,0] op_sel_hi:[1,1,1] neg_lo:[1,0,0] neg_hi:[1,0,0]
	v_pk_fma_f32 v[24:25], v[220:221], v[146:147], v[198:199] op_sel_hi:[0,1,1] neg_lo:[1,0,0] neg_hi:[1,0,0]
	v_pk_fma_f32 v[16:17], v[220:221], v[146:147], v[206:207] op_sel:[1,0,0] op_sel_hi:[1,1,1] neg_lo:[1,0,0] neg_hi:[1,0,0]
	v_pk_fma_f32 v[18:19], v[220:221], v[148:149], v[200:201] op_sel_hi:[0,1,1] neg_lo:[1,0,0] neg_hi:[1,0,0]
	v_pk_fma_f32 v[10:11], v[220:221], v[148:149], v[208:209] op_sel:[1,0,0] op_sel_hi:[1,1,1] neg_lo:[1,0,0] neg_hi:[1,0,0]
	v_pk_fma_f32 v[20:21], v[220:221], v[150:151], v[202:203] op_sel_hi:[0,1,1] neg_lo:[1,0,0] neg_hi:[1,0,0]
	v_pk_fma_f32 v[12:13], v[220:221], v[150:151], v[210:211] op_sel:[1,0,0] op_sel_hi:[1,1,1] neg_lo:[1,0,0] neg_hi:[1,0,0]
	v_pk_mul_f32 v[222:223], v[22:23], v[160:161]
	v_pk_mul_f32 v[224:225], v[14:15], v[160:161]
	v_pk_fma_f32 v[222:223], v[24:25], v[162:163], v[222:223]
	v_pk_fma_f32 v[224:225], v[16:17], v[162:163], v[224:225]
	v_pk_fma_f32 v[222:223], v[18:19], v[164:165], v[222:223]
	v_pk_fma_f32 v[224:225], v[10:11], v[164:165], v[224:225]
	v_pk_fma_f32 v[222:223], v[20:21], v[166:167], v[222:223]
	v_pk_fma_f32 v[224:225], v[12:13], v[166:167], v[224:225]
	s_waitcnt lgkmcnt(0)
; __device__ __forceinline__ void scan_rows(f32x2 (&X)[8], const ScanOps& o, const f32x4 (&b)[2], const f32x4 (&kd)[2], const f32x4 (&r)[2], const bool use_v, float& yA, float& yB) {
;     f32x2 aA = X[0] * o.kk[0].xy, aB = X[4] * o.kk[0].xy;
;     aA += X[1] * o.kk[0].zw; aB += X[5] * o.kk[0].zw;
;     aA += X[2] * o.kk[1].xy; aB += X[6] * o.kk[1].xy;
;     aA += X[3] * o.kk[1].zw; aB += X[7] * o.kk[1].zw;
;     const float saA = sum8(aA.x + aA.y), saB = sum8(aB.x + aB.y);
;     const f32x2 nA = (f32x2){-saA, -saA}, nB = (f32x2){-saB, -saB}, vA = (f32x2){o.v.x, o.v.x}, vB = (f32x2){o.v.y, o.v.y};
;     f32x2 tA, tB, accA, accB;
;     tA = X[0] * o.w[0].xy; tA += nA * b[0].xy; if (use_v) tA += vA * kd[0].xy; X[0] = tA; accA = tA * r[0].xy;
;     tB = X[4] * o.w[0].xy; tB += nB * b[0].xy; if (use_v) tB += vB * kd[0].xy; X[4] = tB; accB = tB * r[0].xy;
;     tA = X[1] * o.w[0].zw; tA += nA * b[0].zw; if (use_v) tA += vA * kd[0].zw; X[1] = tA; accA += tA * r[0].zw;
;     tB = X[5] * o.w[0].zw; tB += nB * b[0].zw; if (use_v) tB += vB * kd[0].zw; X[5] = tB; accB += tB * r[0].zw;
;     tA = X[2] * o.w[1].xy; tA += nA * b[1].xy; if (use_v) tA += vA * kd[1].xy; X[2] = tA; accA += tA * r[1].xy;
;     tB = X[6] * o.w[1].xy; tB += nB * b[1].xy; if (use_v) tB += vB * kd[1].xy; X[6] = tB; accB += tB * r[1].xy;
;     tA = X[3] * o.w[1].zw; tA += nA * b[1].zw; if (use_v) tA += vA * kd[1].zw; X[3] = tA; accA += tA * r[1].zw;
;     tB = X[7] * o.w[1].zw; tB += nB * b[1].zw; if (use_v) tB += vB * kd[1].zw; X[7] = tB; accB += tB * r[1].zw;
;     yA = sum8(accA.x + accA.y); yB = sum8(accB.x + accB.y);
; __device__ void phase_scan(int c, const bf16_t* PROJ, const float* k_k, const bf16_t* Wd, const bf16_t* Bd, const float* k_a, bf16_t* Y, bf16_t* Q, float* FS, float* sm) {
;     ...
;                 for (int i = 0; i < 16; i += 2) {
;                     float yA = 0.f, yB = 0.f;
;                     scan_ld(ob, obv, i + 1, B);
;                     if (roleP) A.v = (f32x2){0.f, 0.f};
;                     scan_step1(X, A, ob + i * 64, yA, yB);
;                     *(f32x2*)(obw + i * 16 + 2 * vp) = (f32x2){yA, yB};
;                     if (i + 2 < 16) scan_ld(ob, obv, i + 2, A);
;                     if (roleP) B.v = (f32x2){0.f, 0.f};
;                     scan_step1(X, B, ob + (i + 1) * 64, yA, yB);
;                     *(f32x2*)(obw + (i + 1) * 16 + 2 * vp) = (f32x2){yA, yB};
	ds_read_b128 v[128:131], v84 offset:2816
	ds_read_b128 v[132:135], v84 offset:2832
	ds_read_b128 v[136:139], v84 offset:6912
	ds_read_b128 v[140:143], v84 offset:6928
	ds_read_b128 v[144:147], v84 offset:11008
	ds_read_b128 v[148:151], v84 offset:11024
	ds_read_b128 v[152:155], v84 offset:15104
	ds_read_b128 v[156:159], v84 offset:15120
	ds_read_b128 v[160:163], v84 offset:19200
	ds_read_b128 v[164:167], v84 offset:19216
	ds_read_b64 v[168:169], v85 offset:23296
	v_pk_mul_f32 v[212:213], v[22:23], v[94:95]
	v_pk_mul_f32 v[216:217], v[14:15], v[94:95]
	v_pk_mul_f32 v[196:197], v[22:23], v[86:87]
	v_pk_mul_f32 v[204:205], v[14:15], v[86:87]
	v_pk_fma_f32 v[212:213], v[24:25], v[96:97], v[212:213]
	v_pk_fma_f32 v[216:217], v[16:17], v[96:97], v[216:217]
	v_pk_mul_f32 v[198:199], v[24:25], v[88:89]
	v_pk_mul_f32 v[206:207], v[16:17], v[88:89]
	v_pk_fma_f32 v[212:213], v[18:19], v[98:99], v[212:213]
	v_pk_fma_f32 v[216:217], v[10:11], v[98:99], v[216:217]
	v_pk_mul_f32 v[200:201], v[18:19], v[90:91]
	v_pk_mul_f32 v[208:209], v[10:11], v[90:91]
	v_pk_fma_f32 v[212:213], v[20:21], v[100:101], v[212:213]
	v_pk_fma_f32 v[216:217], v[12:13], v[100:101], v[216:217]
	v_pk_mul_f32 v[202:203], v[20:21], v[92:93]
	v_pk_mul_f32 v[210:211], v[12:13], v[92:93]
	v_add_f32_e32 v226, v222, v223
	v_add_f32_e32 v227, v224, v225
	v_add_f32_e32 v220, v212, v213
	v_add_f32_e32 v221, v216, v217
	v_pk_fma_f32 v[196:197], v[126:127], v[110:111], v[196:197] op_sel_hi:[0,1,1]
	v_pk_fma_f32 v[204:205], v[126:127], v[110:111], v[204:205] op_sel:[1,0,0] op_sel_hi:[1,1,1]
	ds_write_b64 v228, v[226:227] offset:5184
	v_add_f32_dpp v220, v220, v220 quad_perm:[1,0,3,2] row_mask:0xf bank_mask:0xf bound_ctrl:1
	v_add_f32_dpp v221, v221, v221 quad_perm:[1,0,3,2] row_mask:0xf bank_mask:0xf bound_ctrl:1
	v_pk_fma_f32 v[198:199], v[126:127], v[112:113], v[198:199] op_sel_hi:[0,1,1]
	v_pk_fma_f32 v[206:207], v[126:127], v[112:113], v[206:207] op_sel:[1,0,0] op_sel_hi:[1,1,1]
	v_add_f32_dpp v220, v220, v220 quad_perm:[2,3,0,1] row_mask:0xf bank_mask:0xf bound_ctrl:1
	v_add_f32_dpp v221, v221, v221 quad_perm:[2,3,0,1] row_mask:0xf bank_mask:0xf bound_ctrl:1
	v_pk_fma_f32 v[200:201], v[126:127], v[114:115], v[200:201] op_sel_hi:[0,1,1]
	v_pk_fma_f32 v[208:209], v[126:127], v[114:115], v[208:209] op_sel:[1,0,0] op_sel_hi:[1,1,1]
	v_add_f32_dpp v220, v220, v220 row_half_mirror row_mask:0xf bank_mask:0xf bound_ctrl:1
	v_add_f32_dpp v221, v221, v221 row_half_mirror row_mask:0xf bank_mask:0xf bound_ctrl:1
	v_pk_fma_f32 v[202:203], v[126:127], v[116:117], v[202:203] op_sel_hi:[0,1,1]
	v_pk_fma_f32 v[210:211], v[126:127], v[116:117], v[210:211] op_sel:[1,0,0] op_sel_hi:[1,1,1]
	v_pk_fma_f32 v[22:23], v[220:221], v[102:103], v[196:197] op_sel_hi:[0,1,1] neg_lo:[1,0,0] neg_hi:[1,0,0]
	v_pk_fma_f32 v[14:15], v[220:221], v[102:103], v[204:205] op_sel:[1,0,0] op_sel_hi:[1,1,1] neg_lo:[1,0,0] neg_hi:[1,0,0]
	v_pk_fma_f32 v[24:25], v[220:221], v[104:105], v[198:199] op_sel_hi:[0,1,1] neg_lo:[1,0,0] neg_hi:[1,0,0]
	v_pk_fma_f32 v[16:17], v[220:221], v[104:105], v[206:207] op_sel:[1,0,0] op_sel_hi:[1,1,1] neg_lo:[1,0,0] neg_hi:[1,0,0]
	v_pk_fma_f32 v[18:19], v[220:221], v[106:107], v[200:201] op_sel_hi:[0,1,1] neg_lo:[1,0,0] neg_hi:[1,0,0]
	v_pk_fma_f32 v[10:11], v[220:221], v[106:107], v[208:209] op_sel:[1,0,0] op_sel_hi:[1,1,1] neg_lo:[1,0,0] neg_hi:[1,0,0]
	v_pk_fma_f32 v[20:21], v[220:221], v[108:109], v[202:203] op_sel_hi:[0,1,1] neg_lo:[1,0,0] neg_hi:[1,0,0]
	v_pk_fma_f32 v[12:13], v[220:221], v[108:109], v[210:211] op_sel:[1,0,0] op_sel_hi:[1,1,1] neg_lo:[1,0,0] neg_hi:[1,0,0]
	v_pk_mul_f32 v[222:223], v[22:23], v[118:119]
	v_pk_mul_f32 v[224:225], v[14:15], v[118:119]
	v_pk_fma_f32 v[222:223], v[24:25], v[120:121], v[222:223]
	v_pk_fma_f32 v[224:225], v[16:17], v[120:121], v[224:225]
	v_pk_fma_f32 v[222:223], v[18:19], v[122:123], v[222:223]
	v_pk_fma_f32 v[224:225], v[10:11], v[122:123], v[224:225]
	v_pk_fma_f32 v[222:223], v[20:21], v[124:125], v[222:223]
	v_pk_fma_f32 v[224:225], v[12:13], v[124:125], v[224:225]
	s_waitcnt lgkmcnt(0)
	ds_read_b128 v[86:89], v84 offset:3072
	ds_read_b128 v[90:93], v84 offset:3088
	ds_read_b128 v[94:97], v84 offset:7168
	ds_read_b128 v[98:101], v84 offset:7184
	ds_read_b128 v[102:105], v84 offset:11264
	ds_read_b128 v[106:109], v84 offset:11280
	ds_read_b128 v[110:113], v84 offset:15360
	ds_read_b128 v[114:117], v84 offset:15376
	ds_read_b128 v[118:121], v84 offset:19456
	ds_read_b128 v[122:125], v84 offset:19472
	ds_read_b64 v[126:127], v85 offset:23552
	v_pk_mul_f32 v[212:213], v[22:23], v[136:137]
	v_pk_mul_f32 v[216:217], v[14:15], v[136:137]
	v_pk_mul_f32 v[196:197], v[22:23], v[128:129]
	v_pk_mul_f32 v[204:205], v[14:15], v[128:129]
	v_pk_fma_f32 v[212:213], v[24:25], v[138:139], v[212:213]
	v_pk_fma_f32 v[216:217], v[16:17], v[138:139], v[216:217]
	v_pk_mul_f32 v[198:199], v[24:25], v[130:131]
	v_pk_mul_f32 v[206:207], v[16:17], v[130:131]
	v_pk_fma_f32 v[212:213], v[18:19], v[140:141], v[212:213]
	v_pk_fma_f32 v[216:217], v[10:11], v[140:141], v[216:217]
	v_pk_mul_f32 v[200:201], v[18:19], v[132:133]
	v_pk_mul_f32 v[208:209], v[10:11], v[132:133]
	v_pk_fma_f32 v[212:213], v[20:21], v[142:143], v[212:213]
	v_pk_fma_f32 v[216:217], v[12:13], v[142:143], v[216:217]
	v_pk_mul_f32 v[202:203], v[20:21], v[134:135]
	v_pk_mul_f32 v[210:211], v[12:13], v[134:135]
	v_add_f32_e32 v226, v222, v223
	v_add_f32_e32 v227, v224, v225
	v_add_f32_e32 v220, v212, v213
	v_add_f32_e32 v221, v216, v217
	v_pk_fma_f32 v[196:197], v[168:169], v[152:153], v[196:197] op_sel_hi:[0,1,1]
	v_pk_fma_f32 v[204:205], v[168:169], v[152:153], v[204:205] op_sel:[1,0,0] op_sel_hi:[1,1,1]
; __device__ __forceinline__ void scan_rows(f32x2 (&X)[8], const ScanOps& o, const f32x4 (&b)[2], const f32x4 (&kd)[2], const f32x4 (&r)[2], const bool use_v, float& yA, float& yB) {
;     f32x2 aA = X[0] * o.kk[0].xy, aB = X[4] * o.kk[0].xy;
;     aA += X[1] * o.kk[0].zw; aB += X[5] * o.kk[0].zw;
;     aA += X[2] * o.kk[1].xy; aB += X[6] * o.kk[1].xy;
;     aA += X[3] * o.kk[1].zw; aB += X[7] * o.kk[1].zw;
;     const float saA = sum8(aA.x + aA.y), saB = sum8(aB.x + aB.y);
;     const f32x2 nA = (f32x2){-saA, -saA}, nB = (f32x2){-saB, -saB}, vA = (f32x2){o.v.x, o.v.x}, vB = (f32x2){o.v.y, o.v.y};
;     f32x2 tA, tB, accA, accB;
;     tA = X[0] * o.w[0].xy; tA += nA * b[0].xy; if (use_v) tA += vA * kd[0].xy; X[0] = tA; accA = tA * r[0].xy;
;     tB = X[4] * o.w[0].xy; tB += nB * b[0].xy; if (use_v) tB += vB * kd[0].xy; X[4] = tB; accB = tB * r[0].xy;
;     tA = X[1] * o.w[0].zw; tA += nA * b[0].zw; if (use_v) tA += vA * kd[0].zw; X[1] = tA; accA += tA * r[0].zw;
;     tB = X[5] * o.w[0].zw; tB += nB * b[0].zw; if (use_v) tB += vB * kd[0].zw; X[5] = tB; accB += tB * r[0].zw;
;     tA = X[2] * o.w[1].xy; tA += nA * b[1].xy; if (use_v) tA += vA * kd[1].xy; X[2] = tA; accA += tA * r[1].xy;
;     tB = X[6] * o.w[1].xy; tB += nB * b[1].xy; if (use_v) tB += vB * kd[1].xy; X[6] = tB; accB += tB * r[1].xy;
;     tA = X[3] * o.w[1].zw; tA += nA * b[1].zw; if (use_v) tA += vA * kd[1].zw; X[3] = tA; accA += tA * r[1].zw;
;     tB = X[7] * o.w[1].zw; tB += nB * b[1].zw; if (use_v) tB += vB * kd[1].zw; X[7] = tB; accB += tB * r[1].zw;
;     yA = sum8(accA.x + accA.y); yB = sum8(accB.x + accB.y);
; __device__ void phase_scan(int c, const bf16_t* PROJ, const float* k_k, const bf16_t* Wd, const bf16_t* Bd, const float* k_a, bf16_t* Y, bf16_t* Q, float* FS, float* sm) {
;     ...
;                 for (int i = 0; i < 16; i += 2) {
;                     float yA = 0.f, yB = 0.f;
;                     scan_ld(ob, obv, i + 1, B);
;                     if (roleP) A.v = (f32x2){0.f, 0.f};
;                     scan_step1(X, A, ob + i * 64, yA, yB);
;                     *(f32x2*)(obw + i * 16 + 2 * vp) = (f32x2){yA, yB};
;                     if (i + 2 < 16) scan_ld(ob, obv, i + 2, A);
;                     if (roleP) B.v = (f32x2){0.f, 0.f};
;                     scan_step1(X, B, ob + (i + 1) * 64, yA, yB);
;                     *(f32x2*)(obw + (i + 1) * 16 + 2 * vp) = (f32x2){yA, yB};
	ds_write_b64 v228, v[226:227] offset:5760
	v_add_f32_dpp v220, v220, v220 quad_perm:[1,0,3,2] row_mask:0xf bank_mask:0xf bound_ctrl:1
	v_add_f32_dpp v221, v221, v221 quad_perm:[1,0,3,2] row_mask:0xf bank_mask:0xf bound_ctrl:1
	v_pk_fma_f32 v[198:199], v[168:169], v[154:155], v[198:199] op_sel_hi:[0,1,1]
	v_pk_fma_f32 v[206:207], v[168:169], v[154:155], v[206:207] op_sel:[1,0,0] op_sel_hi:[1,1,1]
	v_add_f32_dpp v220, v220, v220 quad_perm:[2,3,0,1] row_mask:0xf bank_mask:0xf bound_ctrl:1
	v_add_f32_dpp v221, v221, v221 quad_perm:[2,3,0,1] row_mask:0xf bank_mask:0xf bound_ctrl:1
	v_pk_fma_f32 v[200:201], v[168:169], v[156:157], v[200:201] op_sel_hi:[0,1,1]
	v_pk_fma_f32 v[208:209], v[168:169], v[156:157], v[208:209] op_sel:[1,0,0] op_sel_hi:[1,1,1]
	v_add_f32_dpp v220, v220, v220 row_half_mirror row_mask:0xf bank_mask:0xf bound_ctrl:1
	v_add_f32_dpp v221, v221, v221 row_half_mirror row_mask:0xf bank_mask:0xf bound_ctrl:1
	v_pk_fma_f32 v[202:203], v[168:169], v[158:159], v[202:203] op_sel_hi:[0,1,1]
	v_pk_fma_f32 v[210:211], v[168:169], v[158:159], v[210:211] op_sel:[1,0,0] op_sel_hi:[1,1,1]
	v_pk_fma_f32 v[22:23], v[220:221], v[144:145], v[196:197] op_sel_hi:[0,1,1] neg_lo:[1,0,0] neg_hi:[1,0,0]
	v_pk_fma_f32 v[14:15], v[220:221], v[144:145], v[204:205] op_sel:[1,0,0] op_sel_hi:[1,1,1] neg_lo:[1,0,0] neg_hi:[1,0,0]
	v_pk_fma_f32 v[24:25], v[220:221], v[146:147], v[198:199] op_sel_hi:[0,1,1] neg_lo:[1,0,0] neg_hi:[1,0,0]
	v_pk_fma_f32 v[16:17], v[220:221], v[146:147], v[206:207] op_sel:[1,0,0] op_sel_hi:[1,1,1] neg_lo:[1,0,0] neg_hi:[1,0,0]
	v_pk_fma_f32 v[18:19], v[220:221], v[148:149], v[200:201] op_sel_hi:[0,1,1] neg_lo:[1,0,0] neg_hi:[1,0,0]
	v_pk_fma_f32 v[10:11], v[220:221], v[148:149], v[208:209] op_sel:[1,0,0] op_sel_hi:[1,1,1] neg_lo:[1,0,0] neg_hi:[1,0,0]
	v_pk_fma_f32 v[20:21], v[220:221], v[150:151], v[202:203] op_sel_hi:[0,1,1] neg_lo:[1,0,0] neg_hi:[1,0,0]
	v_pk_fma_f32 v[12:13], v[220:221], v[150:151], v[210:211] op_sel:[1,0,0] op_sel_hi:[1,1,1] neg_lo:[1,0,0] neg_hi:[1,0,0]
	v_pk_mul_f32 v[222:223], v[22:23], v[160:161]
	v_pk_mul_f32 v[224:225], v[14:15], v[160:161]
	v_pk_fma_f32 v[222:223], v[24:25], v[162:163], v[222:223]
	v_pk_fma_f32 v[224:225], v[16:17], v[162:163], v[224:225]
	v_pk_fma_f32 v[222:223], v[18:19], v[164:165], v[222:223]
	v_pk_fma_f32 v[224:225], v[10:11], v[164:165], v[224:225]
	v_pk_fma_f32 v[222:223], v[20:21], v[166:167], v[222:223]
	v_pk_fma_f32 v[224:225], v[12:13], v[166:167], v[224:225]
	s_waitcnt lgkmcnt(0)
	ds_read_b128 v[128:131], v84 offset:3328
	ds_read_b128 v[132:135], v84 offset:3344
	ds_read_b128 v[136:139], v84 offset:7424
	ds_read_b128 v[140:143], v84 offset:7440
	ds_read_b128 v[144:147], v84 offset:11520
	ds_read_b128 v[148:151], v84 offset:11536
	ds_read_b128 v[152:155], v84 offset:15616
	ds_read_b128 v[156:159], v84 offset:15632
	ds_read_b128 v[160:163], v84 offset:19712
	ds_read_b128 v[164:167], v84 offset:19728
	ds_read_b64 v[168:169], v85 offset:23808
	v_pk_mul_f32 v[212:213], v[22:23], v[94:95]
	v_pk_mul_f32 v[216:217], v[14:15], v[94:95]
	v_pk_mul_f32 v[196:197], v[22:23], v[86:87]
	v_pk_mul_f32 v[204:205], v[14:15], v[86:87]
	v_pk_fma_f32 v[212:213], v[24:25], v[96:97], v[212:213]
	v_pk_fma_f32 v[216:217], v[16:17], v[96:97], v[216:217]
	v_pk_mul_f32 v[198:199], v[24:25], v[88:89]
	v_pk_mul_f32 v[206:207], v[16:17], v[88:89]
	v_pk_fma_f32 v[212:213], v[18:19], v[98:99], v[212:213]
	v_pk_fma_f32 v[216:217], v[10:11], v[98:99], v[216:217]
	v_pk_mul_f32 v[200:201], v[18:19], v[90:91]
	v_pk_mul_f32 v[208:209], v[10:11], v[90:91]
	v_pk_fma_f32 v[212:213], v[20:21], v[100:101], v[212:213]
	v_pk_fma_f32 v[216:217], v[12:13], v[100:101], v[216:217]
	v_pk_mul_f32 v[202:203], v[20:21], v[92:93]
	v_pk_mul_f32 v[210:211], v[12:13], v[92:93]
	v_add_f32_e32 v226, v222, v223
	v_add_f32_e32 v227, v224, v225
	v_add_f32_e32 v220, v212, v213
	v_add_f32_e32 v221, v216, v217
	v_pk_fma_f32 v[196:197], v[126:127], v[110:111], v[196:197] op_sel_hi:[0,1,1]
	v_pk_fma_f32 v[204:205], v[126:127], v[110:111], v[204:205] op_sel:[1,0,0] op_sel_hi:[1,1,1]
	ds_write_b64 v228, v[226:227] offset:6336
	v_add_f32_dpp v220, v220, v220 quad_perm:[1,0,3,2] row_mask:0xf bank_mask:0xf bound_ctrl:1
	v_add_f32_dpp v221, v221, v221 quad_perm:[1,0,3,2] row_mask:0xf bank_mask:0xf bound_ctrl:1
	v_pk_fma_f32 v[198:199], v[126:127], v[112:113], v[198:199] op_sel_hi:[0,1,1]
	v_pk_fma_f32 v[206:207], v[126:127], v[112:113], v[206:207] op_sel:[1,0,0] op_sel_hi:[1,1,1]
	v_add_f32_dpp v220, v220, v220 quad_perm:[2,3,0,1] row_mask:0xf bank_mask:0xf bound_ctrl:1
	v_add_f32_dpp v221, v221, v221 quad_perm:[2,3,0,1] row_mask:0xf bank_mask:0xf bound_ctrl:1
	v_pk_fma_f32 v[200:201], v[126:127], v[114:115], v[200:201] op_sel_hi:[0,1,1]
	v_pk_fma_f32 v[208:209], v[126:127], v[114:115], v[208:209] op_sel:[1,0,0] op_sel_hi:[1,1,1]
	v_add_f32_dpp v220, v220, v220 row_half_mirror row_mask:0xf bank_mask:0xf bound_ctrl:1
	v_add_f32_dpp v221, v221, v221 row_half_mirror row_mask:0xf bank_mask:0xf bound_ctrl:1
	v_pk_fma_f32 v[202:203], v[126:127], v[116:117], v[202:203] op_sel_hi:[0,1,1]
	v_pk_fma_f32 v[210:211], v[126:127], v[116:117], v[210:211] op_sel:[1,0,0] op_sel_hi:[1,1,1]
	v_pk_fma_f32 v[22:23], v[220:221], v[102:103], v[196:197] op_sel_hi:[0,1,1] neg_lo:[1,0,0] neg_hi:[1,0,0]
	v_pk_fma_f32 v[14:15], v[220:221], v[102:103], v[204:205] op_sel:[1,0,0] op_sel_hi:[1,1,1] neg_lo:[1,0,0] neg_hi:[1,0,0]
	v_pk_fma_f32 v[24:25], v[220:221], v[104:105], v[198:199] op_sel_hi:[0,1,1] neg_lo:[1,0,0] neg_hi:[1,0,0]
	v_pk_fma_f32 v[16:17], v[220:221], v[104:105], v[206:207] op_sel:[1,0,0] op_sel_hi:[1,1,1] neg_lo:[1,0,0] neg_hi:[1,0,0]
	v_pk_fma_f32 v[18:19], v[220:221], v[106:107], v[200:201] op_sel_hi:[0,1,1] neg_lo:[1,0,0] neg_hi:[1,0,0]
	v_pk_fma_f32 v[10:11], v[220:221], v[106:107], v[208:209] op_sel:[1,0,0] op_sel_hi:[1,1,1] neg_lo:[1,0,0] neg_hi:[1,0,0]
	v_pk_fma_f32 v[20:21], v[220:221], v[108:109], v[202:203] op_sel_hi:[0,1,1] neg_lo:[1,0,0] neg_hi:[1,0,0]
	v_pk_fma_f32 v[12:13], v[220:221], v[108:109], v[210:211] op_sel:[1,0,0] op_sel_hi:[1,1,1] neg_lo:[1,0,0] neg_hi:[1,0,0]
	v_pk_mul_f32 v[222:223], v[22:23], v[118:119]
	v_pk_mul_f32 v[224:225], v[14:15], v[118:119]
	v_pk_fma_f32 v[222:223], v[24:25], v[120:121], v[222:223]
	v_pk_fma_f32 v[224:225], v[16:17], v[120:121], v[224:225]
	v_pk_fma_f32 v[222:223], v[18:19], v[122:123], v[222:223]
	v_pk_fma_f32 v[224:225], v[10:11], v[122:123], v[224:225]
	v_pk_fma_f32 v[222:223], v[20:21], v[124:125], v[222:223]
	v_pk_fma_f32 v[224:225], v[12:13], v[124:125], v[224:225]
	s_waitcnt lgkmcnt(0)
; __device__ __forceinline__ void scan_rows(f32x2 (&X)[8], const ScanOps& o, const f32x4 (&b)[2], const f32x4 (&kd)[2], const f32x4 (&r)[2], const bool use_v, float& yA, float& yB) {
;     f32x2 aA = X[0] * o.kk[0].xy, aB = X[4] * o.kk[0].xy;
;     aA += X[1] * o.kk[0].zw; aB += X[5] * o.kk[0].zw;
;     aA += X[2] * o.kk[1].xy; aB += X[6] * o.kk[1].xy;
;     aA += X[3] * o.kk[1].zw; aB += X[7] * o.kk[1].zw;
;     const float saA = sum8(aA.x + aA.y), saB = sum8(aB.x + aB.y);
;     const f32x2 nA = (f32x2){-saA, -saA}, nB = (f32x2){-saB, -saB}, vA = (f32x2){o.v.x, o.v.x}, vB = (f32x2){o.v.y, o.v.y};
;     f32x2 tA, tB, accA, accB;
;     tA = X[0] * o.w[0].xy; tA += nA * b[0].xy; if (use_v) tA += vA * kd[0].xy; X[0] = tA; accA = tA * r[0].xy;
;     tB = X[4] * o.w[0].xy; tB += nB * b[0].xy; if (use_v) tB += vB * kd[0].xy; X[4] = tB; accB = tB * r[0].xy;
;     tA = X[1] * o.w[0].zw; tA += nA * b[0].zw; if (use_v) tA += vA * kd[0].zw; X[1] = tA; accA += tA * r[0].zw;
;     tB = X[5] * o.w[0].zw; tB += nB * b[0].zw; if (use_v) tB += vB * kd[0].zw; X[5] = tB; accB += tB * r[0].zw;
;     tA = X[2] * o.w[1].xy; tA += nA * b[1].xy; if (use_v) tA += vA * kd[1].xy; X[2] = tA; accA += tA * r[1].xy;
;     tB = X[6] * o.w[1].xy; tB += nB * b[1].xy; if (use_v) tB += vB * kd[1].xy; X[6] = tB; accB += tB * r[1].xy;
;     tA = X[3] * o.w[1].zw; tA += nA * b[1].zw; if (use_v) tA += vA * kd[1].zw; X[3] = tA; accA += tA * r[1].zw;
;     tB = X[7] * o.w[1].zw; tB += nB * b[1].zw; if (use_v) tB += vB * kd[1].zw; X[7] = tB; accB += tB * r[1].zw;
;     yA = sum8(accA.x + accA.y); yB = sum8(accB.x + accB.y);
; __device__ void phase_scan(int c, const bf16_t* PROJ, const float* k_k, const bf16_t* Wd, const bf16_t* Bd, const float* k_a, bf16_t* Y, bf16_t* Q, float* FS, float* sm) {
;     ...
;                 for (int i = 0; i < 16; i += 2) {
;                     float yA = 0.f, yB = 0.f;
;                     scan_ld(ob, obv, i + 1, B);
;                     if (roleP) A.v = (f32x2){0.f, 0.f};
;                     scan_step1(X, A, ob + i * 64, yA, yB);
;                     *(f32x2*)(obw + i * 16 + 2 * vp) = (f32x2){yA, yB};
;                     if (i + 2 < 16) scan_ld(ob, obv, i + 2, A);
;                     if (roleP) B.v = (f32x2){0.f, 0.f};
;                     scan_step1(X, B, ob + (i + 1) * 64, yA, yB);
;                     *(f32x2*)(obw + (i + 1) * 16 + 2 * vp) = (f32x2){yA, yB};
	ds_read_b128 v[86:89], v84 offset:3584
	ds_read_b128 v[90:93], v84 offset:3600
	ds_read_b128 v[94:97], v84 offset:7680
	ds_read_b128 v[98:101], v84 offset:7696
	ds_read_b128 v[102:105], v84 offset:11776
	ds_read_b128 v[106:109], v84 offset:11792
	ds_read_b128 v[110:113], v84 offset:15872
	ds_read_b128 v[114:117], v84 offset:15888
	ds_read_b128 v[118:121], v84 offset:19968
	ds_read_b128 v[122:125], v84 offset:19984
	ds_read_b64 v[126:127], v85 offset:24064
	v_pk_mul_f32 v[212:213], v[22:23], v[136:137]
	v_pk_mul_f32 v[216:217], v[14:15], v[136:137]
	v_pk_mul_f32 v[196:197], v[22:23], v[128:129]
	v_pk_mul_f32 v[204:205], v[14:15], v[128:129]
	v_pk_fma_f32 v[212:213], v[24:25], v[138:139], v[212:213]
	v_pk_fma_f32 v[216:217], v[16:17], v[138:139], v[216:217]
	v_pk_mul_f32 v[198:199], v[24:25], v[130:131]
	v_pk_mul_f32 v[206:207], v[16:17], v[130:131]
	v_pk_fma_f32 v[212:213], v[18:19], v[140:141], v[212:213]
	v_pk_fma_f32 v[216:217], v[10:11], v[140:141], v[216:217]
	v_pk_mul_f32 v[200:201], v[18:19], v[132:133]
	v_pk_mul_f32 v[208:209], v[10:11], v[132:133]
	v_pk_fma_f32 v[212:213], v[20:21], v[142:143], v[212:213]
	v_pk_fma_f32 v[216:217], v[12:13], v[142:143], v[216:217]
	v_pk_mul_f32 v[202:203], v[20:21], v[134:135]
	v_pk_mul_f32 v[210:211], v[12:13], v[134:135]
	v_add_f32_e32 v226, v222, v223
	v_add_f32_e32 v227, v224, v225
	v_add_f32_e32 v220, v212, v213
	v_add_f32_e32 v221, v216, v217
	v_pk_fma_f32 v[196:197], v[168:169], v[152:153], v[196:197] op_sel_hi:[0,1,1]
	v_pk_fma_f32 v[204:205], v[168:169], v[152:153], v[204:205] op_sel:[1,0,0] op_sel_hi:[1,1,1]
	ds_write_b64 v228, v[226:227] offset:6912
	v_add_f32_dpp v220, v220, v220 quad_perm:[1,0,3,2] row_mask:0xf bank_mask:0xf bound_ctrl:1
	v_add_f32_dpp v221, v221, v221 quad_perm:[1,0,3,2] row_mask:0xf bank_mask:0xf bound_ctrl:1
	v_pk_fma_f32 v[198:199], v[168:169], v[154:155], v[198:199] op_sel_hi:[0,1,1]
	v_pk_fma_f32 v[206:207], v[168:169], v[154:155], v[206:207] op_sel:[1,0,0] op_sel_hi:[1,1,1]
	v_add_f32_dpp v220, v220, v220 quad_perm:[2,3,0,1] row_mask:0xf bank_mask:0xf bound_ctrl:1
	v_add_f32_dpp v221, v221, v221 quad_perm:[2,3,0,1] row_mask:0xf bank_mask:0xf bound_ctrl:1
	v_pk_fma_f32 v[200:201], v[168:169], v[156:157], v[200:201] op_sel_hi:[0,1,1]
	v_pk_fma_f32 v[208:209], v[168:169], v[156:157], v[208:209] op_sel:[1,0,0] op_sel_hi:[1,1,1]
	v_add_f32_dpp v220, v220, v220 row_half_mirror row_mask:0xf bank_mask:0xf bound_ctrl:1
	v_add_f32_dpp v221, v221, v221 row_half_mirror row_mask:0xf bank_mask:0xf bound_ctrl:1
	v_pk_fma_f32 v[202:203], v[168:169], v[158:159], v[202:203] op_sel_hi:[0,1,1]
	v_pk_fma_f32 v[210:211], v[168:169], v[158:159], v[210:211] op_sel:[1,0,0] op_sel_hi:[1,1,1]
	v_pk_fma_f32 v[22:23], v[220:221], v[144:145], v[196:197] op_sel_hi:[0,1,1] neg_lo:[1,0,0] neg_hi:[1,0,0]
	v_pk_fma_f32 v[14:15], v[220:221], v[144:145], v[204:205] op_sel:[1,0,0] op_sel_hi:[1,1,1] neg_lo:[1,0,0] neg_hi:[1,0,0]
	v_pk_fma_f32 v[24:25], v[220:221], v[146:147], v[198:199] op_sel_hi:[0,1,1] neg_lo:[1,0,0] neg_hi:[1,0,0]
	v_pk_fma_f32 v[16:17], v[220:221], v[146:147], v[206:207] op_sel:[1,0,0] op_sel_hi:[1,1,1] neg_lo:[1,0,0] neg_hi:[1,0,0]
	v_pk_fma_f32 v[18:19], v[220:221], v[148:149], v[200:201] op_sel_hi:[0,1,1] neg_lo:[1,0,0] neg_hi:[1,0,0]
	v_pk_fma_f32 v[10:11], v[220:221], v[148:149], v[208:209] op_sel:[1,0,0] op_sel_hi:[1,1,1] neg_lo:[1,0,0] neg_hi:[1,0,0]
	v_pk_fma_f32 v[20:21], v[220:221], v[150:151], v[202:203] op_sel_hi:[0,1,1] neg_lo:[1,0,0] neg_hi:[1,0,0]
	v_pk_fma_f32 v[12:13], v[220:221], v[150:151], v[210:211] op_sel:[1,0,0] op_sel_hi:[1,1,1] neg_lo:[1,0,0] neg_hi:[1,0,0]
	v_pk_mul_f32 v[222:223], v[22:23], v[160:161]
	v_pk_mul_f32 v[224:225], v[14:15], v[160:161]
	v_pk_fma_f32 v[222:223], v[24:25], v[162:163], v[222:223]
	v_pk_fma_f32 v[224:225], v[16:17], v[162:163], v[224:225]
	v_pk_fma_f32 v[222:223], v[18:19], v[164:165], v[222:223]
	v_pk_fma_f32 v[224:225], v[10:11], v[164:165], v[224:225]
	v_pk_fma_f32 v[222:223], v[20:21], v[166:167], v[222:223]
	v_pk_fma_f32 v[224:225], v[12:13], v[166:167], v[224:225]
	s_waitcnt lgkmcnt(0)
	ds_read_b128 v[128:131], v84 offset:3840
	ds_read_b128 v[132:135], v84 offset:3856
	ds_read_b128 v[136:139], v84 offset:7936
	ds_read_b128 v[140:143], v84 offset:7952
	ds_read_b128 v[144:147], v84 offset:12032
	ds_read_b128 v[148:151], v84 offset:12048
	ds_read_b128 v[152:155], v84 offset:16128
	ds_read_b128 v[156:159], v84 offset:16144
	ds_read_b128 v[160:163], v84 offset:20224
	ds_read_b128 v[164:167], v84 offset:20240
	ds_read_b64 v[168:169], v85 offset:24320
	v_pk_mul_f32 v[212:213], v[22:23], v[94:95]
	v_pk_mul_f32 v[216:217], v[14:15], v[94:95]
	v_pk_mul_f32 v[196:197], v[22:23], v[86:87]
	v_pk_mul_f32 v[204:205], v[14:15], v[86:87]
	v_pk_fma_f32 v[212:213], v[24:25], v[96:97], v[212:213]
	v_pk_fma_f32 v[216:217], v[16:17], v[96:97], v[216:217]
	v_pk_mul_f32 v[198:199], v[24:25], v[88:89]
	v_pk_mul_f32 v[206:207], v[16:17], v[88:89]
	v_pk_fma_f32 v[212:213], v[18:19], v[98:99], v[212:213]
	v_pk_fma_f32 v[216:217], v[10:11], v[98:99], v[216:217]
	v_pk_mul_f32 v[200:201], v[18:19], v[90:91]
	v_pk_mul_f32 v[208:209], v[10:11], v[90:91]
	v_pk_fma_f32 v[212:213], v[20:21], v[100:101], v[212:213]
	v_pk_fma_f32 v[216:217], v[12:13], v[100:101], v[216:217]
	v_pk_mul_f32 v[202:203], v[20:21], v[92:93]
	v_pk_mul_f32 v[210:211], v[12:13], v[92:93]
	v_add_f32_e32 v226, v222, v223
	v_add_f32_e32 v227, v224, v225
	v_add_f32_e32 v220, v212, v213
	v_add_f32_e32 v221, v216, v217
	v_pk_fma_f32 v[196:197], v[126:127], v[110:111], v[196:197] op_sel_hi:[0,1,1]
	v_pk_fma_f32 v[204:205], v[126:127], v[110:111], v[204:205] op_sel:[1,0,0] op_sel_hi:[1,1,1]
; __device__ __forceinline__ void scan_rows(f32x2 (&X)[8], const ScanOps& o, const f32x4 (&b)[2], const f32x4 (&kd)[2], const f32x4 (&r)[2], const bool use_v, float& yA, float& yB) {
;     f32x2 aA = X[0] * o.kk[0].xy, aB = X[4] * o.kk[0].xy;
;     aA += X[1] * o.kk[0].zw; aB += X[5] * o.kk[0].zw;
;     aA += X[2] * o.kk[1].xy; aB += X[6] * o.kk[1].xy;
;     aA += X[3] * o.kk[1].zw; aB += X[7] * o.kk[1].zw;
;     const float saA = sum8(aA.x + aA.y), saB = sum8(aB.x + aB.y);
;     const f32x2 nA = (f32x2){-saA, -saA}, nB = (f32x2){-saB, -saB}, vA = (f32x2){o.v.x, o.v.x}, vB = (f32x2){o.v.y, o.v.y};
;     f32x2 tA, tB, accA, accB;
;     tA = X[0] * o.w[0].xy; tA += nA * b[0].xy; if (use_v) tA += vA * kd[0].xy; X[0] = tA; accA = tA * r[0].xy;
;     tB = X[4] * o.w[0].xy; tB += nB * b[0].xy; if (use_v) tB += vB * kd[0].xy; X[4] = tB; accB = tB * r[0].xy;
;     tA = X[1] * o.w[0].zw; tA += nA * b[0].zw; if (use_v) tA += vA * kd[0].zw; X[1] = tA; accA += tA * r[0].zw;
;     tB = X[5] * o.w[0].zw; tB += nB * b[0].zw; if (use_v) tB += vB * kd[0].zw; X[5] = tB; accB += tB * r[0].zw;
;     tA = X[2] * o.w[1].xy; tA += nA * b[1].xy; if (use_v) tA += vA * kd[1].xy; X[2] = tA; accA += tA * r[1].xy;
;     tB = X[6] * o.w[1].xy; tB += nB * b[1].xy; if (use_v) tB += vB * kd[1].xy; X[6] = tB; accB += tB * r[1].xy;
;     tA = X[3] * o.w[1].zw; tA += nA * b[1].zw; if (use_v) tA += vA * kd[1].zw; X[3] = tA; accA += tA * r[1].zw;
;     tB = X[7] * o.w[1].zw; tB += nB * b[1].zw; if (use_v) tB += vB * kd[1].zw; X[7] = tB; accB += tB * r[1].zw;
;     yA = sum8(accA.x + accA.y); yB = sum8(accB.x + accB.y);
; __device__ void phase_scan(int c, const bf16_t* PROJ, const float* k_k, const bf16_t* Wd, const bf16_t* Bd, const float* k_a, bf16_t* Y, bf16_t* Q, float* FS, float* sm) {
;     ...
;                 for (int i = 0; i < 16; i += 2) {
;                     float yA = 0.f, yB = 0.f;
;                     scan_ld(ob, obv, i + 1, B);
;                     if (roleP) A.v = (f32x2){0.f, 0.f};
;                     scan_step1(X, A, ob + i * 64, yA, yB);
;                     *(f32x2*)(obw + i * 16 + 2 * vp) = (f32x2){yA, yB};
;                     if (i + 2 < 16) scan_ld(ob, obv, i + 2, A);
;                     if (roleP) B.v = (f32x2){0.f, 0.f};
;                     scan_step1(X, B, ob + (i + 1) * 64, yA, yB);
;                     *(f32x2*)(obw + (i + 1) * 16 + 2 * vp) = (f32x2){yA, yB};
	ds_write_b64 v228, v[226:227] offset:7488
	v_add_f32_dpp v220, v220, v220 quad_perm:[1,0,3,2] row_mask:0xf bank_mask:0xf bound_ctrl:1
	v_add_f32_dpp v221, v221, v221 quad_perm:[1,0,3,2] row_mask:0xf bank_mask:0xf bound_ctrl:1
	v_pk_fma_f32 v[198:199], v[126:127], v[112:113], v[198:199] op_sel_hi:[0,1,1]
	v_pk_fma_f32 v[206:207], v[126:127], v[112:113], v[206:207] op_sel:[1,0,0] op_sel_hi:[1,1,1]
	v_add_f32_dpp v220, v220, v220 quad_perm:[2,3,0,1] row_mask:0xf bank_mask:0xf bound_ctrl:1
	v_add_f32_dpp v221, v221, v221 quad_perm:[2,3,0,1] row_mask:0xf bank_mask:0xf bound_ctrl:1
	v_pk_fma_f32 v[200:201], v[126:127], v[114:115], v[200:201] op_sel_hi:[0,1,1]
	v_pk_fma_f32 v[208:209], v[126:127], v[114:115], v[208:209] op_sel:[1,0,0] op_sel_hi:[1,1,1]
	v_add_f32_dpp v220, v220, v220 row_half_mirror row_mask:0xf bank_mask:0xf bound_ctrl:1
	v_add_f32_dpp v221, v221, v221 row_half_mirror row_mask:0xf bank_mask:0xf bound_ctrl:1
	v_pk_fma_f32 v[202:203], v[126:127], v[116:117], v[202:203] op_sel_hi:[0,1,1]
	v_pk_fma_f32 v[210:211], v[126:127], v[116:117], v[210:211] op_sel:[1,0,0] op_sel_hi:[1,1,1]
	v_pk_fma_f32 v[22:23], v[220:221], v[102:103], v[196:197] op_sel_hi:[0,1,1] neg_lo:[1,0,0] neg_hi:[1,0,0]
	v_pk_fma_f32 v[14:15], v[220:221], v[102:103], v[204:205] op_sel:[1,0,0] op_sel_hi:[1,1,1] neg_lo:[1,0,0] neg_hi:[1,0,0]
	v_pk_fma_f32 v[24:25], v[220:221], v[104:105], v[198:199] op_sel_hi:[0,1,1] neg_lo:[1,0,0] neg_hi:[1,0,0]
	v_pk_fma_f32 v[16:17], v[220:221], v[104:105], v[206:207] op_sel:[1,0,0] op_sel_hi:[1,1,1] neg_lo:[1,0,0] neg_hi:[1,0,0]
	v_pk_fma_f32 v[18:19], v[220:221], v[106:107], v[200:201] op_sel_hi:[0,1,1] neg_lo:[1,0,0] neg_hi:[1,0,0]
	v_pk_fma_f32 v[10:11], v[220:221], v[106:107], v[208:209] op_sel:[1,0,0] op_sel_hi:[1,1,1] neg_lo:[1,0,0] neg_hi:[1,0,0]
	v_pk_fma_f32 v[20:21], v[220:221], v[108:109], v[202:203] op_sel_hi:[0,1,1] neg_lo:[1,0,0] neg_hi:[1,0,0]
	v_pk_fma_f32 v[12:13], v[220:221], v[108:109], v[210:211] op_sel:[1,0,0] op_sel_hi:[1,1,1] neg_lo:[1,0,0] neg_hi:[1,0,0]
	v_pk_mul_f32 v[222:223], v[22:23], v[118:119]
	v_pk_mul_f32 v[224:225], v[14:15], v[118:119]
	v_pk_fma_f32 v[222:223], v[24:25], v[120:121], v[222:223]
	v_pk_fma_f32 v[224:225], v[16:17], v[120:121], v[224:225]
	v_pk_fma_f32 v[222:223], v[18:19], v[122:123], v[222:223]
	v_pk_fma_f32 v[224:225], v[10:11], v[122:123], v[224:225]
	v_pk_fma_f32 v[222:223], v[20:21], v[124:125], v[222:223]
	v_pk_fma_f32 v[224:225], v[12:13], v[124:125], v[224:225]
	s_waitcnt lgkmcnt(0)
	v_pk_mul_f32 v[212:213], v[22:23], v[136:137]
	v_pk_mul_f32 v[216:217], v[14:15], v[136:137]
	v_pk_mul_f32 v[196:197], v[22:23], v[128:129]
	v_pk_mul_f32 v[204:205], v[14:15], v[128:129]
	v_pk_fma_f32 v[212:213], v[24:25], v[138:139], v[212:213]
	v_pk_fma_f32 v[216:217], v[16:17], v[138:139], v[216:217]
	v_pk_mul_f32 v[198:199], v[24:25], v[130:131]
	v_pk_mul_f32 v[206:207], v[16:17], v[130:131]
	v_pk_fma_f32 v[212:213], v[18:19], v[140:141], v[212:213]
	v_pk_fma_f32 v[216:217], v[10:11], v[140:141], v[216:217]
	v_pk_mul_f32 v[200:201], v[18:19], v[132:133]
	v_pk_mul_f32 v[208:209], v[10:11], v[132:133]
	v_pk_fma_f32 v[212:213], v[20:21], v[142:143], v[212:213]
	v_pk_fma_f32 v[216:217], v[12:13], v[142:143], v[216:217]
	v_pk_mul_f32 v[202:203], v[20:21], v[134:135]
	v_pk_mul_f32 v[210:211], v[12:13], v[134:135]
	v_add_f32_e32 v226, v222, v223
	v_add_f32_e32 v227, v224, v225
	v_add_f32_e32 v220, v212, v213
	v_add_f32_e32 v221, v216, v217
	v_pk_fma_f32 v[196:197], v[168:169], v[152:153], v[196:197] op_sel_hi:[0,1,1]
	v_pk_fma_f32 v[204:205], v[168:169], v[152:153], v[204:205] op_sel:[1,0,0] op_sel_hi:[1,1,1]
	ds_write_b64 v228, v[226:227] offset:8064
	v_add_f32_dpp v220, v220, v220 quad_perm:[1,0,3,2] row_mask:0xf bank_mask:0xf bound_ctrl:1
	v_add_f32_dpp v221, v221, v221 quad_perm:[1,0,3,2] row_mask:0xf bank_mask:0xf bound_ctrl:1
	v_pk_fma_f32 v[198:199], v[168:169], v[154:155], v[198:199] op_sel_hi:[0,1,1]
	v_pk_fma_f32 v[206:207], v[168:169], v[154:155], v[206:207] op_sel:[1,0,0] op_sel_hi:[1,1,1]
	v_add_f32_dpp v220, v220, v220 quad_perm:[2,3,0,1] row_mask:0xf bank_mask:0xf bound_ctrl:1
	v_add_f32_dpp v221, v221, v221 quad_perm:[2,3,0,1] row_mask:0xf bank_mask:0xf bound_ctrl:1
	v_pk_fma_f32 v[200:201], v[168:169], v[156:157], v[200:201] op_sel_hi:[0,1,1]
	v_pk_fma_f32 v[208:209], v[168:169], v[156:157], v[208:209] op_sel:[1,0,0] op_sel_hi:[1,1,1]
	v_add_f32_dpp v220, v220, v220 row_half_mirror row_mask:0xf bank_mask:0xf bound_ctrl:1
	v_add_f32_dpp v221, v221, v221 row_half_mirror row_mask:0xf bank_mask:0xf bound_ctrl:1
	v_pk_fma_f32 v[202:203], v[168:169], v[158:159], v[202:203] op_sel_hi:[0,1,1]
	v_pk_fma_f32 v[210:211], v[168:169], v[158:159], v[210:211] op_sel:[1,0,0] op_sel_hi:[1,1,1]
	v_pk_fma_f32 v[22:23], v[220:221], v[144:145], v[196:197] op_sel_hi:[0,1,1] neg_lo:[1,0,0] neg_hi:[1,0,0]
	v_pk_fma_f32 v[14:15], v[220:221], v[144:145], v[204:205] op_sel:[1,0,0] op_sel_hi:[1,1,1] neg_lo:[1,0,0] neg_hi:[1,0,0]
	v_pk_fma_f32 v[24:25], v[220:221], v[146:147], v[198:199] op_sel_hi:[0,1,1] neg_lo:[1,0,0] neg_hi:[1,0,0]
	v_pk_fma_f32 v[16:17], v[220:221], v[146:147], v[206:207] op_sel:[1,0,0] op_sel_hi:[1,1,1] neg_lo:[1,0,0] neg_hi:[1,0,0]
	v_pk_fma_f32 v[18:19], v[220:221], v[148:149], v[200:201] op_sel_hi:[0,1,1] neg_lo:[1,0,0] neg_hi:[1,0,0]
	v_pk_fma_f32 v[10:11], v[220:221], v[148:149], v[208:209] op_sel:[1,0,0] op_sel_hi:[1,1,1] neg_lo:[1,0,0] neg_hi:[1,0,0]
	v_pk_fma_f32 v[20:21], v[220:221], v[150:151], v[202:203] op_sel_hi:[0,1,1] neg_lo:[1,0,0] neg_hi:[1,0,0]
	v_pk_fma_f32 v[12:13], v[220:221], v[150:151], v[210:211] op_sel:[1,0,0] op_sel_hi:[1,1,1] neg_lo:[1,0,0] neg_hi:[1,0,0]
	v_pk_mul_f32 v[222:223], v[22:23], v[160:161]
	v_pk_mul_f32 v[224:225], v[14:15], v[160:161]
	v_pk_fma_f32 v[222:223], v[24:25], v[162:163], v[222:223]
	v_pk_fma_f32 v[224:225], v[16:17], v[162:163], v[224:225]
	v_pk_fma_f32 v[222:223], v[18:19], v[164:165], v[222:223]
	v_pk_fma_f32 v[224:225], v[10:11], v[164:165], v[224:225]
	v_pk_fma_f32 v[222:223], v[20:21], v[166:167], v[222:223]
	v_pk_fma_f32 v[224:225], v[12:13], v[166:167], v[224:225]
	v_add_f32_e32 v226, v222, v223
	v_add_f32_e32 v227, v224, v225
	ds_write_b64 v228, v[226:227] offset:8640
	s_branch .Lscan_body_end
; __device__ __forceinline__ void scan_rows(f32x2 (&X)[8], const ScanOps& o, const f32x4 (&b)[2], const f32x4 (&kd)[2], const f32x4 (&r)[2], const bool use_v, float& yA, float& yB) {
;     f32x2 aA = X[0] * o.kk[0].xy, aB = X[4] * o.kk[0].xy;
;     aA += X[1] * o.kk[0].zw; aB += X[5] * o.kk[0].zw;
;     aA += X[2] * o.kk[1].xy; aB += X[6] * o.kk[1].xy;
;     aA += X[3] * o.kk[1].zw; aB += X[7] * o.kk[1].zw;
;     const float saA = sum8(aA.x + aA.y), saB = sum8(aB.x + aB.y);
;     const f32x2 nA = (f32x2){-saA, -saA}, nB = (f32x2){-saB, -saB}, vA = (f32x2){o.v.x, o.v.x}, vB = (f32x2){o.v.y, o.v.y};
;     f32x2 tA, tB, accA, accB;
;     tA = X[0] * o.w[0].xy; tA += nA * b[0].xy; if (use_v) tA += vA * kd[0].xy; X[0] = tA; accA = tA * r[0].xy;
;     tB = X[4] * o.w[0].xy; tB += nB * b[0].xy; if (use_v) tB += vB * kd[0].xy; X[4] = tB; accB = tB * r[0].xy;
;     tA = X[1] * o.w[0].zw; tA += nA * b[0].zw; if (use_v) tA += vA * kd[0].zw; X[1] = tA; accA += tA * r[0].zw;
;     tB = X[5] * o.w[0].zw; tB += nB * b[0].zw; if (use_v) tB += vB * kd[0].zw; X[5] = tB; accB += tB * r[0].zw;
;     tA = X[2] * o.w[1].xy; tA += nA * b[1].xy; if (use_v) tA += vA * kd[1].xy; X[2] = tA; accA += tA * r[1].xy;
;     tB = X[6] * o.w[1].xy; tB += nB * b[1].xy; if (use_v) tB += vB * kd[1].xy; X[6] = tB; accB += tB * r[1].xy;
; __device__ void phase_scan(int c, const bf16_t* PROJ, const float* k_k, const bf16_t* Wd, const bf16_t* Bd, const float* k_a, bf16_t* Y, bf16_t* Q, float* FS, float* sm) {
;     ...
;             if (act) {
;                 const float* ob = opb + (ci & 1) * 6144 + q * 8;
;                 const float* obv = opb + (ci & 1) * 6144 + 5120 + wq * 16 + 2 * vp;
;                 ScanOps A, B;
;                 scan_ld(ob, obv, 0, A);
; #pragma unroll
;                 for (int i = 0; i < 16; i += 2) {
;                     float yA = 0.f, yB = 0.f;
;                     scan_ld(ob, obv, i + 1, B);
;                     if (roleP) A.v = (f32x2){0.f, 0.f};
;                     scan_step1(X, A, ob + i * 64, yA, yB);
;                     *(f32x2*)(obw + i * 16 + 2 * vp) = (f32x2){yA, yB};
;                     if (i + 2 < 16) scan_ld(ob, obv, i + 2, A);
;                     if (roleP) B.v = (f32x2){0.f, 0.f};
;                     scan_step1(X, B, ob + (i + 1) * 64, yA, yB);
.Lscan_p_body:
	s_setprio 1
	s_waitcnt lgkmcnt(0)
	ds_read_b128 v[128:131], v84 offset:256
	ds_read_b128 v[132:135], v84 offset:272
	ds_read_b128 v[136:139], v84 offset:4352
	ds_read_b128 v[140:143], v84 offset:4368
	ds_read_b128 v[144:147], v84 offset:8448
	ds_read_b128 v[148:151], v84 offset:8464
	ds_read_b128 v[160:163], v84 offset:16640
	ds_read_b128 v[164:167], v84 offset:16656
	v_pk_mul_f32 v[212:213], v[22:23], v[94:95]
	v_pk_mul_f32 v[216:217], v[14:15], v[94:95]
	v_pk_mul_f32 v[196:197], v[22:23], v[86:87]
	v_pk_mul_f32 v[204:205], v[14:15], v[86:87]
	v_pk_fma_f32 v[212:213], v[24:25], v[96:97], v[212:213]
	v_pk_fma_f32 v[216:217], v[16:17], v[96:97], v[216:217]
	v_pk_mul_f32 v[198:199], v[24:25], v[88:89]
	v_pk_mul_f32 v[206:207], v[16:17], v[88:89]
	v_pk_fma_f32 v[212:213], v[18:19], v[98:99], v[212:213]
	v_pk_fma_f32 v[216:217], v[10:11], v[98:99], v[216:217]
	v_pk_fma_f32 v[212:213], v[20:21], v[100:101], v[212:213]
	v_pk_fma_f32 v[216:217], v[12:13], v[100:101], v[216:217]
	v_add_f32_e32 v220, v212, v213
	v_add_f32_e32 v221, v216, v217
	v_pk_mul_f32 v[200:201], v[18:19], v[90:91]
	v_pk_mul_f32 v[208:209], v[10:11], v[90:91]
	v_add_f32_dpp v220, v220, v220 quad_perm:[1,0,3,2] row_mask:0xf bank_mask:0xf bound_ctrl:1
	v_add_f32_dpp v221, v221, v221 quad_perm:[1,0,3,2] row_mask:0xf bank_mask:0xf bound_ctrl:1
	v_pk_mul_f32 v[202:203], v[20:21], v[92:93]
	v_pk_mul_f32 v[210:211], v[12:13], v[92:93]
	v_add_f32_dpp v220, v220, v220 quad_perm:[2,3,0,1] row_mask:0xf bank_mask:0xf bound_ctrl:1
	v_add_f32_dpp v221, v221, v221 quad_perm:[2,3,0,1] row_mask:0xf bank_mask:0xf bound_ctrl:1
	s_nop 0
	v_add_f32_dpp v220, v220, v220 row_half_mirror row_mask:0xf bank_mask:0xf bound_ctrl:1
	v_add_f32_dpp v221, v221, v221 row_half_mirror row_mask:0xf bank_mask:0xf bound_ctrl:1
	s_nop 0
	v_pk_fma_f32 v[22:23], v[220:221], v[102:103], v[196:197] op_sel_hi:[0,1,1] neg_lo:[1,0,0] neg_hi:[1,0,0]
	v_pk_fma_f32 v[14:15], v[220:221], v[102:103], v[204:205] op_sel:[1,0,0] op_sel_hi:[1,1,1] neg_lo:[1,0,0] neg_hi:[1,0,0]
	v_pk_fma_f32 v[24:25], v[220:221], v[104:105], v[198:199] op_sel_hi:[0,1,1] neg_lo:[1,0,0] neg_hi:[1,0,0]
	v_pk_fma_f32 v[16:17], v[220:221], v[104:105], v[206:207] op_sel:[1,0,0] op_sel_hi:[1,1,1] neg_lo:[1,0,0] neg_hi:[1,0,0]
	v_pk_fma_f32 v[18:19], v[220:221], v[106:107], v[200:201] op_sel_hi:[0,1,1] neg_lo:[1,0,0] neg_hi:[1,0,0]
	v_pk_fma_f32 v[10:11], v[220:221], v[106:107], v[208:209] op_sel:[1,0,0] op_sel_hi:[1,1,1] neg_lo:[1,0,0] neg_hi:[1,0,0]
	v_pk_fma_f32 v[20:21], v[220:221], v[108:109], v[202:203] op_sel_hi:[0,1,1] neg_lo:[1,0,0] neg_hi:[1,0,0]
	v_pk_fma_f32 v[12:13], v[220:221], v[108:109], v[210:211] op_sel:[1,0,0] op_sel_hi:[1,1,1] neg_lo:[1,0,0] neg_hi:[1,0,0]
	v_pk_mul_f32 v[222:223], v[22:23], v[118:119]
	v_pk_mul_f32 v[224:225], v[14:15], v[118:119]
	v_pk_fma_f32 v[222:223], v[24:25], v[120:121], v[222:223]
	v_pk_fma_f32 v[224:225], v[16:17], v[120:121], v[224:225]
	v_pk_fma_f32 v[222:223], v[18:19], v[122:123], v[222:223]
	v_pk_fma_f32 v[224:225], v[10:11], v[122:123], v[224:225]
	v_pk_fma_f32 v[222:223], v[20:21], v[124:125], v[222:223]
	v_pk_fma_f32 v[224:225], v[12:13], v[124:125], v[224:225]
	s_waitcnt lgkmcnt(0)
	ds_read_b128 v[86:89], v84 offset:512
	ds_read_b128 v[90:93], v84 offset:528
	ds_read_b128 v[94:97], v84 offset:4608
	ds_read_b128 v[98:101], v84 offset:4624
	ds_read_b128 v[102:105], v84 offset:8704
	ds_read_b128 v[106:109], v84 offset:8720
	ds_read_b128 v[118:121], v84 offset:16896
	ds_read_b128 v[122:125], v84 offset:16912
	v_pk_mul_f32 v[212:213], v[22:23], v[136:137]
	v_pk_mul_f32 v[216:217], v[14:15], v[136:137]
	v_pk_mul_f32 v[196:197], v[22:23], v[128:129]
	v_pk_mul_f32 v[204:205], v[14:15], v[128:129]
	v_pk_fma_f32 v[212:213], v[24:25], v[138:139], v[212:213]
	v_pk_fma_f32 v[216:217], v[16:17], v[138:139], v[216:217]
	v_pk_mul_f32 v[198:199], v[24:25], v[130:131]
	v_pk_mul_f32 v[206:207], v[16:17], v[130:131]
	v_pk_fma_f32 v[212:213], v[18:19], v[140:141], v[212:213]
	v_pk_fma_f32 v[216:217], v[10:11], v[140:141], v[216:217]
	v_pk_fma_f32 v[212:213], v[20:21], v[142:143], v[212:213]
	v_pk_fma_f32 v[216:217], v[12:13], v[142:143], v[216:217]
	v_add_f32_e32 v226, v222, v223
	v_add_f32_e32 v227, v224, v225
	v_add_f32_e32 v220, v212, v213
	v_add_f32_e32 v221, v216, v217
	v_pk_mul_f32 v[200:201], v[18:19], v[132:133]
	v_pk_mul_f32 v[208:209], v[10:11], v[132:133]
	ds_write_b64 v228, v[226:227]
	v_add_f32_dpp v220, v220, v220 quad_perm:[1,0,3,2] row_mask:0xf bank_mask:0xf bound_ctrl:1
	v_add_f32_dpp v221, v221, v221 quad_perm:[1,0,3,2] row_mask:0xf bank_mask:0xf bound_ctrl:1
	v_pk_mul_f32 v[202:203], v[20:21], v[134:135]
	v_pk_mul_f32 v[210:211], v[12:13], v[134:135]
	v_add_f32_dpp v220, v220, v220 quad_perm:[2,3,0,1] row_mask:0xf bank_mask:0xf bound_ctrl:1
	v_add_f32_dpp v221, v221, v221 quad_perm:[2,3,0,1] row_mask:0xf bank_mask:0xf bound_ctrl:1
	s_nop 0
	v_add_f32_dpp v220, v220, v220 row_half_mirror row_mask:0xf bank_mask:0xf bound_ctrl:1
	v_add_f32_dpp v221, v221, v221 row_half_mirror row_mask:0xf bank_mask:0xf bound_ctrl:1
	s_nop 0
	v_pk_fma_f32 v[22:23], v[220:221], v[144:145], v[196:197] op_sel_hi:[0,1,1] neg_lo:[1,0,0] neg_hi:[1,0,0]
	v_pk_fma_f32 v[14:15], v[220:221], v[144:145], v[204:205] op_sel:[1,0,0] op_sel_hi:[1,1,1] neg_lo:[1,0,0] neg_hi:[1,0,0]
	v_pk_fma_f32 v[24:25], v[220:221], v[146:147], v[198:199] op_sel_hi:[0,1,1] neg_lo:[1,0,0] neg_hi:[1,0,0]
	v_pk_fma_f32 v[16:17], v[220:221], v[146:147], v[206:207] op_sel:[1,0,0] op_sel_hi:[1,1,1] neg_lo:[1,0,0] neg_hi:[1,0,0]
	v_pk_fma_f32 v[18:19], v[220:221], v[148:149], v[200:201] op_sel_hi:[0,1,1] neg_lo:[1,0,0] neg_hi:[1,0,0]
	v_pk_fma_f32 v[10:11], v[220:221], v[148:149], v[208:209] op_sel:[1,0,0] op_sel_hi:[1,1,1] neg_lo:[1,0,0] neg_hi:[1,0,0]
	v_pk_fma_f32 v[20:21], v[220:221], v[150:151], v[202:203] op_sel_hi:[0,1,1] neg_lo:[1,0,0] neg_hi:[1,0,0]
	v_pk_fma_f32 v[12:13], v[220:221], v[150:151], v[210:211] op_sel:[1,0,0] op_sel_hi:[1,1,1] neg_lo:[1,0,0] neg_hi:[1,0,0]
	v_pk_mul_f32 v[222:223], v[22:23], v[160:161]
	v_pk_mul_f32 v[224:225], v[14:15], v[160:161]
	v_pk_fma_f32 v[222:223], v[24:25], v[162:163], v[222:223]
	v_pk_fma_f32 v[224:225], v[16:17], v[162:163], v[224:225]
	v_pk_fma_f32 v[222:223], v[18:19], v[164:165], v[222:223]
	v_pk_fma_f32 v[224:225], v[10:11], v[164:165], v[224:225]
	v_pk_fma_f32 v[222:223], v[20:21], v[166:167], v[222:223]
	v_pk_fma_f32 v[224:225], v[12:13], v[166:167], v[224:225]
	s_waitcnt lgkmcnt(0)
; __device__ __forceinline__ void scan_rows(f32x2 (&X)[8], const ScanOps& o, const f32x4 (&b)[2], const f32x4 (&kd)[2], const f32x4 (&r)[2], const bool use_v, float& yA, float& yB) {
;     f32x2 aA = X[0] * o.kk[0].xy, aB = X[4] * o.kk[0].xy;
;     aA += X[1] * o.kk[0].zw; aB += X[5] * o.kk[0].zw;
;     aA += X[2] * o.kk[1].xy; aB += X[6] * o.kk[1].xy;
;     aA += X[3] * o.kk[1].zw; aB += X[7] * o.kk[1].zw;
;     const float saA = sum8(aA.x + aA.y), saB = sum8(aB.x + aB.y);
;     const f32x2 nA = (f32x2){-saA, -saA}, nB = (f32x2){-saB, -saB}, vA = (f32x2){o.v.x, o.v.x}, vB = (f32x2){o.v.y, o.v.y};
;     f32x2 tA, tB, accA, accB;
;     tA = X[0] * o.w[0].xy; tA += nA * b[0].xy; if (use_v) tA += vA * kd[0].xy; X[0] = tA; accA = tA * r[0].xy;
;     tB = X[4] * o.w[0].xy; tB += nB * b[0].xy; if (use_v) tB += vB * kd[0].xy; X[4] = tB; accB = tB * r[0].xy;
;     tA = X[1] * o.w[0].zw; tA += nA * b[0].zw; if (use_v) tA += vA * kd[0].zw; X[1] = tA; accA += tA * r[0].zw;
;     tB = X[5] * o.w[0].zw; tB += nB * b[0].zw; if (use_v) tB += vB * kd[0].zw; X[5] = tB; accB += tB * r[0].zw;
;     tA = X[2] * o.w[1].xy; tA += nA * b[1].xy; if (use_v) tA += vA * kd[1].xy; X[2] = tA; accA += tA * r[1].xy;
;     tB = X[6] * o.w[1].xy; tB += nB * b[1].xy; if (use_v) tB += vB * kd[1].xy; X[6] = tB; accB += tB * r[1].xy;
;     tA = X[3] * o.w[1].zw; tA += nA * b[1].zw; if (use_v) tA += vA * kd[1].zw; X[3] = tA; accA += tA * r[1].zw;
;     tB = X[7] * o.w[1].zw; tB += nB * b[1].zw; if (use_v) tB += vB * kd[1].zw; X[7] = tB; accB += tB * r[1].zw;
; __device__ void phase_scan(int c, const bf16_t* PROJ, const float* k_k, const bf16_t* Wd, const bf16_t* Bd, const float* k_a, bf16_t* Y, bf16_t* Q, float* FS, float* sm) {
;     ...
;                 for (int i = 0; i < 16; i += 2) {
;                     float yA = 0.f, yB = 0.f;
;                     scan_ld(ob, obv, i + 1, B);
;                     if (roleP) A.v = (f32x2){0.f, 0.f};
;                     scan_step1(X, A, ob + i * 64, yA, yB);
;                     *(f32x2*)(obw + i * 16 + 2 * vp) = (f32x2){yA, yB};
;                     if (i + 2 < 16) scan_ld(ob, obv, i + 2, A);
;                     if (roleP) B.v = (f32x2){0.f, 0.f};
;                     scan_step1(X, B, ob + (i + 1) * 64, yA, yB);
;                     *(f32x2*)(obw + (i + 1) * 16 + 2 * vp) = (f32x2){yA, yB};
;                 }
	ds_read_b128 v[128:131], v84 offset:768
	ds_read_b128 v[132:135], v84 offset:784
	ds_read_b128 v[136:139], v84 offset:4864
	ds_read_b128 v[140:143], v84 offset:4880
	ds_read_b128 v[144:147], v84 offset:8960
	ds_read_b128 v[148:151], v84 offset:8976
	ds_read_b128 v[160:163], v84 offset:17152
	ds_read_b128 v[164:167], v84 offset:17168
	v_pk_mul_f32 v[212:213], v[22:23], v[94:95]
	v_pk_mul_f32 v[216:217], v[14:15], v[94:95]
	v_pk_mul_f32 v[196:197], v[22:23], v[86:87]
	v_pk_mul_f32 v[204:205], v[14:15], v[86:87]
	v_pk_fma_f32 v[212:213], v[24:25], v[96:97], v[212:213]
	v_pk_fma_f32 v[216:217], v[16:17], v[96:97], v[216:217]
	v_pk_mul_f32 v[198:199], v[24:25], v[88:89]
	v_pk_mul_f32 v[206:207], v[16:17], v[88:89]
	v_pk_fma_f32 v[212:213], v[18:19], v[98:99], v[212:213]
	v_pk_fma_f32 v[216:217], v[10:11], v[98:99], v[216:217]
	v_pk_fma_f32 v[212:213], v[20:21], v[100:101], v[212:213]
	v_pk_fma_f32 v[216:217], v[12:13], v[100:101], v[216:217]
	v_add_f32_e32 v226, v222, v223
	v_add_f32_e32 v227, v224, v225
	v_add_f32_e32 v220, v212, v213
	v_add_f32_e32 v221, v216, v217
	v_pk_mul_f32 v[200:201], v[18:19], v[90:91]
	v_pk_mul_f32 v[208:209], v[10:11], v[90:91]
	ds_write_b64 v228, v[226:227] offset:576
	v_add_f32_dpp v220, v220, v220 quad_perm:[1,0,3,2] row_mask:0xf bank_mask:0xf bound_ctrl:1
	v_add_f32_dpp v221, v221, v221 quad_perm:[1,0,3,2] row_mask:0xf bank_mask:0xf bound_ctrl:1
	v_pk_mul_f32 v[202:203], v[20:21], v[92:93]
	v_pk_mul_f32 v[210:211], v[12:13], v[92:93]
	v_add_f32_dpp v220, v220, v220 quad_perm:[2,3,0,1] row_mask:0xf bank_mask:0xf bound_ctrl:1
	v_add_f32_dpp v221, v221, v221 quad_perm:[2,3,0,1] row_mask:0xf bank_mask:0xf bound_ctrl:1
	s_nop 0
	v_add_f32_dpp v220, v220, v220 row_half_mirror row_mask:0xf bank_mask:0xf bound_ctrl:1
	v_add_f32_dpp v221, v221, v221 row_half_mirror row_mask:0xf bank_mask:0xf bound_ctrl:1
	s_nop 0
	v_pk_fma_f32 v[22:23], v[220:221], v[102:103], v[196:197] op_sel_hi:[0,1,1] neg_lo:[1,0,0] neg_hi:[1,0,0]
	v_pk_fma_f32 v[14:15], v[220:221], v[102:103], v[204:205] op_sel:[1,0,0] op_sel_hi:[1,1,1] neg_lo:[1,0,0] neg_hi:[1,0,0]
	v_pk_fma_f32 v[24:25], v[220:221], v[104:105], v[198:199] op_sel_hi:[0,1,1] neg_lo:[1,0,0] neg_hi:[1,0,0]
	v_pk_fma_f32 v[16:17], v[220:221], v[104:105], v[206:207] op_sel:[1,0,0] op_sel_hi:[1,1,1] neg_lo:[1,0,0] neg_hi:[1,0,0]
	v_pk_fma_f32 v[18:19], v[220:221], v[106:107], v[200:201] op_sel_hi:[0,1,1] neg_lo:[1,0,0] neg_hi:[1,0,0]
	v_pk_fma_f32 v[10:11], v[220:221], v[106:107], v[208:209] op_sel:[1,0,0] op_sel_hi:[1,1,1] neg_lo:[1,0,0] neg_hi:[1,0,0]
	v_pk_fma_f32 v[20:21], v[220:221], v[108:109], v[202:203] op_sel_hi:[0,1,1] neg_lo:[1,0,0] neg_hi:[1,0,0]
	v_pk_fma_f32 v[12:13], v[220:221], v[108:109], v[210:211] op_sel:[1,0,0] op_sel_hi:[1,1,1] neg_lo:[1,0,0] neg_hi:[1,0,0]
	v_pk_mul_f32 v[222:223], v[22:23], v[118:119]
	v_pk_mul_f32 v[224:225], v[14:15], v[118:119]
	v_pk_fma_f32 v[222:223], v[24:25], v[120:121], v[222:223]
	v_pk_fma_f32 v[224:225], v[16:17], v[120:121], v[224:225]
	v_pk_fma_f32 v[222:223], v[18:19], v[122:123], v[222:223]
	v_pk_fma_f32 v[224:225], v[10:11], v[122:123], v[224:225]
	v_pk_fma_f32 v[222:223], v[20:21], v[124:125], v[222:223]
	v_pk_fma_f32 v[224:225], v[12:13], v[124:125], v[224:225]
	s_waitcnt lgkmcnt(0)
	ds_read_b128 v[86:89], v84 offset:1024
	ds_read_b128 v[90:93], v84 offset:1040
	ds_read_b128 v[94:97], v84 offset:5120
	ds_read_b128 v[98:101], v84 offset:5136
	ds_read_b128 v[102:105], v84 offset:9216
	ds_read_b128 v[106:109], v84 offset:9232
	ds_read_b128 v[118:121], v84 offset:17408
	ds_read_b128 v[122:125], v84 offset:17424
	v_pk_mul_f32 v[212:213], v[22:23], v[136:137]
	v_pk_mul_f32 v[216:217], v[14:15], v[136:137]
	v_pk_mul_f32 v[196:197], v[22:23], v[128:129]
	v_pk_mul_f32 v[204:205], v[14:15], v[128:129]
	v_pk_fma_f32 v[212:213], v[24:25], v[138:139], v[212:213]
	v_pk_fma_f32 v[216:217], v[16:17], v[138:139], v[216:217]
	v_pk_mul_f32 v[198:199], v[24:25], v[130:131]
	v_pk_mul_f32 v[206:207], v[16:17], v[130:131]
	v_pk_fma_f32 v[212:213], v[18:19], v[140:141], v[212:213]
	v_pk_fma_f32 v[216:217], v[10:11], v[140:141], v[216:217]
	v_pk_fma_f32 v[212:213], v[20:21], v[142:143], v[212:213]
	v_pk_fma_f32 v[216:217], v[12:13], v[142:143], v[216:217]
	v_add_f32_e32 v226, v222, v223
	v_add_f32_e32 v227, v224, v225
	v_add_f32_e32 v220, v212, v213
	v_add_f32_e32 v221, v216, v217
	v_pk_mul_f32 v[200:201], v[18:19], v[132:133]
	v_pk_mul_f32 v[208:209], v[10:11], v[132:133]
	ds_write_b64 v228, v[226:227] offset:1152
	v_add_f32_dpp v220, v220, v220 quad_perm:[1,0,3,2] row_mask:0xf bank_mask:0xf bound_ctrl:1
	v_add_f32_dpp v221, v221, v221 quad_perm:[1,0,3,2] row_mask:0xf bank_mask:0xf bound_ctrl:1
	v_pk_mul_f32 v[202:203], v[20:21], v[134:135]
	v_pk_mul_f32 v[210:211], v[12:13], v[134:135]
	v_add_f32_dpp v220, v220, v220 quad_perm:[2,3,0,1] row_mask:0xf bank_mask:0xf bound_ctrl:1
	v_add_f32_dpp v221, v221, v221 quad_perm:[2,3,0,1] row_mask:0xf bank_mask:0xf bound_ctrl:1
	s_nop 0
	v_add_f32_dpp v220, v220, v220 row_half_mirror row_mask:0xf bank_mask:0xf bound_ctrl:1
	v_add_f32_dpp v221, v221, v221 row_half_mirror row_mask:0xf bank_mask:0xf bound_ctrl:1
	s_nop 0
	v_pk_fma_f32 v[22:23], v[220:221], v[144:145], v[196:197] op_sel_hi:[0,1,1] neg_lo:[1,0,0] neg_hi:[1,0,0]
	v_pk_fma_f32 v[14:15], v[220:221], v[144:145], v[204:205] op_sel:[1,0,0] op_sel_hi:[1,1,1] neg_lo:[1,0,0] neg_hi:[1,0,0]
	v_pk_fma_f32 v[24:25], v[220:221], v[146:147], v[198:199] op_sel_hi:[0,1,1] neg_lo:[1,0,0] neg_hi:[1,0,0]
	v_pk_fma_f32 v[16:17], v[220:221], v[146:147], v[206:207] op_sel:[1,0,0] op_sel_hi:[1,1,1] neg_lo:[1,0,0] neg_hi:[1,0,0]
	v_pk_fma_f32 v[18:19], v[220:221], v[148:149], v[200:201] op_sel_hi:[0,1,1] neg_lo:[1,0,0] neg_hi:[1,0,0]
	v_pk_fma_f32 v[10:11], v[220:221], v[148:149], v[208:209] op_sel:[1,0,0] op_sel_hi:[1,1,1] neg_lo:[1,0,0] neg_hi:[1,0,0]
	v_pk_fma_f32 v[20:21], v[220:221], v[150:151], v[202:203] op_sel_hi:[0,1,1] neg_lo:[1,0,0] neg_hi:[1,0,0]
	v_pk_fma_f32 v[12:13], v[220:221], v[150:151], v[210:211] op_sel:[1,0,0] op_sel_hi:[1,1,1] neg_lo:[1,0,0] neg_hi:[1,0,0]
	v_pk_mul_f32 v[222:223], v[22:23], v[160:161]
	v_pk_mul_f32 v[224:225], v[14:15], v[160:161]
	v_pk_fma_f32 v[222:223], v[24:25], v[162:163], v[222:223]
	v_pk_fma_f32 v[224:225], v[16:17], v[162:163], v[224:225]
	v_pk_fma_f32 v[222:223], v[18:19], v[164:165], v[222:223]
	v_pk_fma_f32 v[224:225], v[10:11], v[164:165], v[224:225]
	v_pk_fma_f32 v[222:223], v[20:21], v[166:167], v[222:223]
	v_pk_fma_f32 v[224:225], v[12:13], v[166:167], v[224:225]
	s_waitcnt lgkmcnt(0)
; __device__ __forceinline__ void scan_rows(f32x2 (&X)[8], const ScanOps& o, const f32x4 (&b)[2], const f32x4 (&kd)[2], const f32x4 (&r)[2], const bool use_v, float& yA, float& yB) {
;     f32x2 aA = X[0] * o.kk[0].xy, aB = X[4] * o.kk[0].xy;
;     aA += X[1] * o.kk[0].zw; aB += X[5] * o.kk[0].zw;
;     aA += X[2] * o.kk[1].xy; aB += X[6] * o.kk[1].xy;
;     aA += X[3] * o.kk[1].zw; aB += X[7] * o.kk[1].zw;
;     const float saA = sum8(aA.x + aA.y), saB = sum8(aB.x + aB.y);
;     const f32x2 nA = (f32x2){-saA, -saA}, nB = (f32x2){-saB, -saB}, vA = (f32x2){o.v.x, o.v.x}, vB = (f32x2){o.v.y, o.v.y};
;     f32x2 tA, tB, accA, accB;
;     tA = X[0] * o.w[0].xy; tA += nA * b[0].xy; if (use_v) tA += vA * kd[0].xy; X[0] = tA; accA = tA * r[0].xy;
;     tB = X[4] * o.w[0].xy; tB += nB * b[0].xy; if (use_v) tB += vB * kd[0].xy; X[4] = tB; accB = tB * r[0].xy;
;     tA = X[1] * o.w[0].zw; tA += nA * b[0].zw; if (use_v) tA += vA * kd[0].zw; X[1] = tA; accA += tA * r[0].zw;
;     tB = X[5] * o.w[0].zw; tB += nB * b[0].zw; if (use_v) tB += vB * kd[0].zw; X[5] = tB; accB += tB * r[0].zw;
;     tA = X[2] * o.w[1].xy; tA += nA * b[1].xy; if (use_v) tA += vA * kd[1].xy; X[2] = tA; accA += tA * r[1].xy;
;     tB = X[6] * o.w[1].xy; tB += nB * b[1].xy; if (use_v) tB += vB * kd[1].xy; X[6] = tB; accB += tB * r[1].xy;
;     tA = X[3] * o.w[1].zw; tA += nA * b[1].zw; if (use_v) tA += vA * kd[1].zw; X[3] = tA; accA += tA * r[1].zw;
;     tB = X[7] * o.w[1].zw; tB += nB * b[1].zw; if (use_v) tB += vB * kd[1].zw; X[7] = tB; accB += tB * r[1].zw;
; __device__ void phase_scan(int c, const bf16_t* PROJ, const float* k_k, const bf16_t* Wd, const bf16_t* Bd, const float* k_a, bf16_t* Y, bf16_t* Q, float* FS, float* sm) {
;     ...
;                 for (int i = 0; i < 16; i += 2) {
;                     float yA = 0.f, yB = 0.f;
;                     scan_ld(ob, obv, i + 1, B);
;                     if (roleP) A.v = (f32x2){0.f, 0.f};
;                     scan_step1(X, A, ob + i * 64, yA, yB);
;                     *(f32x2*)(obw + i * 16 + 2 * vp) = (f32x2){yA, yB};
;                     if (i + 2 < 16) scan_ld(ob, obv, i + 2, A);
;                     if (roleP) B.v = (f32x2){0.f, 0.f};
;                     scan_step1(X, B, ob + (i + 1) * 64, yA, yB);
;                     *(f32x2*)(obw + (i + 1) * 16 + 2 * vp) = (f32x2){yA, yB};
;                 }
	ds_read_b128 v[128:131], v84 offset:1280
	ds_read_b128 v[132:135], v84 offset:1296
	ds_read_b128 v[136:139], v84 offset:5376
	ds_read_b128 v[140:143], v84 offset:5392
	ds_read_b128 v[144:147], v84 offset:9472
	ds_read_b128 v[148:151], v84 offset:9488
	ds_read_b128 v[160:163], v84 offset:17664
	ds_read_b128 v[164:167], v84 offset:17680
	v_pk_mul_f32 v[212:213], v[22:23], v[94:95]
	v_pk_mul_f32 v[216:217], v[14:15], v[94:95]
	v_pk_mul_f32 v[196:197], v[22:23], v[86:87]
	v_pk_mul_f32 v[204:205], v[14:15], v[86:87]
	v_pk_fma_f32 v[212:213], v[24:25], v[96:97], v[212:213]
	v_pk_fma_f32 v[216:217], v[16:17], v[96:97], v[216:217]
	v_pk_mul_f32 v[198:199], v[24:25], v[88:89]
	v_pk_mul_f32 v[206:207], v[16:17], v[88:89]
	v_pk_fma_f32 v[212:213], v[18:19], v[98:99], v[212:213]
	v_pk_fma_f32 v[216:217], v[10:11], v[98:99], v[216:217]
	v_pk_fma_f32 v[212:213], v[20:21], v[100:101], v[212:213]
	v_pk_fma_f32 v[216:217], v[12:13], v[100:101], v[216:217]
	v_add_f32_e32 v226, v222, v223
	v_add_f32_e32 v227, v224, v225
	v_add_f32_e32 v220, v212, v213
	v_add_f32_e32 v221, v216, v217
	v_pk_mul_f32 v[200:201], v[18:19], v[90:91]
	v_pk_mul_f32 v[208:209], v[10:11], v[90:91]
	ds_write_b64 v228, v[226:227] offset:1728
	v_add_f32_dpp v220, v220, v220 quad_perm:[1,0,3,2] row_mask:0xf bank_mask:0xf bound_ctrl:1
	v_add_f32_dpp v221, v221, v221 quad_perm:[1,0,3,2] row_mask:0xf bank_mask:0xf bound_ctrl:1
	v_pk_mul_f32 v[202:203], v[20:21], v[92:93]
	v_pk_mul_f32 v[210:211], v[12:13], v[92:93]
	v_add_f32_dpp v220, v220, v220 quad_perm:[2,3,0,1] row_mask:0xf bank_mask:0xf bound_ctrl:1
	v_add_f32_dpp v221, v221, v221 quad_perm:[2,3,0,1] row_mask:0xf bank_mask:0xf bound_ctrl:1
	s_nop 0
	v_add_f32_dpp v220, v220, v220 row_half_mirror row_mask:0xf bank_mask:0xf bound_ctrl:1
	v_add_f32_dpp v221, v221, v221 row_half_mirror row_mask:0xf bank_mask:0xf bound_ctrl:1
	s_nop 0
	v_pk_fma_f32 v[22:23], v[220:221], v[102:103], v[196:197] op_sel_hi:[0,1,1] neg_lo:[1,0,0] neg_hi:[1,0,0]
	v_pk_fma_f32 v[14:15], v[220:221], v[102:103], v[204:205] op_sel:[1,0,0] op_sel_hi:[1,1,1] neg_lo:[1,0,0] neg_hi:[1,0,0]
	v_pk_fma_f32 v[24:25], v[220:221], v[104:105], v[198:199] op_sel_hi:[0,1,1] neg_lo:[1,0,0] neg_hi:[1,0,0]
	v_pk_fma_f32 v[16:17], v[220:221], v[104:105], v[206:207] op_sel:[1,0,0] op_sel_hi:[1,1,1] neg_lo:[1,0,0] neg_hi:[1,0,0]
	v_pk_fma_f32 v[18:19], v[220:221], v[106:107], v[200:201] op_sel_hi:[0,1,1] neg_lo:[1,0,0] neg_hi:[1,0,0]
	v_pk_fma_f32 v[10:11], v[220:221], v[106:107], v[208:209] op_sel:[1,0,0] op_sel_hi:[1,1,1] neg_lo:[1,0,0] neg_hi:[1,0,0]
	v_pk_fma_f32 v[20:21], v[220:221], v[108:109], v[202:203] op_sel_hi:[0,1,1] neg_lo:[1,0,0] neg_hi:[1,0,0]
	v_pk_fma_f32 v[12:13], v[220:221], v[108:109], v[210:211] op_sel:[1,0,0] op_sel_hi:[1,1,1] neg_lo:[1,0,0] neg_hi:[1,0,0]
	v_pk_mul_f32 v[222:223], v[22:23], v[118:119]
	v_pk_mul_f32 v[224:225], v[14:15], v[118:119]
	v_pk_fma_f32 v[222:223], v[24:25], v[120:121], v[222:223]
	v_pk_fma_f32 v[224:225], v[16:17], v[120:121], v[224:225]
	v_pk_fma_f32 v[222:223], v[18:19], v[122:123], v[222:223]
	v_pk_fma_f32 v[224:225], v[10:11], v[122:123], v[224:225]
	v_pk_fma_f32 v[222:223], v[20:21], v[124:125], v[222:223]
	v_pk_fma_f32 v[224:225], v[12:13], v[124:125], v[224:225]
	s_waitcnt lgkmcnt(0)
	ds_read_b128 v[86:89], v84 offset:1536
	ds_read_b128 v[90:93], v84 offset:1552
	ds_read_b128 v[94:97], v84 offset:5632
	ds_read_b128 v[98:101], v84 offset:5648
	ds_read_b128 v[102:105], v84 offset:9728
	ds_read_b128 v[106:109], v84 offset:9744
	ds_read_b128 v[118:121], v84 offset:17920
	ds_read_b128 v[122:125], v84 offset:17936
	v_pk_mul_f32 v[212:213], v[22:23], v[136:137]
	v_pk_mul_f32 v[216:217], v[14:15], v[136:137]
	v_pk_mul_f32 v[196:197], v[22:23], v[128:129]
	v_pk_mul_f32 v[204:205], v[14:15], v[128:129]
	v_pk_fma_f32 v[212:213], v[24:25], v[138:139], v[212:213]
	v_pk_fma_f32 v[216:217], v[16:17], v[138:139], v[216:217]
	v_pk_mul_f32 v[198:199], v[24:25], v[130:131]
	v_pk_mul_f32 v[206:207], v[16:17], v[130:131]
	v_pk_fma_f32 v[212:213], v[18:19], v[140:141], v[212:213]
	v_pk_fma_f32 v[216:217], v[10:11], v[140:141], v[216:217]
	v_pk_fma_f32 v[212:213], v[20:21], v[142:143], v[212:213]
	v_pk_fma_f32 v[216:217], v[12:13], v[142:143], v[216:217]
	v_add_f32_e32 v226, v222, v223
	v_add_f32_e32 v227, v224, v225
	v_add_f32_e32 v220, v212, v213
	v_add_f32_e32 v221, v216, v217
	v_pk_mul_f32 v[200:201], v[18:19], v[132:133]
	v_pk_mul_f32 v[208:209], v[10:11], v[132:133]
	ds_write_b64 v228, v[226:227] offset:2304
	v_add_f32_dpp v220, v220, v220 quad_perm:[1,0,3,2] row_mask:0xf bank_mask:0xf bound_ctrl:1
	v_add_f32_dpp v221, v221, v221 quad_perm:[1,0,3,2] row_mask:0xf bank_mask:0xf bound_ctrl:1
	v_pk_mul_f32 v[202:203], v[20:21], v[134:135]
	v_pk_mul_f32 v[210:211], v[12:13], v[134:135]
	v_add_f32_dpp v220, v220, v220 quad_perm:[2,3,0,1] row_mask:0xf bank_mask:0xf bound_ctrl:1
	v_add_f32_dpp v221, v221, v221 quad_perm:[2,3,0,1] row_mask:0xf bank_mask:0xf bound_ctrl:1
	s_nop 0
	v_add_f32_dpp v220, v220, v220 row_half_mirror row_mask:0xf bank_mask:0xf bound_ctrl:1
	v_add_f32_dpp v221, v221, v221 row_half_mirror row_mask:0xf bank_mask:0xf bound_ctrl:1
	s_nop 0
	v_pk_fma_f32 v[22:23], v[220:221], v[144:145], v[196:197] op_sel_hi:[0,1,1] neg_lo:[1,0,0] neg_hi:[1,0,0]
	v_pk_fma_f32 v[14:15], v[220:221], v[144:145], v[204:205] op_sel:[1,0,0] op_sel_hi:[1,1,1] neg_lo:[1,0,0] neg_hi:[1,0,0]
	v_pk_fma_f32 v[24:25], v[220:221], v[146:147], v[198:199] op_sel_hi:[0,1,1] neg_lo:[1,0,0] neg_hi:[1,0,0]
	v_pk_fma_f32 v[16:17], v[220:221], v[146:147], v[206:207] op_sel:[1,0,0] op_sel_hi:[1,1,1] neg_lo:[1,0,0] neg_hi:[1,0,0]
	v_pk_fma_f32 v[18:19], v[220:221], v[148:149], v[200:201] op_sel_hi:[0,1,1] neg_lo:[1,0,0] neg_hi:[1,0,0]
	v_pk_fma_f32 v[10:11], v[220:221], v[148:149], v[208:209] op_sel:[1,0,0] op_sel_hi:[1,1,1] neg_lo:[1,0,0] neg_hi:[1,0,0]
	v_pk_fma_f32 v[20:21], v[220:221], v[150:151], v[202:203] op_sel_hi:[0,1,1] neg_lo:[1,0,0] neg_hi:[1,0,0]
	v_pk_fma_f32 v[12:13], v[220:221], v[150:151], v[210:211] op_sel:[1,0,0] op_sel_hi:[1,1,1] neg_lo:[1,0,0] neg_hi:[1,0,0]
	v_pk_mul_f32 v[222:223], v[22:23], v[160:161]
	v_pk_mul_f32 v[224:225], v[14:15], v[160:161]
	v_pk_fma_f32 v[222:223], v[24:25], v[162:163], v[222:223]
	v_pk_fma_f32 v[224:225], v[16:17], v[162:163], v[224:225]
	v_pk_fma_f32 v[222:223], v[18:19], v[164:165], v[222:223]
	v_pk_fma_f32 v[224:225], v[10:11], v[164:165], v[224:225]
	v_pk_fma_f32 v[222:223], v[20:21], v[166:167], v[222:223]
	v_pk_fma_f32 v[224:225], v[12:13], v[166:167], v[224:225]
	s_waitcnt lgkmcnt(0)
; __device__ __forceinline__ void scan_rows(f32x2 (&X)[8], const ScanOps& o, const f32x4 (&b)[2], const f32x4 (&kd)[2], const f32x4 (&r)[2], const bool use_v, float& yA, float& yB) {
;     f32x2 aA = X[0] * o.kk[0].xy, aB = X[4] * o.kk[0].xy;
;     aA += X[1] * o.kk[0].zw; aB += X[5] * o.kk[0].zw;
;     aA += X[2] * o.kk[1].xy; aB += X[6] * o.kk[1].xy;
;     aA += X[3] * o.kk[1].zw; aB += X[7] * o.kk[1].zw;
;     const float saA = sum8(aA.x + aA.y), saB = sum8(aB.x + aB.y);
;     const f32x2 nA = (f32x2){-saA, -saA}, nB = (f32x2){-saB, -saB}, vA = (f32x2){o.v.x, o.v.x}, vB = (f32x2){o.v.y, o.v.y};
;     f32x2 tA, tB, accA, accB;
;     tA = X[0] * o.w[0].xy; tA += nA * b[0].xy; if (use_v) tA += vA * kd[0].xy; X[0] = tA; accA = tA * r[0].xy;
;     tB = X[4] * o.w[0].xy; tB += nB * b[0].xy; if (use_v) tB += vB * kd[0].xy; X[4] = tB; accB = tB * r[0].xy;
;     tA = X[1] * o.w[0].zw; tA += nA * b[0].zw; if (use_v) tA += vA * kd[0].zw; X[1] = tA; accA += tA * r[0].zw;
;     tB = X[5] * o.w[0].zw; tB += nB * b[0].zw; if (use_v) tB += vB * kd[0].zw; X[5] = tB; accB += tB * r[0].zw;
;     tA = X[2] * o.w[1].xy; tA += nA * b[1].xy; if (use_v) tA += vA * kd[1].xy; X[2] = tA; accA += tA * r[1].xy;
;     tB = X[6] * o.w[1].xy; tB += nB * b[1].xy; if (use_v) tB += vB * kd[1].xy; X[6] = tB; accB += tB * r[1].xy;
;     tA = X[3] * o.w[1].zw; tA += nA * b[1].zw; if (use_v) tA += vA * kd[1].zw; X[3] = tA; accA += tA * r[1].zw;
;     tB = X[7] * o.w[1].zw; tB += nB * b[1].zw; if (use_v) tB += vB * kd[1].zw; X[7] = tB; accB += tB * r[1].zw;
; __device__ void phase_scan(int c, const bf16_t* PROJ, const float* k_k, const bf16_t* Wd, const bf16_t* Bd, const float* k_a, bf16_t* Y, bf16_t* Q, float* FS, float* sm) {
;     ...
;                 for (int i = 0; i < 16; i += 2) {
;                     float yA = 0.f, yB = 0.f;
;                     scan_ld(ob, obv, i + 1, B);
;                     if (roleP) A.v = (f32x2){0.f, 0.f};
;                     scan_step1(X, A, ob + i * 64, yA, yB);
;                     *(f32x2*)(obw + i * 16 + 2 * vp) = (f32x2){yA, yB};
;                     if (i + 2 < 16) scan_ld(ob, obv, i + 2, A);
;                     if (roleP) B.v = (f32x2){0.f, 0.f};
;                     scan_step1(X, B, ob + (i + 1) * 64, yA, yB);
;                     *(f32x2*)(obw + (i + 1) * 16 + 2 * vp) = (f32x2){yA, yB};
;                 }
	ds_read_b128 v[128:131], v84 offset:1792
	ds_read_b128 v[132:135], v84 offset:1808
	ds_read_b128 v[136:139], v84 offset:5888
	ds_read_b128 v[140:143], v84 offset:5904
	ds_read_b128 v[144:147], v84 offset:9984
	ds_read_b128 v[148:151], v84 offset:10000
	ds_read_b128 v[160:163], v84 offset:18176
	ds_read_b128 v[164:167], v84 offset:18192
	v_pk_mul_f32 v[212:213], v[22:23], v[94:95]
	v_pk_mul_f32 v[216:217], v[14:15], v[94:95]
	v_pk_mul_f32 v[196:197], v[22:23], v[86:87]
	v_pk_mul_f32 v[204:205], v[14:15], v[86:87]
	v_pk_fma_f32 v[212:213], v[24:25], v[96:97], v[212:213]
	v_pk_fma_f32 v[216:217], v[16:17], v[96:97], v[216:217]
	v_pk_mul_f32 v[198:199], v[24:25], v[88:89]
	v_pk_mul_f32 v[206:207], v[16:17], v[88:89]
	v_pk_fma_f32 v[212:213], v[18:19], v[98:99], v[212:213]
	v_pk_fma_f32 v[216:217], v[10:11], v[98:99], v[216:217]
	v_pk_fma_f32 v[212:213], v[20:21], v[100:101], v[212:213]
	v_pk_fma_f32 v[216:217], v[12:13], v[100:101], v[216:217]
	v_add_f32_e32 v226, v222, v223
	v_add_f32_e32 v227, v224, v225
	v_add_f32_e32 v220, v212, v213
	v_add_f32_e32 v221, v216, v217
	v_pk_mul_f32 v[200:201], v[18:19], v[90:91]
	v_pk_mul_f32 v[208:209], v[10:11], v[90:91]
	ds_write_b64 v228, v[226:227] offset:2880
	v_add_f32_dpp v220, v220, v220 quad_perm:[1,0,3,2] row_mask:0xf bank_mask:0xf bound_ctrl:1
	v_add_f32_dpp v221, v221, v221 quad_perm:[1,0,3,2] row_mask:0xf bank_mask:0xf bound_ctrl:1
	v_pk_mul_f32 v[202:203], v[20:21], v[92:93]
	v_pk_mul_f32 v[210:211], v[12:13], v[92:93]
	v_add_f32_dpp v220, v220, v220 quad_perm:[2,3,0,1] row_mask:0xf bank_mask:0xf bound_ctrl:1
	v_add_f32_dpp v221, v221, v221 quad_perm:[2,3,0,1] row_mask:0xf bank_mask:0xf bound_ctrl:1
	s_nop 0
	v_add_f32_dpp v220, v220, v220 row_half_mirror row_mask:0xf bank_mask:0xf bound_ctrl:1
	v_add_f32_dpp v221, v221, v221 row_half_mirror row_mask:0xf bank_mask:0xf bound_ctrl:1
	s_nop 0
	v_pk_fma_f32 v[22:23], v[220:221], v[102:103], v[196:197] op_sel_hi:[0,1,1] neg_lo:[1,0,0] neg_hi:[1,0,0]
	v_pk_fma_f32 v[14:15], v[220:221], v[102:103], v[204:205] op_sel:[1,0,0] op_sel_hi:[1,1,1] neg_lo:[1,0,0] neg_hi:[1,0,0]
	v_pk_fma_f32 v[24:25], v[220:221], v[104:105], v[198:199] op_sel_hi:[0,1,1] neg_lo:[1,0,0] neg_hi:[1,0,0]
	v_pk_fma_f32 v[16:17], v[220:221], v[104:105], v[206:207] op_sel:[1,0,0] op_sel_hi:[1,1,1] neg_lo:[1,0,0] neg_hi:[1,0,0]
	v_pk_fma_f32 v[18:19], v[220:221], v[106:107], v[200:201] op_sel_hi:[0,1,1] neg_lo:[1,0,0] neg_hi:[1,0,0]
	v_pk_fma_f32 v[10:11], v[220:221], v[106:107], v[208:209] op_sel:[1,0,0] op_sel_hi:[1,1,1] neg_lo:[1,0,0] neg_hi:[1,0,0]
	v_pk_fma_f32 v[20:21], v[220:221], v[108:109], v[202:203] op_sel_hi:[0,1,1] neg_lo:[1,0,0] neg_hi:[1,0,0]
	v_pk_fma_f32 v[12:13], v[220:221], v[108:109], v[210:211] op_sel:[1,0,0] op_sel_hi:[1,1,1] neg_lo:[1,0,0] neg_hi:[1,0,0]
	v_pk_mul_f32 v[222:223], v[22:23], v[118:119]
	v_pk_mul_f32 v[224:225], v[14:15], v[118:119]
	v_pk_fma_f32 v[222:223], v[24:25], v[120:121], v[222:223]
	v_pk_fma_f32 v[224:225], v[16:17], v[120:121], v[224:225]
	v_pk_fma_f32 v[222:223], v[18:19], v[122:123], v[222:223]
	v_pk_fma_f32 v[224:225], v[10:11], v[122:123], v[224:225]
	v_pk_fma_f32 v[222:223], v[20:21], v[124:125], v[222:223]
	v_pk_fma_f32 v[224:225], v[12:13], v[124:125], v[224:225]
	s_waitcnt lgkmcnt(0)
	ds_read_b128 v[86:89], v84 offset:2048
	ds_read_b128 v[90:93], v84 offset:2064
	ds_read_b128 v[94:97], v84 offset:6144
	ds_read_b128 v[98:101], v84 offset:6160
	ds_read_b128 v[102:105], v84 offset:10240
	ds_read_b128 v[106:109], v84 offset:10256
	ds_read_b128 v[118:121], v84 offset:18432
	ds_read_b128 v[122:125], v84 offset:18448
	v_pk_mul_f32 v[212:213], v[22:23], v[136:137]
	v_pk_mul_f32 v[216:217], v[14:15], v[136:137]
	v_pk_mul_f32 v[196:197], v[22:23], v[128:129]
	v_pk_mul_f32 v[204:205], v[14:15], v[128:129]
	v_pk_fma_f32 v[212:213], v[24:25], v[138:139], v[212:213]
	v_pk_fma_f32 v[216:217], v[16:17], v[138:139], v[216:217]
	v_pk_mul_f32 v[198:199], v[24:25], v[130:131]
	v_pk_mul_f32 v[206:207], v[16:17], v[130:131]
	v_pk_fma_f32 v[212:213], v[18:19], v[140:141], v[212:213]
	v_pk_fma_f32 v[216:217], v[10:11], v[140:141], v[216:217]
	v_pk_fma_f32 v[212:213], v[20:21], v[142:143], v[212:213]
	v_pk_fma_f32 v[216:217], v[12:13], v[142:143], v[216:217]
	v_add_f32_e32 v226, v222, v223
	v_add_f32_e32 v227, v224, v225
	v_add_f32_e32 v220, v212, v213
	v_add_f32_e32 v221, v216, v217
	v_pk_mul_f32 v[200:201], v[18:19], v[132:133]
	v_pk_mul_f32 v[208:209], v[10:11], v[132:133]
	ds_write_b64 v228, v[226:227] offset:3456
	v_add_f32_dpp v220, v220, v220 quad_perm:[1,0,3,2] row_mask:0xf bank_mask:0xf bound_ctrl:1
	v_add_f32_dpp v221, v221, v221 quad_perm:[1,0,3,2] row_mask:0xf bank_mask:0xf bound_ctrl:1
	v_pk_mul_f32 v[202:203], v[20:21], v[134:135]
	v_pk_mul_f32 v[210:211], v[12:13], v[134:135]
	v_add_f32_dpp v220, v220, v220 quad_perm:[2,3,0,1] row_mask:0xf bank_mask:0xf bound_ctrl:1
	v_add_f32_dpp v221, v221, v221 quad_perm:[2,3,0,1] row_mask:0xf bank_mask:0xf bound_ctrl:1
	s_nop 0
	v_add_f32_dpp v220, v220, v220 row_half_mirror row_mask:0xf bank_mask:0xf bound_ctrl:1
	v_add_f32_dpp v221, v221, v221 row_half_mirror row_mask:0xf bank_mask:0xf bound_ctrl:1
	s_nop 0
	v_pk_fma_f32 v[22:23], v[220:221], v[144:145], v[196:197] op_sel_hi:[0,1,1] neg_lo:[1,0,0] neg_hi:[1,0,0]
	v_pk_fma_f32 v[14:15], v[220:221], v[144:145], v[204:205] op_sel:[1,0,0] op_sel_hi:[1,1,1] neg_lo:[1,0,0] neg_hi:[1,0,0]
	v_pk_fma_f32 v[24:25], v[220:221], v[146:147], v[198:199] op_sel_hi:[0,1,1] neg_lo:[1,0,0] neg_hi:[1,0,0]
	v_pk_fma_f32 v[16:17], v[220:221], v[146:147], v[206:207] op_sel:[1,0,0] op_sel_hi:[1,1,1] neg_lo:[1,0,0] neg_hi:[1,0,0]
	v_pk_fma_f32 v[18:19], v[220:221], v[148:149], v[200:201] op_sel_hi:[0,1,1] neg_lo:[1,0,0] neg_hi:[1,0,0]
	v_pk_fma_f32 v[10:11], v[220:221], v[148:149], v[208:209] op_sel:[1,0,0] op_sel_hi:[1,1,1] neg_lo:[1,0,0] neg_hi:[1,0,0]
	v_pk_fma_f32 v[20:21], v[220:221], v[150:151], v[202:203] op_sel_hi:[0,1,1] neg_lo:[1,0,0] neg_hi:[1,0,0]
	v_pk_fma_f32 v[12:13], v[220:221], v[150:151], v[210:211] op_sel:[1,0,0] op_sel_hi:[1,1,1] neg_lo:[1,0,0] neg_hi:[1,0,0]
	v_pk_mul_f32 v[222:223], v[22:23], v[160:161]
	v_pk_mul_f32 v[224:225], v[14:15], v[160:161]
	v_pk_fma_f32 v[222:223], v[24:25], v[162:163], v[222:223]
	v_pk_fma_f32 v[224:225], v[16:17], v[162:163], v[224:225]
	v_pk_fma_f32 v[222:223], v[18:19], v[164:165], v[222:223]
	v_pk_fma_f32 v[224:225], v[10:11], v[164:165], v[224:225]
	v_pk_fma_f32 v[222:223], v[20:21], v[166:167], v[222:223]
	v_pk_fma_f32 v[224:225], v[12:13], v[166:167], v[224:225]
	s_waitcnt lgkmcnt(0)
; __device__ __forceinline__ void scan_rows(f32x2 (&X)[8], const ScanOps& o, const f32x4 (&b)[2], const f32x4 (&kd)[2], const f32x4 (&r)[2], const bool use_v, float& yA, float& yB) {
;     f32x2 aA = X[0] * o.kk[0].xy, aB = X[4] * o.kk[0].xy;
;     aA += X[1] * o.kk[0].zw; aB += X[5] * o.kk[0].zw;
;     aA += X[2] * o.kk[1].xy; aB += X[6] * o.kk[1].xy;
;     aA += X[3] * o.kk[1].zw; aB += X[7] * o.kk[1].zw;
;     const float saA = sum8(aA.x + aA.y), saB = sum8(aB.x + aB.y);
;     const f32x2 nA = (f32x2){-saA, -saA}, nB = (f32x2){-saB, -saB}, vA = (f32x2){o.v.x, o.v.x}, vB = (f32x2){o.v.y, o.v.y};
;     f32x2 tA, tB, accA, accB;
;     tA = X[0] * o.w[0].xy; tA += nA * b[0].xy; if (use_v) tA += vA * kd[0].xy; X[0] = tA; accA = tA * r[0].xy;
;     tB = X[4] * o.w[0].xy; tB += nB * b[0].xy; if (use_v) tB += vB * kd[0].xy; X[4] = tB; accB = tB * r[0].xy;
;     tA = X[1] * o.w[0].zw; tA += nA * b[0].zw; if (use_v) tA += vA * kd[0].zw; X[1] = tA; accA += tA * r[0].zw;
;     tB = X[5] * o.w[0].zw; tB += nB * b[0].zw; if (use_v) tB += vB * kd[0].zw; X[5] = tB; accB += tB * r[0].zw;
;     tA = X[2] * o.w[1].xy; tA += nA * b[1].xy; if (use_v) tA += vA * kd[1].xy; X[2] = tA; accA += tA * r[1].xy;
;     tB = X[6] * o.w[1].xy; tB += nB * b[1].xy; if (use_v) tB += vB * kd[1].xy; X[6] = tB; accB += tB * r[1].xy;
;     tA = X[3] * o.w[1].zw; tA += nA * b[1].zw; if (use_v) tA += vA * kd[1].zw; X[3] = tA; accA += tA * r[1].zw;
;     tB = X[7] * o.w[1].zw; tB += nB * b[1].zw; if (use_v) tB += vB * kd[1].zw; X[7] = tB; accB += tB * r[1].zw;
; __device__ void phase_scan(int c, const bf16_t* PROJ, const float* k_k, const bf16_t* Wd, const bf16_t* Bd, const float* k_a, bf16_t* Y, bf16_t* Q, float* FS, float* sm) {
;     ...
;                 for (int i = 0; i < 16; i += 2) {
;                     float yA = 0.f, yB = 0.f;
;                     scan_ld(ob, obv, i + 1, B);
;                     if (roleP) A.v = (f32x2){0.f, 0.f};
;                     scan_step1(X, A, ob + i * 64, yA, yB);
;                     *(f32x2*)(obw + i * 16 + 2 * vp) = (f32x2){yA, yB};
;                     if (i + 2 < 16) scan_ld(ob, obv, i + 2, A);
;                     if (roleP) B.v = (f32x2){0.f, 0.f};
;                     scan_step1(X, B, ob + (i + 1) * 64, yA, yB);
;                     *(f32x2*)(obw + (i + 1) * 16 + 2 * vp) = (f32x2){yA, yB};
;                 }
	ds_read_b128 v[128:131], v84 offset:2304
	ds_read_b128 v[132:135], v84 offset:2320
	ds_read_b128 v[136:139], v84 offset:6400
	ds_read_b128 v[140:143], v84 offset:6416
	ds_read_b128 v[144:147], v84 offset:10496
	ds_read_b128 v[148:151], v84 offset:10512
	ds_read_b128 v[160:163], v84 offset:18688
	ds_read_b128 v[164:167], v84 offset:18704
	v_pk_mul_f32 v[212:213], v[22:23], v[94:95]
	v_pk_mul_f32 v[216:217], v[14:15], v[94:95]
	v_pk_mul_f32 v[196:197], v[22:23], v[86:87]
	v_pk_mul_f32 v[204:205], v[14:15], v[86:87]
	v_pk_fma_f32 v[212:213], v[24:25], v[96:97], v[212:213]
	v_pk_fma_f32 v[216:217], v[16:17], v[96:97], v[216:217]
	v_pk_mul_f32 v[198:199], v[24:25], v[88:89]
	v_pk_mul_f32 v[206:207], v[16:17], v[88:89]
	v_pk_fma_f32 v[212:213], v[18:19], v[98:99], v[212:213]
	v_pk_fma_f32 v[216:217], v[10:11], v[98:99], v[216:217]
	v_pk_fma_f32 v[212:213], v[20:21], v[100:101], v[212:213]
	v_pk_fma_f32 v[216:217], v[12:13], v[100:101], v[216:217]
	v_add_f32_e32 v226, v222, v223
	v_add_f32_e32 v227, v224, v225
	v_add_f32_e32 v220, v212, v213
	v_add_f32_e32 v221, v216, v217
	v_pk_mul_f32 v[200:201], v[18:19], v[90:91]
	v_pk_mul_f32 v[208:209], v[10:11], v[90:91]
	ds_write_b64 v228, v[226:227] offset:4032
	v_add_f32_dpp v220, v220, v220 quad_perm:[1,0,3,2] row_mask:0xf bank_mask:0xf bound_ctrl:1
	v_add_f32_dpp v221, v221, v221 quad_perm:[1,0,3,2] row_mask:0xf bank_mask:0xf bound_ctrl:1
	v_pk_mul_f32 v[202:203], v[20:21], v[92:93]
	v_pk_mul_f32 v[210:211], v[12:13], v[92:93]
	v_add_f32_dpp v220, v220, v220 quad_perm:[2,3,0,1] row_mask:0xf bank_mask:0xf bound_ctrl:1
	v_add_f32_dpp v221, v221, v221 quad_perm:[2,3,0,1] row_mask:0xf bank_mask:0xf bound_ctrl:1
	s_nop 0
	v_add_f32_dpp v220, v220, v220 row_half_mirror row_mask:0xf bank_mask:0xf bound_ctrl:1
	v_add_f32_dpp v221, v221, v221 row_half_mirror row_mask:0xf bank_mask:0xf bound_ctrl:1
	s_nop 0
	v_pk_fma_f32 v[22:23], v[220:221], v[102:103], v[196:197] op_sel_hi:[0,1,1] neg_lo:[1,0,0] neg_hi:[1,0,0]
	v_pk_fma_f32 v[14:15], v[220:221], v[102:103], v[204:205] op_sel:[1,0,0] op_sel_hi:[1,1,1] neg_lo:[1,0,0] neg_hi:[1,0,0]
	v_pk_fma_f32 v[24:25], v[220:221], v[104:105], v[198:199] op_sel_hi:[0,1,1] neg_lo:[1,0,0] neg_hi:[1,0,0]
	v_pk_fma_f32 v[16:17], v[220:221], v[104:105], v[206:207] op_sel:[1,0,0] op_sel_hi:[1,1,1] neg_lo:[1,0,0] neg_hi:[1,0,0]
	v_pk_fma_f32 v[18:19], v[220:221], v[106:107], v[200:201] op_sel_hi:[0,1,1] neg_lo:[1,0,0] neg_hi:[1,0,0]
	v_pk_fma_f32 v[10:11], v[220:221], v[106:107], v[208:209] op_sel:[1,0,0] op_sel_hi:[1,1,1] neg_lo:[1,0,0] neg_hi:[1,0,0]
	v_pk_fma_f32 v[20:21], v[220:221], v[108:109], v[202:203] op_sel_hi:[0,1,1] neg_lo:[1,0,0] neg_hi:[1,0,0]
	v_pk_fma_f32 v[12:13], v[220:221], v[108:109], v[210:211] op_sel:[1,0,0] op_sel_hi:[1,1,1] neg_lo:[1,0,0] neg_hi:[1,0,0]
	v_pk_mul_f32 v[222:223], v[22:23], v[118:119]
	v_pk_mul_f32 v[224:225], v[14:15], v[118:119]
	v_pk_fma_f32 v[222:223], v[24:25], v[120:121], v[222:223]
	v_pk_fma_f32 v[224:225], v[16:17], v[120:121], v[224:225]
	v_pk_fma_f32 v[222:223], v[18:19], v[122:123], v[222:223]
	v_pk_fma_f32 v[224:225], v[10:11], v[122:123], v[224:225]
	v_pk_fma_f32 v[222:223], v[20:21], v[124:125], v[222:223]
	v_pk_fma_f32 v[224:225], v[12:13], v[124:125], v[224:225]
	s_waitcnt lgkmcnt(0)
	ds_read_b128 v[86:89], v84 offset:2560
	ds_read_b128 v[90:93], v84 offset:2576
	ds_read_b128 v[94:97], v84 offset:6656
	ds_read_b128 v[98:101], v84 offset:6672
	ds_read_b128 v[102:105], v84 offset:10752
	ds_read_b128 v[106:109], v84 offset:10768
	ds_read_b128 v[118:121], v84 offset:18944
	ds_read_b128 v[122:125], v84 offset:18960
	v_pk_mul_f32 v[212:213], v[22:23], v[136:137]
	v_pk_mul_f32 v[216:217], v[14:15], v[136:137]
	v_pk_mul_f32 v[196:197], v[22:23], v[128:129]
	v_pk_mul_f32 v[204:205], v[14:15], v[128:129]
	v_pk_fma_f32 v[212:213], v[24:25], v[138:139], v[212:213]
	v_pk_fma_f32 v[216:217], v[16:17], v[138:139], v[216:217]
	v_pk_mul_f32 v[198:199], v[24:25], v[130:131]
	v_pk_mul_f32 v[206:207], v[16:17], v[130:131]
	v_pk_fma_f32 v[212:213], v[18:19], v[140:141], v[212:213]
	v_pk_fma_f32 v[216:217], v[10:11], v[140:141], v[216:217]
	v_pk_fma_f32 v[212:213], v[20:21], v[142:143], v[212:213]
	v_pk_fma_f32 v[216:217], v[12:13], v[142:143], v[216:217]
	v_add_f32_e32 v226, v222, v223
	v_add_f32_e32 v227, v224, v225
	v_add_f32_e32 v220, v212, v213
	v_add_f32_e32 v221, v216, v217
	v_pk_mul_f32 v[200:201], v[18:19], v[132:133]
	v_pk_mul_f32 v[208:209], v[10:11], v[132:133]
	ds_write_b64 v228, v[226:227] offset:4608
	v_add_f32_dpp v220, v220, v220 quad_perm:[1,0,3,2] row_mask:0xf bank_mask:0xf bound_ctrl:1
	v_add_f32_dpp v221, v221, v221 quad_perm:[1,0,3,2] row_mask:0xf bank_mask:0xf bound_ctrl:1
	v_pk_mul_f32 v[202:203], v[20:21], v[134:135]
	v_pk_mul_f32 v[210:211], v[12:13], v[134:135]
	v_add_f32_dpp v220, v220, v220 quad_perm:[2,3,0,1] row_mask:0xf bank_mask:0xf bound_ctrl:1
	v_add_f32_dpp v221, v221, v221 quad_perm:[2,3,0,1] row_mask:0xf bank_mask:0xf bound_ctrl:1
	s_nop 0
	v_add_f32_dpp v220, v220, v220 row_half_mirror row_mask:0xf bank_mask:0xf bound_ctrl:1
	v_add_f32_dpp v221, v221, v221 row_half_mirror row_mask:0xf bank_mask:0xf bound_ctrl:1
	s_nop 0
	v_pk_fma_f32 v[22:23], v[220:221], v[144:145], v[196:197] op_sel_hi:[0,1,1] neg_lo:[1,0,0] neg_hi:[1,0,0]
	v_pk_fma_f32 v[14:15], v[220:221], v[144:145], v[204:205] op_sel:[1,0,0] op_sel_hi:[1,1,1] neg_lo:[1,0,0] neg_hi:[1,0,0]
	v_pk_fma_f32 v[24:25], v[220:221], v[146:147], v[198:199] op_sel_hi:[0,1,1] neg_lo:[1,0,0] neg_hi:[1,0,0]
	v_pk_fma_f32 v[16:17], v[220:221], v[146:147], v[206:207] op_sel:[1,0,0] op_sel_hi:[1,1,1] neg_lo:[1,0,0] neg_hi:[1,0,0]
	v_pk_fma_f32 v[18:19], v[220:221], v[148:149], v[200:201] op_sel_hi:[0,1,1] neg_lo:[1,0,0] neg_hi:[1,0,0]
	v_pk_fma_f32 v[10:11], v[220:221], v[148:149], v[208:209] op_sel:[1,0,0] op_sel_hi:[1,1,1] neg_lo:[1,0,0] neg_hi:[1,0,0]
	v_pk_fma_f32 v[20:21], v[220:221], v[150:151], v[202:203] op_sel_hi:[0,1,1] neg_lo:[1,0,0] neg_hi:[1,0,0]
	v_pk_fma_f32 v[12:13], v[220:221], v[150:151], v[210:211] op_sel:[1,0,0] op_sel_hi:[1,1,1] neg_lo:[1,0,0] neg_hi:[1,0,0]
	v_pk_mul_f32 v[222:223], v[22:23], v[160:161]
	v_pk_mul_f32 v[224:225], v[14:15], v[160:161]
	v_pk_fma_f32 v[222:223], v[24:25], v[162:163], v[222:223]
	v_pk_fma_f32 v[224:225], v[16:17], v[162:163], v[224:225]
	v_pk_fma_f32 v[222:223], v[18:19], v[164:165], v[222:223]
	v_pk_fma_f32 v[224:225], v[10:11], v[164:165], v[224:225]
	v_pk_fma_f32 v[222:223], v[20:21], v[166:167], v[222:223]
	v_pk_fma_f32 v[224:225], v[12:13], v[166:167], v[224:225]
	s_waitcnt lgkmcnt(0)
; __device__ __forceinline__ void scan_rows(f32x2 (&X)[8], const ScanOps& o, const f32x4 (&b)[2], const f32x4 (&kd)[2], const f32x4 (&r)[2], const bool use_v, float& yA, float& yB) {
;     f32x2 aA = X[0] * o.kk[0].xy, aB = X[4] * o.kk[0].xy;
;     aA += X[1] * o.kk[0].zw; aB += X[5] * o.kk[0].zw;
;     aA += X[2] * o.kk[1].xy; aB += X[6] * o.kk[1].xy;
;     aA += X[3] * o.kk[1].zw; aB += X[7] * o.kk[1].zw;
;     const float saA = sum8(aA.x + aA.y), saB = sum8(aB.x + aB.y);
;     const f32x2 nA = (f32x2){-saA, -saA}, nB = (f32x2){-saB, -saB}, vA = (f32x2){o.v.x, o.v.x}, vB = (f32x2){o.v.y, o.v.y};
;     f32x2 tA, tB, accA, accB;
;     tA = X[0] * o.w[0].xy; tA += nA * b[0].xy; if (use_v) tA += vA * kd[0].xy; X[0] = tA; accA = tA * r[0].xy;
;     tB = X[4] * o.w[0].xy; tB += nB * b[0].xy; if (use_v) tB += vB * kd[0].xy; X[4] = tB; accB = tB * r[0].xy;
;     tA = X[1] * o.w[0].zw; tA += nA * b[0].zw; if (use_v) tA += vA * kd[0].zw; X[1] = tA; accA += tA * r[0].zw;
;     tB = X[5] * o.w[0].zw; tB += nB * b[0].zw; if (use_v) tB += vB * kd[0].zw; X[5] = tB; accB += tB * r[0].zw;
;     tA = X[2] * o.w[1].xy; tA += nA * b[1].xy; if (use_v) tA += vA * kd[1].xy; X[2] = tA; accA += tA * r[1].xy;
;     tB = X[6] * o.w[1].xy; tB += nB * b[1].xy; if (use_v) tB += vB * kd[1].xy; X[6] = tB; accB += tB * r[1].xy;
;     tA = X[3] * o.w[1].zw; tA += nA * b[1].zw; if (use_v) tA += vA * kd[1].zw; X[3] = tA; accA += tA * r[1].zw;
;     tB = X[7] * o.w[1].zw; tB += nB * b[1].zw; if (use_v) tB += vB * kd[1].zw; X[7] = tB; accB += tB * r[1].zw;
; __device__ void phase_scan(int c, const bf16_t* PROJ, const float* k_k, const bf16_t* Wd, const bf16_t* Bd, const float* k_a, bf16_t* Y, bf16_t* Q, float* FS, float* sm) {
;     ...
;                 for (int i = 0; i < 16; i += 2) {
;                     float yA = 0.f, yB = 0.f;
;                     scan_ld(ob, obv, i + 1, B);
;                     if (roleP) A.v = (f32x2){0.f, 0.f};
;                     scan_step1(X, A, ob + i * 64, yA, yB);
;                     *(f32x2*)(obw + i * 16 + 2 * vp) = (f32x2){yA, yB};
;                     if (i + 2 < 16) scan_ld(ob, obv, i + 2, A);
;                     if (roleP) B.v = (f32x2){0.f, 0.f};
;                     scan_step1(X, B, ob + (i + 1) * 64, yA, yB);
;                     *(f32x2*)(obw + (i + 1) * 16 + 2 * vp) = (f32x2){yA, yB};
;                 }
	ds_read_b128 v[128:131], v84 offset:2816
	ds_read_b128 v[132:135], v84 offset:2832
	ds_read_b128 v[136:139], v84 offset:6912
	ds_read_b128 v[140:143], v84 offset:6928
	ds_read_b128 v[144:147], v84 offset:11008
	ds_read_b128 v[148:151], v84 offset:11024
	ds_read_b128 v[160:163], v84 offset:19200
	ds_read_b128 v[164:167], v84 offset:19216
	v_pk_mul_f32 v[212:213], v[22:23], v[94:95]
	v_pk_mul_f32 v[216:217], v[14:15], v[94:95]
	v_pk_mul_f32 v[196:197], v[22:23], v[86:87]
	v_pk_mul_f32 v[204:205], v[14:15], v[86:87]
	v_pk_fma_f32 v[212:213], v[24:25], v[96:97], v[212:213]
	v_pk_fma_f32 v[216:217], v[16:17], v[96:97], v[216:217]
	v_pk_mul_f32 v[198:199], v[24:25], v[88:89]
	v_pk_mul_f32 v[206:207], v[16:17], v[88:89]
	v_pk_fma_f32 v[212:213], v[18:19], v[98:99], v[212:213]
	v_pk_fma_f32 v[216:217], v[10:11], v[98:99], v[216:217]
	v_pk_fma_f32 v[212:213], v[20:21], v[100:101], v[212:213]
	v_pk_fma_f32 v[216:217], v[12:13], v[100:101], v[216:217]
	v_add_f32_e32 v226, v222, v223
	v_add_f32_e32 v227, v224, v225
	v_add_f32_e32 v220, v212, v213
	v_add_f32_e32 v221, v216, v217
	v_pk_mul_f32 v[200:201], v[18:19], v[90:91]
	v_pk_mul_f32 v[208:209], v[10:11], v[90:91]
	ds_write_b64 v228, v[226:227] offset:5184
	v_add_f32_dpp v220, v220, v220 quad_perm:[1,0,3,2] row_mask:0xf bank_mask:0xf bound_ctrl:1
	v_add_f32_dpp v221, v221, v221 quad_perm:[1,0,3,2] row_mask:0xf bank_mask:0xf bound_ctrl:1
	v_pk_mul_f32 v[202:203], v[20:21], v[92:93]
	v_pk_mul_f32 v[210:211], v[12:13], v[92:93]
	v_add_f32_dpp v220, v220, v220 quad_perm:[2,3,0,1] row_mask:0xf bank_mask:0xf bound_ctrl:1
	v_add_f32_dpp v221, v221, v221 quad_perm:[2,3,0,1] row_mask:0xf bank_mask:0xf bound_ctrl:1
	s_nop 0
	v_add_f32_dpp v220, v220, v220 row_half_mirror row_mask:0xf bank_mask:0xf bound_ctrl:1
	v_add_f32_dpp v221, v221, v221 row_half_mirror row_mask:0xf bank_mask:0xf bound_ctrl:1
	s_nop 0
	v_pk_fma_f32 v[22:23], v[220:221], v[102:103], v[196:197] op_sel_hi:[0,1,1] neg_lo:[1,0,0] neg_hi:[1,0,0]
	v_pk_fma_f32 v[14:15], v[220:221], v[102:103], v[204:205] op_sel:[1,0,0] op_sel_hi:[1,1,1] neg_lo:[1,0,0] neg_hi:[1,0,0]
	v_pk_fma_f32 v[24:25], v[220:221], v[104:105], v[198:199] op_sel_hi:[0,1,1] neg_lo:[1,0,0] neg_hi:[1,0,0]
	v_pk_fma_f32 v[16:17], v[220:221], v[104:105], v[206:207] op_sel:[1,0,0] op_sel_hi:[1,1,1] neg_lo:[1,0,0] neg_hi:[1,0,0]
	v_pk_fma_f32 v[18:19], v[220:221], v[106:107], v[200:201] op_sel_hi:[0,1,1] neg_lo:[1,0,0] neg_hi:[1,0,0]
	v_pk_fma_f32 v[10:11], v[220:221], v[106:107], v[208:209] op_sel:[1,0,0] op_sel_hi:[1,1,1] neg_lo:[1,0,0] neg_hi:[1,0,0]
	v_pk_fma_f32 v[20:21], v[220:221], v[108:109], v[202:203] op_sel_hi:[0,1,1] neg_lo:[1,0,0] neg_hi:[1,0,0]
	v_pk_fma_f32 v[12:13], v[220:221], v[108:109], v[210:211] op_sel:[1,0,0] op_sel_hi:[1,1,1] neg_lo:[1,0,0] neg_hi:[1,0,0]
	v_pk_mul_f32 v[222:223], v[22:23], v[118:119]
	v_pk_mul_f32 v[224:225], v[14:15], v[118:119]
	v_pk_fma_f32 v[222:223], v[24:25], v[120:121], v[222:223]
	v_pk_fma_f32 v[224:225], v[16:17], v[120:121], v[224:225]
	v_pk_fma_f32 v[222:223], v[18:19], v[122:123], v[222:223]
	v_pk_fma_f32 v[224:225], v[10:11], v[122:123], v[224:225]
	v_pk_fma_f32 v[222:223], v[20:21], v[124:125], v[222:223]
	v_pk_fma_f32 v[224:225], v[12:13], v[124:125], v[224:225]
	s_waitcnt lgkmcnt(0)
	ds_read_b128 v[86:89], v84 offset:3072
	ds_read_b128 v[90:93], v84 offset:3088
	ds_read_b128 v[94:97], v84 offset:7168
	ds_read_b128 v[98:101], v84 offset:7184
	ds_read_b128 v[102:105], v84 offset:11264
	ds_read_b128 v[106:109], v84 offset:11280
	ds_read_b128 v[118:121], v84 offset:19456
	ds_read_b128 v[122:125], v84 offset:19472
	v_pk_mul_f32 v[212:213], v[22:23], v[136:137]
	v_pk_mul_f32 v[216:217], v[14:15], v[136:137]
	v_pk_mul_f32 v[196:197], v[22:23], v[128:129]
	v_pk_mul_f32 v[204:205], v[14:15], v[128:129]
	v_pk_fma_f32 v[212:213], v[24:25], v[138:139], v[212:213]
	v_pk_fma_f32 v[216:217], v[16:17], v[138:139], v[216:217]
	v_pk_mul_f32 v[198:199], v[24:25], v[130:131]
	v_pk_mul_f32 v[206:207], v[16:17], v[130:131]
	v_pk_fma_f32 v[212:213], v[18:19], v[140:141], v[212:213]
	v_pk_fma_f32 v[216:217], v[10:11], v[140:141], v[216:217]
	v_pk_fma_f32 v[212:213], v[20:21], v[142:143], v[212:213]
	v_pk_fma_f32 v[216:217], v[12:13], v[142:143], v[216:217]
	v_add_f32_e32 v226, v222, v223
	v_add_f32_e32 v227, v224, v225
	v_add_f32_e32 v220, v212, v213
	v_add_f32_e32 v221, v216, v217
	v_pk_mul_f32 v[200:201], v[18:19], v[132:133]
	v_pk_mul_f32 v[208:209], v[10:11], v[132:133]
	ds_write_b64 v228, v[226:227] offset:5760
	v_add_f32_dpp v220, v220, v220 quad_perm:[1,0,3,2] row_mask:0xf bank_mask:0xf bound_ctrl:1
	v_add_f32_dpp v221, v221, v221 quad_perm:[1,0,3,2] row_mask:0xf bank_mask:0xf bound_ctrl:1
	v_pk_mul_f32 v[202:203], v[20:21], v[134:135]
	v_pk_mul_f32 v[210:211], v[12:13], v[134:135]
	v_add_f32_dpp v220, v220, v220 quad_perm:[2,3,0,1] row_mask:0xf bank_mask:0xf bound_ctrl:1
	v_add_f32_dpp v221, v221, v221 quad_perm:[2,3,0,1] row_mask:0xf bank_mask:0xf bound_ctrl:1
	s_nop 0
	v_add_f32_dpp v220, v220, v220 row_half_mirror row_mask:0xf bank_mask:0xf bound_ctrl:1
	v_add_f32_dpp v221, v221, v221 row_half_mirror row_mask:0xf bank_mask:0xf bound_ctrl:1
	s_nop 0
	v_pk_fma_f32 v[22:23], v[220:221], v[144:145], v[196:197] op_sel_hi:[0,1,1] neg_lo:[1,0,0] neg_hi:[1,0,0]
	v_pk_fma_f32 v[14:15], v[220:221], v[144:145], v[204:205] op_sel:[1,0,0] op_sel_hi:[1,1,1] neg_lo:[1,0,0] neg_hi:[1,0,0]
	v_pk_fma_f32 v[24:25], v[220:221], v[146:147], v[198:199] op_sel_hi:[0,1,1] neg_lo:[1,0,0] neg_hi:[1,0,0]
	v_pk_fma_f32 v[16:17], v[220:221], v[146:147], v[206:207] op_sel:[1,0,0] op_sel_hi:[1,1,1] neg_lo:[1,0,0] neg_hi:[1,0,0]
	v_pk_fma_f32 v[18:19], v[220:221], v[148:149], v[200:201] op_sel_hi:[0,1,1] neg_lo:[1,0,0] neg_hi:[1,0,0]
	v_pk_fma_f32 v[10:11], v[220:221], v[148:149], v[208:209] op_sel:[1,0,0] op_sel_hi:[1,1,1] neg_lo:[1,0,0] neg_hi:[1,0,0]
	v_pk_fma_f32 v[20:21], v[220:221], v[150:151], v[202:203] op_sel_hi:[0,1,1] neg_lo:[1,0,0] neg_hi:[1,0,0]
	v_pk_fma_f32 v[12:13], v[220:221], v[150:151], v[210:211] op_sel:[1,0,0] op_sel_hi:[1,1,1] neg_lo:[1,0,0] neg_hi:[1,0,0]
	v_pk_mul_f32 v[222:223], v[22:23], v[160:161]
	v_pk_mul_f32 v[224:225], v[14:15], v[160:161]
	v_pk_fma_f32 v[222:223], v[24:25], v[162:163], v[222:223]
	v_pk_fma_f32 v[224:225], v[16:17], v[162:163], v[224:225]
	v_pk_fma_f32 v[222:223], v[18:19], v[164:165], v[222:223]
	v_pk_fma_f32 v[224:225], v[10:11], v[164:165], v[224:225]
	v_pk_fma_f32 v[222:223], v[20:21], v[166:167], v[222:223]
	v_pk_fma_f32 v[224:225], v[12:13], v[166:167], v[224:225]
	s_waitcnt lgkmcnt(0)
; __device__ __forceinline__ void scan_rows(f32x2 (&X)[8], const ScanOps& o, const f32x4 (&b)[2], const f32x4 (&kd)[2], const f32x4 (&r)[2], const bool use_v, float& yA, float& yB) {
;     f32x2 aA = X[0] * o.kk[0].xy, aB = X[4] * o.kk[0].xy;
;     aA += X[1] * o.kk[0].zw; aB += X[5] * o.kk[0].zw;
;     aA += X[2] * o.kk[1].xy; aB += X[6] * o.kk[1].xy;
;     aA += X[3] * o.kk[1].zw; aB += X[7] * o.kk[1].zw;
;     const float saA = sum8(aA.x + aA.y), saB = sum8(aB.x + aB.y);
;     const f32x2 nA = (f32x2){-saA, -saA}, nB = (f32x2){-saB, -saB}, vA = (f32x2){o.v.x, o.v.x}, vB = (f32x2){o.v.y, o.v.y};
;     f32x2 tA, tB, accA, accB;
;     tA = X[0] * o.w[0].xy; tA += nA * b[0].xy; if (use_v) tA += vA * kd[0].xy; X[0] = tA; accA = tA * r[0].xy;
;     tB = X[4] * o.w[0].xy; tB += nB * b[0].xy; if (use_v) tB += vB * kd[0].xy; X[4] = tB; accB = tB * r[0].xy;
;     tA = X[1] * o.w[0].zw; tA += nA * b[0].zw; if (use_v) tA += vA * kd[0].zw; X[1] = tA; accA += tA * r[0].zw;
;     tB = X[5] * o.w[0].zw; tB += nB * b[0].zw; if (use_v) tB += vB * kd[0].zw; X[5] = tB; accB += tB * r[0].zw;
;     tA = X[2] * o.w[1].xy; tA += nA * b[1].xy; if (use_v) tA += vA * kd[1].xy; X[2] = tA; accA += tA * r[1].xy;
;     tB = X[6] * o.w[1].xy; tB += nB * b[1].xy; if (use_v) tB += vB * kd[1].xy; X[6] = tB; accB += tB * r[1].xy;
;     tA = X[3] * o.w[1].zw; tA += nA * b[1].zw; if (use_v) tA += vA * kd[1].zw; X[3] = tA; accA += tA * r[1].zw;
;     tB = X[7] * o.w[1].zw; tB += nB * b[1].zw; if (use_v) tB += vB * kd[1].zw; X[7] = tB; accB += tB * r[1].zw;
; __device__ void phase_scan(int c, const bf16_t* PROJ, const float* k_k, const bf16_t* Wd, const bf16_t* Bd, const float* k_a, bf16_t* Y, bf16_t* Q, float* FS, float* sm) {
;     ...
;                 for (int i = 0; i < 16; i += 2) {
;                     float yA = 0.f, yB = 0.f;
;                     scan_ld(ob, obv, i + 1, B);
;                     if (roleP) A.v = (f32x2){0.f, 0.f};
;                     scan_step1(X, A, ob + i * 64, yA, yB);
;                     *(f32x2*)(obw + i * 16 + 2 * vp) = (f32x2){yA, yB};
;                     if (i + 2 < 16) scan_ld(ob, obv, i + 2, A);
;                     if (roleP) B.v = (f32x2){0.f, 0.f};
;                     scan_step1(X, B, ob + (i + 1) * 64, yA, yB);
;                     *(f32x2*)(obw + (i + 1) * 16 + 2 * vp) = (f32x2){yA, yB};
;                 }
	ds_read_b128 v[128:131], v84 offset:3328
	ds_read_b128 v[132:135], v84 offset:3344
	ds_read_b128 v[136:139], v84 offset:7424
	ds_read_b128 v[140:143], v84 offset:7440
	ds_read_b128 v[144:147], v84 offset:11520
	ds_read_b128 v[148:151], v84 offset:11536
	ds_read_b128 v[160:163], v84 offset:19712
	ds_read_b128 v[164:167], v84 offset:19728
	v_pk_mul_f32 v[212:213], v[22:23], v[94:95]
	v_pk_mul_f32 v[216:217], v[14:15], v[94:95]
	v_pk_mul_f32 v[196:197], v[22:23], v[86:87]
	v_pk_mul_f32 v[204:205], v[14:15], v[86:87]
	v_pk_fma_f32 v[212:213], v[24:25], v[96:97], v[212:213]
	v_pk_fma_f32 v[216:217], v[16:17], v[96:97], v[216:217]
	v_pk_mul_f32 v[198:199], v[24:25], v[88:89]
	v_pk_mul_f32 v[206:207], v[16:17], v[88:89]
	v_pk_fma_f32 v[212:213], v[18:19], v[98:99], v[212:213]
	v_pk_fma_f32 v[216:217], v[10:11], v[98:99], v[216:217]
	v_pk_fma_f32 v[212:213], v[20:21], v[100:101], v[212:213]
	v_pk_fma_f32 v[216:217], v[12:13], v[100:101], v[216:217]
	v_add_f32_e32 v226, v222, v223
	v_add_f32_e32 v227, v224, v225
	v_add_f32_e32 v220, v212, v213
	v_add_f32_e32 v221, v216, v217
	v_pk_mul_f32 v[200:201], v[18:19], v[90:91]
	v_pk_mul_f32 v[208:209], v[10:11], v[90:91]
	ds_write_b64 v228, v[226:227] offset:6336
	v_add_f32_dpp v220, v220, v220 quad_perm:[1,0,3,2] row_mask:0xf bank_mask:0xf bound_ctrl:1
	v_add_f32_dpp v221, v221, v221 quad_perm:[1,0,3,2] row_mask:0xf bank_mask:0xf bound_ctrl:1
	v_pk_mul_f32 v[202:203], v[20:21], v[92:93]
	v_pk_mul_f32 v[210:211], v[12:13], v[92:93]
	v_add_f32_dpp v220, v220, v220 quad_perm:[2,3,0,1] row_mask:0xf bank_mask:0xf bound_ctrl:1
	v_add_f32_dpp v221, v221, v221 quad_perm:[2,3,0,1] row_mask:0xf bank_mask:0xf bound_ctrl:1
	s_nop 0
	v_add_f32_dpp v220, v220, v220 row_half_mirror row_mask:0xf bank_mask:0xf bound_ctrl:1
	v_add_f32_dpp v221, v221, v221 row_half_mirror row_mask:0xf bank_mask:0xf bound_ctrl:1
	s_nop 0
	v_pk_fma_f32 v[22:23], v[220:221], v[102:103], v[196:197] op_sel_hi:[0,1,1] neg_lo:[1,0,0] neg_hi:[1,0,0]
	v_pk_fma_f32 v[14:15], v[220:221], v[102:103], v[204:205] op_sel:[1,0,0] op_sel_hi:[1,1,1] neg_lo:[1,0,0] neg_hi:[1,0,0]
	v_pk_fma_f32 v[24:25], v[220:221], v[104:105], v[198:199] op_sel_hi:[0,1,1] neg_lo:[1,0,0] neg_hi:[1,0,0]
	v_pk_fma_f32 v[16:17], v[220:221], v[104:105], v[206:207] op_sel:[1,0,0] op_sel_hi:[1,1,1] neg_lo:[1,0,0] neg_hi:[1,0,0]
	v_pk_fma_f32 v[18:19], v[220:221], v[106:107], v[200:201] op_sel_hi:[0,1,1] neg_lo:[1,0,0] neg_hi:[1,0,0]
	v_pk_fma_f32 v[10:11], v[220:221], v[106:107], v[208:209] op_sel:[1,0,0] op_sel_hi:[1,1,1] neg_lo:[1,0,0] neg_hi:[1,0,0]
	v_pk_fma_f32 v[20:21], v[220:221], v[108:109], v[202:203] op_sel_hi:[0,1,1] neg_lo:[1,0,0] neg_hi:[1,0,0]
	v_pk_fma_f32 v[12:13], v[220:221], v[108:109], v[210:211] op_sel:[1,0,0] op_sel_hi:[1,1,1] neg_lo:[1,0,0] neg_hi:[1,0,0]
	v_pk_mul_f32 v[222:223], v[22:23], v[118:119]
	v_pk_mul_f32 v[224:225], v[14:15], v[118:119]
	v_pk_fma_f32 v[222:223], v[24:25], v[120:121], v[222:223]
	v_pk_fma_f32 v[224:225], v[16:17], v[120:121], v[224:225]
	v_pk_fma_f32 v[222:223], v[18:19], v[122:123], v[222:223]
	v_pk_fma_f32 v[224:225], v[10:11], v[122:123], v[224:225]
	v_pk_fma_f32 v[222:223], v[20:21], v[124:125], v[222:223]
	v_pk_fma_f32 v[224:225], v[12:13], v[124:125], v[224:225]
	s_waitcnt lgkmcnt(0)
	ds_read_b128 v[86:89], v84 offset:3584
	ds_read_b128 v[90:93], v84 offset:3600
	ds_read_b128 v[94:97], v84 offset:7680
	ds_read_b128 v[98:101], v84 offset:7696
	ds_read_b128 v[102:105], v84 offset:11776
	ds_read_b128 v[106:109], v84 offset:11792
	ds_read_b128 v[118:121], v84 offset:19968
	ds_read_b128 v[122:125], v84 offset:19984
	v_pk_mul_f32 v[212:213], v[22:23], v[136:137]
	v_pk_mul_f32 v[216:217], v[14:15], v[136:137]
	v_pk_mul_f32 v[196:197], v[22:23], v[128:129]
	v_pk_mul_f32 v[204:205], v[14:15], v[128:129]
	v_pk_fma_f32 v[212:213], v[24:25], v[138:139], v[212:213]
	v_pk_fma_f32 v[216:217], v[16:17], v[138:139], v[216:217]
	v_pk_mul_f32 v[198:199], v[24:25], v[130:131]
	v_pk_mul_f32 v[206:207], v[16:17], v[130:131]
	v_pk_fma_f32 v[212:213], v[18:19], v[140:141], v[212:213]
	v_pk_fma_f32 v[216:217], v[10:11], v[140:141], v[216:217]
	v_pk_fma_f32 v[212:213], v[20:21], v[142:143], v[212:213]
	v_pk_fma_f32 v[216:217], v[12:13], v[142:143], v[216:217]
	v_add_f32_e32 v226, v222, v223
	v_add_f32_e32 v227, v224, v225
	v_add_f32_e32 v220, v212, v213
	v_add_f32_e32 v221, v216, v217
	v_pk_mul_f32 v[200:201], v[18:19], v[132:133]
	v_pk_mul_f32 v[208:209], v[10:11], v[132:133]
	ds_write_b64 v228, v[226:227] offset:6912
	v_add_f32_dpp v220, v220, v220 quad_perm:[1,0,3,2] row_mask:0xf bank_mask:0xf bound_ctrl:1
	v_add_f32_dpp v221, v221, v221 quad_perm:[1,0,3,2] row_mask:0xf bank_mask:0xf bound_ctrl:1
	v_pk_mul_f32 v[202:203], v[20:21], v[134:135]
	v_pk_mul_f32 v[210:211], v[12:13], v[134:135]
	v_add_f32_dpp v220, v220, v220 quad_perm:[2,3,0,1] row_mask:0xf bank_mask:0xf bound_ctrl:1
	v_add_f32_dpp v221, v221, v221 quad_perm:[2,3,0,1] row_mask:0xf bank_mask:0xf bound_ctrl:1
	s_nop 0
	v_add_f32_dpp v220, v220, v220 row_half_mirror row_mask:0xf bank_mask:0xf bound_ctrl:1
	v_add_f32_dpp v221, v221, v221 row_half_mirror row_mask:0xf bank_mask:0xf bound_ctrl:1
	s_nop 0
	v_pk_fma_f32 v[22:23], v[220:221], v[144:145], v[196:197] op_sel_hi:[0,1,1] neg_lo:[1,0,0] neg_hi:[1,0,0]
	v_pk_fma_f32 v[14:15], v[220:221], v[144:145], v[204:205] op_sel:[1,0,0] op_sel_hi:[1,1,1] neg_lo:[1,0,0] neg_hi:[1,0,0]
	v_pk_fma_f32 v[24:25], v[220:221], v[146:147], v[198:199] op_sel_hi:[0,1,1] neg_lo:[1,0,0] neg_hi:[1,0,0]
	v_pk_fma_f32 v[16:17], v[220:221], v[146:147], v[206:207] op_sel:[1,0,0] op_sel_hi:[1,1,1] neg_lo:[1,0,0] neg_hi:[1,0,0]
	v_pk_fma_f32 v[18:19], v[220:221], v[148:149], v[200:201] op_sel_hi:[0,1,1] neg_lo:[1,0,0] neg_hi:[1,0,0]
	v_pk_fma_f32 v[10:11], v[220:221], v[148:149], v[208:209] op_sel:[1,0,0] op_sel_hi:[1,1,1] neg_lo:[1,0,0] neg_hi:[1,0,0]
	v_pk_fma_f32 v[20:21], v[220:221], v[150:151], v[202:203] op_sel_hi:[0,1,1] neg_lo:[1,0,0] neg_hi:[1,0,0]
	v_pk_fma_f32 v[12:13], v[220:221], v[150:151], v[210:211] op_sel:[1,0,0] op_sel_hi:[1,1,1] neg_lo:[1,0,0] neg_hi:[1,0,0]
	v_pk_mul_f32 v[222:223], v[22:23], v[160:161]
	v_pk_mul_f32 v[224:225], v[14:15], v[160:161]
	v_pk_fma_f32 v[222:223], v[24:25], v[162:163], v[222:223]
	v_pk_fma_f32 v[224:225], v[16:17], v[162:163], v[224:225]
	v_pk_fma_f32 v[222:223], v[18:19], v[164:165], v[222:223]
	v_pk_fma_f32 v[224:225], v[10:11], v[164:165], v[224:225]
	v_pk_fma_f32 v[222:223], v[20:21], v[166:167], v[222:223]
	v_pk_fma_f32 v[224:225], v[12:13], v[166:167], v[224:225]
	s_waitcnt lgkmcnt(0)
; __device__ __forceinline__ void scan_rows(f32x2 (&X)[8], const ScanOps& o, const f32x4 (&b)[2], const f32x4 (&kd)[2], const f32x4 (&r)[2], const bool use_v, float& yA, float& yB) {
;     f32x2 aA = X[0] * o.kk[0].xy, aB = X[4] * o.kk[0].xy;
;     aA += X[1] * o.kk[0].zw; aB += X[5] * o.kk[0].zw;
;     aA += X[2] * o.kk[1].xy; aB += X[6] * o.kk[1].xy;
;     aA += X[3] * o.kk[1].zw; aB += X[7] * o.kk[1].zw;
;     const float saA = sum8(aA.x + aA.y), saB = sum8(aB.x + aB.y);
;     const f32x2 nA = (f32x2){-saA, -saA}, nB = (f32x2){-saB, -saB}, vA = (f32x2){o.v.x, o.v.x}, vB = (f32x2){o.v.y, o.v.y};
;     f32x2 tA, tB, accA, accB;
;     tA = X[0] * o.w[0].xy; tA += nA * b[0].xy; if (use_v) tA += vA * kd[0].xy; X[0] = tA; accA = tA * r[0].xy;
;     tB = X[4] * o.w[0].xy; tB += nB * b[0].xy; if (use_v) tB += vB * kd[0].xy; X[4] = tB; accB = tB * r[0].xy;
;     tA = X[1] * o.w[0].zw; tA += nA * b[0].zw; if (use_v) tA += vA * kd[0].zw; X[1] = tA; accA += tA * r[0].zw;
;     tB = X[5] * o.w[0].zw; tB += nB * b[0].zw; if (use_v) tB += vB * kd[0].zw; X[5] = tB; accB += tB * r[0].zw;
;     tA = X[2] * o.w[1].xy; tA += nA * b[1].xy; if (use_v) tA += vA * kd[1].xy; X[2] = tA; accA += tA * r[1].xy;
;     tB = X[6] * o.w[1].xy; tB += nB * b[1].xy; if (use_v) tB += vB * kd[1].xy; X[6] = tB; accB += tB * r[1].xy;
;     tA = X[3] * o.w[1].zw; tA += nA * b[1].zw; if (use_v) tA += vA * kd[1].zw; X[3] = tA; accA += tA * r[1].zw;
;     tB = X[7] * o.w[1].zw; tB += nB * b[1].zw; if (use_v) tB += vB * kd[1].zw; X[7] = tB; accB += tB * r[1].zw;
; __device__ void phase_scan(int c, const bf16_t* PROJ, const float* k_k, const bf16_t* Wd, const bf16_t* Bd, const float* k_a, bf16_t* Y, bf16_t* Q, float* FS, float* sm) {
;     ...
;                 for (int i = 0; i < 16; i += 2) {
;                     float yA = 0.f, yB = 0.f;
;                     scan_ld(ob, obv, i + 1, B);
;                     if (roleP) A.v = (f32x2){0.f, 0.f};
;                     scan_step1(X, A, ob + i * 64, yA, yB);
;                     *(f32x2*)(obw + i * 16 + 2 * vp) = (f32x2){yA, yB};
;                     if (i + 2 < 16) scan_ld(ob, obv, i + 2, A);
;                     if (roleP) B.v = (f32x2){0.f, 0.f};
;                     scan_step1(X, B, ob + (i + 1) * 64, yA, yB);
;                     *(f32x2*)(obw + (i + 1) * 16 + 2 * vp) = (f32x2){yA, yB};
;                 }
	ds_read_b128 v[128:131], v84 offset:3840
	ds_read_b128 v[132:135], v84 offset:3856
	ds_read_b128 v[136:139], v84 offset:7936
	ds_read_b128 v[140:143], v84 offset:7952
	ds_read_b128 v[144:147], v84 offset:12032
	ds_read_b128 v[148:151], v84 offset:12048
	ds_read_b128 v[160:163], v84 offset:20224
	ds_read_b128 v[164:167], v84 offset:20240
	v_pk_mul_f32 v[212:213], v[22:23], v[94:95]
	v_pk_mul_f32 v[216:217], v[14:15], v[94:95]
	v_pk_mul_f32 v[196:197], v[22:23], v[86:87]
	v_pk_mul_f32 v[204:205], v[14:15], v[86:87]
	v_pk_fma_f32 v[212:213], v[24:25], v[96:97], v[212:213]
	v_pk_fma_f32 v[216:217], v[16:17], v[96:97], v[216:217]
	v_pk_mul_f32 v[198:199], v[24:25], v[88:89]
	v_pk_mul_f32 v[206:207], v[16:17], v[88:89]
	v_pk_fma_f32 v[212:213], v[18:19], v[98:99], v[212:213]
	v_pk_fma_f32 v[216:217], v[10:11], v[98:99], v[216:217]
	v_pk_fma_f32 v[212:213], v[20:21], v[100:101], v[212:213]
	v_pk_fma_f32 v[216:217], v[12:13], v[100:101], v[216:217]
	v_add_f32_e32 v226, v222, v223
	v_add_f32_e32 v227, v224, v225
	v_add_f32_e32 v220, v212, v213
	v_add_f32_e32 v221, v216, v217
	v_pk_mul_f32 v[200:201], v[18:19], v[90:91]
	v_pk_mul_f32 v[208:209], v[10:11], v[90:91]
	ds_write_b64 v228, v[226:227] offset:7488
	v_add_f32_dpp v220, v220, v220 quad_perm:[1,0,3,2] row_mask:0xf bank_mask:0xf bound_ctrl:1
	v_add_f32_dpp v221, v221, v221 quad_perm:[1,0,3,2] row_mask:0xf bank_mask:0xf bound_ctrl:1
	v_pk_mul_f32 v[202:203], v[20:21], v[92:93]
	v_pk_mul_f32 v[210:211], v[12:13], v[92:93]
	v_add_f32_dpp v220, v220, v220 quad_perm:[2,3,0,1] row_mask:0xf bank_mask:0xf bound_ctrl:1
	v_add_f32_dpp v221, v221, v221 quad_perm:[2,3,0,1] row_mask:0xf bank_mask:0xf bound_ctrl:1
	s_nop 0
	v_add_f32_dpp v220, v220, v220 row_half_mirror row_mask:0xf bank_mask:0xf bound_ctrl:1
	v_add_f32_dpp v221, v221, v221 row_half_mirror row_mask:0xf bank_mask:0xf bound_ctrl:1
	s_nop 0
	v_pk_fma_f32 v[22:23], v[220:221], v[102:103], v[196:197] op_sel_hi:[0,1,1] neg_lo:[1,0,0] neg_hi:[1,0,0]
	v_pk_fma_f32 v[14:15], v[220:221], v[102:103], v[204:205] op_sel:[1,0,0] op_sel_hi:[1,1,1] neg_lo:[1,0,0] neg_hi:[1,0,0]
	v_pk_fma_f32 v[24:25], v[220:221], v[104:105], v[198:199] op_sel_hi:[0,1,1] neg_lo:[1,0,0] neg_hi:[1,0,0]
	v_pk_fma_f32 v[16:17], v[220:221], v[104:105], v[206:207] op_sel:[1,0,0] op_sel_hi:[1,1,1] neg_lo:[1,0,0] neg_hi:[1,0,0]
	v_pk_fma_f32 v[18:19], v[220:221], v[106:107], v[200:201] op_sel_hi:[0,1,1] neg_lo:[1,0,0] neg_hi:[1,0,0]
	v_pk_fma_f32 v[10:11], v[220:221], v[106:107], v[208:209] op_sel:[1,0,0] op_sel_hi:[1,1,1] neg_lo:[1,0,0] neg_hi:[1,0,0]
	v_pk_fma_f32 v[20:21], v[220:221], v[108:109], v[202:203] op_sel_hi:[0,1,1] neg_lo:[1,0,0] neg_hi:[1,0,0]
	v_pk_fma_f32 v[12:13], v[220:221], v[108:109], v[210:211] op_sel:[1,0,0] op_sel_hi:[1,1,1] neg_lo:[1,0,0] neg_hi:[1,0,0]
	v_pk_mul_f32 v[222:223], v[22:23], v[118:119]
	v_pk_mul_f32 v[224:225], v[14:15], v[118:119]
	v_pk_fma_f32 v[222:223], v[24:25], v[120:121], v[222:223]
	v_pk_fma_f32 v[224:225], v[16:17], v[120:121], v[224:225]
	v_pk_fma_f32 v[222:223], v[18:19], v[122:123], v[222:223]
	v_pk_fma_f32 v[224:225], v[10:11], v[122:123], v[224:225]
	v_pk_fma_f32 v[222:223], v[20:21], v[124:125], v[222:223]
	v_pk_fma_f32 v[224:225], v[12:13], v[124:125], v[224:225]
	s_waitcnt lgkmcnt(0)
	v_pk_mul_f32 v[212:213], v[22:23], v[136:137]
	v_pk_mul_f32 v[216:217], v[14:15], v[136:137]
	v_pk_mul_f32 v[196:197], v[22:23], v[128:129]
	v_pk_mul_f32 v[204:205], v[14:15], v[128:129]
	v_pk_fma_f32 v[212:213], v[24:25], v[138:139], v[212:213]
	v_pk_fma_f32 v[216:217], v[16:17], v[138:139], v[216:217]
	v_pk_mul_f32 v[198:199], v[24:25], v[130:131]
	v_pk_mul_f32 v[206:207], v[16:17], v[130:131]
	v_pk_fma_f32 v[212:213], v[18:19], v[140:141], v[212:213]
	v_pk_fma_f32 v[216:217], v[10:11], v[140:141], v[216:217]
	v_pk_fma_f32 v[212:213], v[20:21], v[142:143], v[212:213]
	v_pk_fma_f32 v[216:217], v[12:13], v[142:143], v[216:217]
	v_add_f32_e32 v226, v222, v223
	v_add_f32_e32 v227, v224, v225
	v_add_f32_e32 v220, v212, v213
	v_add_f32_e32 v221, v216, v217
	v_pk_mul_f32 v[200:201], v[18:19], v[132:133]
	v_pk_mul_f32 v[208:209], v[10:11], v[132:133]
	ds_write_b64 v228, v[226:227] offset:8064
	v_add_f32_dpp v220, v220, v220 quad_perm:[1,0,3,2] row_mask:0xf bank_mask:0xf bound_ctrl:1
	v_add_f32_dpp v221, v221, v221 quad_perm:[1,0,3,2] row_mask:0xf bank_mask:0xf bound_ctrl:1
	v_pk_mul_f32 v[202:203], v[20:21], v[134:135]
	v_pk_mul_f32 v[210:211], v[12:13], v[134:135]
	v_add_f32_dpp v220, v220, v220 quad_perm:[2,3,0,1] row_mask:0xf bank_mask:0xf bound_ctrl:1
	v_add_f32_dpp v221, v221, v221 quad_perm:[2,3,0,1] row_mask:0xf bank_mask:0xf bound_ctrl:1
	s_nop 0
	v_add_f32_dpp v220, v220, v220 row_half_mirror row_mask:0xf bank_mask:0xf bound_ctrl:1
	v_add_f32_dpp v221, v221, v221 row_half_mirror row_mask:0xf bank_mask:0xf bound_ctrl:1
	s_nop 0
	v_pk_fma_f32 v[22:23], v[220:221], v[144:145], v[196:197] op_sel_hi:[0,1,1] neg_lo:[1,0,0] neg_hi:[1,0,0]
	v_pk_fma_f32 v[14:15], v[220:221], v[144:145], v[204:205] op_sel:[1,0,0] op_sel_hi:[1,1,1] neg_lo:[1,0,0] neg_hi:[1,0,0]
	v_pk_fma_f32 v[24:25], v[220:221], v[146:147], v[198:199] op_sel_hi:[0,1,1] neg_lo:[1,0,0] neg_hi:[1,0,0]
	v_pk_fma_f32 v[16:17], v[220:221], v[146:147], v[206:207] op_sel:[1,0,0] op_sel_hi:[1,1,1] neg_lo:[1,0,0] neg_hi:[1,0,0]
	v_pk_fma_f32 v[18:19], v[220:221], v[148:149], v[200:201] op_sel_hi:[0,1,1] neg_lo:[1,0,0] neg_hi:[1,0,0]
	v_pk_fma_f32 v[10:11], v[220:221], v[148:149], v[208:209] op_sel:[1,0,0] op_sel_hi:[1,1,1] neg_lo:[1,0,0] neg_hi:[1,0,0]
	v_pk_fma_f32 v[20:21], v[220:221], v[150:151], v[202:203] op_sel_hi:[0,1,1] neg_lo:[1,0,0] neg_hi:[1,0,0]
	v_pk_fma_f32 v[12:13], v[220:221], v[150:151], v[210:211] op_sel:[1,0,0] op_sel_hi:[1,1,1] neg_lo:[1,0,0] neg_hi:[1,0,0]
	v_pk_mul_f32 v[222:223], v[22:23], v[160:161]
	v_pk_mul_f32 v[224:225], v[14:15], v[160:161]
	v_pk_fma_f32 v[222:223], v[24:25], v[162:163], v[222:223]
	v_pk_fma_f32 v[224:225], v[16:17], v[162:163], v[224:225]
	v_pk_fma_f32 v[222:223], v[18:19], v[164:165], v[222:223]
	v_pk_fma_f32 v[224:225], v[10:11], v[164:165], v[224:225]
	v_pk_fma_f32 v[222:223], v[20:21], v[166:167], v[222:223]
	v_pk_fma_f32 v[224:225], v[12:13], v[166:167], v[224:225]
	v_add_f32_e32 v226, v222, v223
	v_add_f32_e32 v227, v224, v225
	ds_write_b64 v228, v[226:227] offset:8640
	s_setprio 0
; __device__ __forceinline__ unsigned pack2(float lo, float hi) { return (unsigned)f2bf(lo) | ((unsigned)f2bf(hi) << 16); }
; __device__ void phase_scan(int c, const bf16_t* PROJ, const float* k_k, const bf16_t* Wd, const bf16_t* Bd, const float* k_a, bf16_t* Y, bf16_t* Q, float* FS, float* sm) {
;     ...
;                 __builtin_amdgcn_wave_barrier(); asm volatile("s_waitcnt lgkmcnt(0)" ::: "memory");
;                 { const int st = lane >> 2, v4 = (lane & 3) * 4;
;                   const int g = g0 + ci * 16 + st; const int t = dir ? (L - 1 - g) : g;
;                   const size_t o = ((size_t)dir * TCH + (size_t)seq * L + t) * 512 + h * 64 + wq * 16 + v4;
;                   const f32x4 yv = *(const f32x4*)(obw + st * 16 + v4);
;                   uint2 pk; pk.x = pack2(yv[0], yv[1]); pk.y = pack2(yv[2], yv[3]); *(uint2*)(gout + o) = pk; }
;                 __builtin_amdgcn_wave_barrier();
.Lscan_body_end:
	s_waitcnt lgkmcnt(0)
	v_add_u32_e32 v84, s40, v82
	v_cndmask_b32_e64 v88, v83, v84, s[10:11]
	ds_read_b128 v[196:199], v229
	ds_read_b128 v[200:203], v229 offset:64
	ds_read_b128 v[204:207], v231 offset:128
	ds_read_b128 v[208:211], v231 offset:192
	ds_read_b128 v[212:215], v234 offset:256
	ds_read_b128 v[216:219], v234 offset:320
	ds_read_b128 v[220:223], v235 offset:384
	ds_read_b128 v[224:227], v235 offset:448
	v_ashrrev_i32_e32 v89, 31, v88
	v_lshl_add_u64 v[88:89], v[60:61], 0, v[88:89]
	v_lshlrev_b64 v[88:89], 10, v[88:89]
	v_lshl_add_u64 v[88:89], v[62:63], 0, v[88:89]
	s_waitcnt lgkmcnt(0)
	v_pk_add_f32 v[196:197], v[196:197], v[200:201]
	v_pk_add_f32 v[204:205], v[204:205], v[208:209]
	v_pk_add_f32 v[212:213], v[212:213], v[216:217]
	v_pk_add_f32 v[220:221], v[220:221], v[224:225]
	v_pk_add_f32 v[198:199], v[198:199], v[202:203]
	v_pk_add_f32 v[206:207], v[206:207], v[210:211]
	v_pk_add_f32 v[214:215], v[214:215], v[218:219]
	v_pk_add_f32 v[222:223], v[222:223], v[226:227]
	v_pk_add_f32 v[196:197], v[196:197], v[204:205]
	v_pk_add_f32 v[212:213], v[212:213], v[220:221]
	v_pk_add_f32 v[198:199], v[198:199], v[206:207]
	v_pk_add_f32 v[214:215], v[214:215], v[222:223]
	v_pk_add_f32 v[84:85], v[196:197], v[212:213]
	v_pk_add_f32 v[86:87], v[198:199], v[214:215]
	s_nop 0
	v_and_b32_sdwa v90, v86, v185 dst_sel:DWORD dst_unused:UNUSED_PAD src0_sel:WORD_1 src1_sel:DWORD
	v_and_b32_sdwa v91, v84, v185 dst_sel:DWORD dst_unused:UNUSED_PAD src0_sel:WORD_1 src1_sel:DWORD
	v_add3_u32 v84, v84, v91, s46
	v_add3_u32 v86, v86, v90, s46
	v_and_b32_sdwa v90, v87, v185 dst_sel:DWORD dst_unused:UNUSED_PAD src0_sel:WORD_1 src1_sel:DWORD
	v_and_b32_sdwa v91, v85, v185 dst_sel:DWORD dst_unused:UNUSED_PAD src0_sel:WORD_1 src1_sel:DWORD
	v_add3_u32 v87, v87, v90, s46
	v_add3_u32 v85, v85, v91, s46
	v_and_b32_e32 v87, 0xffff0000, v87
	v_and_b32_e32 v90, 0xffff0000, v85
	v_or_b32_sdwa v85, v87, v86 dst_sel:DWORD dst_unused:UNUSED_PAD src0_sel:DWORD src1_sel:WORD_1
	v_or_b32_sdwa v84, v90, v84 dst_sel:DWORD dst_unused:UNUSED_PAD src0_sel:DWORD src1_sel:WORD_1
	global_store_dwordx2 v[88:89], v[84:85], off
	s_branch .LBB0_71
